# retention: de-serialized intra staging+epilogue loads, ret_scan counted vmcnt; RWKV: hand-written scan loop, y reduced in-wave, staging reads pre-reduced y
# baseline (speedup 1.0000x reference)
.LBB0_638:
	s_or_b64 exec, exec, s[10:11]
	s_and_b32 s0, s51, 56
	s_ashr_i32 s16, s4, 3
	s_or_b32 s1, s0, s16
	s_ashr_i32 s4, s1, 3
	s_and_b32 s17, s4, 3
	v_cvt_f32_ubyte0_e32 v1, s17
	v_sub_f32_e32 v1, 0xc0a00000, v1
	s_mov_b32 s0, 0xc2fc0000
	v_mov_b32_e32 v14, 0x42800000
	v_cmp_gt_f32_e32 vcc, s0, v1
	s_lshl_b32 s13, s16, 5
	s_and_b64 s[8:9], vcc, exec
	v_cndmask_b32_e32 v2, 0, v14, vcc
	v_add_f32_e32 v1, v1, v2
	v_exp_f32_e32 v1, v1
	s_cselect_b32 s5, 0xffffffc0, 0
	v_mov_b32_e32 v2, 0x42000000
	v_mov_b32_e32 v3, 0
	v_ldexp_f32 v1, v1, s5
	v_sub_f32_e32 v1, 1.0, v1
	s_mov_b32 s5, 0x800000
	v_cmp_gt_f32_e32 vcc, s5, v1
	s_and_b64 s[8:9], vcc, exec
	s_cselect_b32 s5, 32, 0
	v_ldexp_f32 v1, v1, s5
	v_log_f32_e32 v1, v1
	v_cndmask_b32_e32 v2, 0, v2, vcc
	v_and_b32_e32 v6, 0x3f00, v131
	v_mov_b32_e32 v7, v3
	v_sub_f32_e32 v1, v1, v2
	v_mul_f32_e32 v2, 0x43000000, v1
	v_cmp_gt_f32_e32 vcc, s0, v2
	s_and_b64 s[10:11], vcc, exec
	s_cselect_b32 s5, 0xffffffc0, 0
	v_cndmask_b32_e32 v2, 0, v14, vcc
	v_fmac_f32_e32 v2, 0x43000000, v1
	v_exp_f32_e32 v2, v2
	s_ashr_i32 s12, s1, 5
	s_and_b32 s14, s13, 0xe0
	s_movk_i32 s1, 0x2000
	v_ldexp_f32 v122, v2, s5
	s_ashr_i32 s5, s4, 31
	s_lshl_b64 s[10:11], s[4:5], 23
	s_add_u32 s18, s78, s10
	s_addc_u32 s19, s79, s11
	v_and_b32_e32 v2, 0xf0, v131
	v_lshl_add_u64 v[4:5], s[18:19], 0, v[2:3]
	s_mov_b64 s[4:5], 0x38000000
	v_lshl_add_u64 v[4:5], v[4:5], 0, s[4:5]
	v_lshl_add_u64 v[8:9], v[4:5], 0, v[6:7]
	v_add_co_u32_e32 v10, vcc, s1, v8
	s_movk_i32 s1, 0x6000
	s_nop 0
	v_addc_co_u32_e32 v11, vcc, 0, v9, vcc
	global_load_dwordx4 v[18:21], v[8:9], off
	global_load_dwordx4 v[26:29], v[10:11], off
	v_or_b32_e32 v10, 0x4000, v6
	v_mov_b32_e32 v11, v3
	v_add_co_u32_e32 v12, vcc, s1, v8
	v_lshl_add_u64 v[10:11], v[4:5], 0, v[10:11]
	s_nop 0
	v_addc_co_u32_e32 v13, vcc, 0, v9, vcc
	s_mov_b32 s1, 0xa000
	global_load_dwordx4 v[34:37], v[10:11], off
	global_load_dwordx4 v[38:41], v[12:13], off
	v_add_co_u32_e32 v12, vcc, s1, v8
	v_or_b32_e32 v10, 0x8000, v6
	v_mov_b32_e32 v11, v3
	v_addc_co_u32_e32 v13, vcc, 0, v9, vcc
	v_or_b32_e32 v6, 0xc000, v6
	s_mov_b32 s1, 0xe000
	v_lshl_add_u64 v[10:11], v[4:5], 0, v[10:11]
	v_lshl_add_u64 v[4:5], v[4:5], 0, v[6:7]
	v_add_co_u32_e32 v6, vcc, s1, v8
	v_lshrrev_b32_e32 v16, 4, v153
	global_load_dwordx4 v[54:57], v[10:11], off
	global_load_dwordx4 v[58:61], v[12:13], off
	v_addc_co_u32_e32 v7, vcc, 0, v9, vcc
	global_load_dwordx4 v[66:69], v[4:5], off
	global_load_dwordx4 v[74:77], v[6:7], off
	v_add_lshl_u32 v4, s14, v16, 8
	v_mov_b32_e32 v5, v3
	v_lshl_add_u64 v[6:7], s[18:19], 0, v[4:5]
	s_ashr_i32 s13, s12, 31
	v_lshl_add_u64 v[6:7], v[6:7], 0, v[2:3]
	s_brev_b32 s1, 60
	s_lshl_b64 s[4:5], s[12:13], 14
	v_add_co_u32_e32 v6, vcc, s1, v6
	s_lshl_b32 s1, s50, 4
	s_add_u32 s8, s4, s1
	s_addc_u32 s15, s5, 0
	v_or_b32_e32 v8, s8, v130
	v_mov_b32_e32 v9, s15
	v_lshlrev_b64 v[8:9], 13, v[8:9]
	s_mov_b32 s9, 0
	v_lshl_add_u64 v[10:11], s[6:7], 0, v[8:9]
	s_lshl_b32 s8, s17, 9
	v_addc_co_u32_e32 v7, vcc, 0, v7, vcc
	v_lshl_add_u64 v[10:11], v[10:11], 0, s[8:9]
	v_and_b32_e32 v12, 48, v152
	v_mov_b32_e32 v13, v3
	v_lshl_add_u64 v[10:11], v[10:11], 0, v[12:13]
	global_load_dwordx4 v[70:73], v[6:7], off
	global_load_dwordx4 v[90:93], v[10:11], off
	global_load_dwordx4 v[86:89], v[10:11], off offset:64
	global_load_dwordx4 v[82:85], v[10:11], off offset:128
	global_load_dwordx4 v[78:81], v[10:11], off offset:192
	global_load_dwordx4 v[62:65], v[10:11], off offset:256
	global_load_dwordx4 v[46:49], v[10:11], off offset:320
	global_load_dwordx4 v[30:33], v[10:11], off offset:384
	global_load_dwordx4 v[22:25], v[10:11], off offset:448
	v_lshrrev_b32_e32 v15, 4, v152
	v_lshl_or_b32 v134, v15, 2, s1
	v_or_b32_e32 v132, 1, v134
	v_cvt_f32_u32_e32 v7, v132
	v_or_b32_e32 v128, 2, v134
	v_not_b32_e32 v42, 63
	v_or_b32_e32 v124, 3, v134
	v_mul_f32_e32 v17, v1, v7
	v_cmp_gt_f32_e32 vcc, s0, v17
	v_and_b32_e32 v5, 48, v153
	s_add_i32 s6, 0, 0x13200
	v_cndmask_b32_e32 v17, 0, v14, vcc
	v_fmac_f32_e32 v17, v1, v7
	v_cvt_f32_u32_e32 v7, v128
	v_cndmask_b32_e32 v43, 0, v42, vcc
	v_exp_f32_e32 v17, v17
	s_and_b32 s1, s3, 0xffffffc0
	v_mul_f32_e32 v44, v1, v7
	v_cmp_gt_f32_e32 vcc, s0, v44
	v_ldexp_f32 v148, v17, v43
	v_add_u32_e32 v10, s6, v5
	v_cndmask_b32_e32 v44, 0, v14, vcc
	v_fmac_f32_e32 v44, v1, v7
	v_exp_f32_e32 v7, v44
	v_cndmask_b32_e32 v17, 0, v42, vcc
	v_cvt_f32_u32_e32 v44, v124
	s_add_i32 s6, s6, s1
	v_ldexp_f32 v145, v7, v17
	v_add_u32_e32 v17, 4, v134
	v_cvt_f32_u32_e32 v17, v17
	v_mul_f32_e32 v7, v1, v44
	v_cmp_gt_f32_e32 vcc, s0, v7
	v_lshl_or_b32 v6, s50, 5, v130
	v_mul_f32_e32 v43, v1, v17
	v_cndmask_b32_e32 v7, 0, v14, vcc
	v_cmp_gt_f32_e64 s[0:1], s0, v43
	v_fmac_f32_e32 v7, v1, v44
	v_exp_f32_e32 v7, v7
	v_cndmask_b32_e64 v14, 0, v14, s[0:1]
	v_fmac_f32_e32 v14, v1, v17
	v_exp_f32_e32 v1, v14
	v_cndmask_b32_e32 v14, 0, v42, vcc
	v_ldexp_f32 v144, v7, v14
	v_cndmask_b32_e64 v7, 0, v42, s[0:1]
	v_ldexp_f32 v1, v1, v7
	v_add_u32_e32 v7, 0x200, v153
	v_lshrrev_b32_e32 v7, 4, v7
	v_mul_u32_u24_e32 v7, 0x110, v7
	v_add3_u32 v133, 0, v7, v2
	v_add_u32_e32 v7, 0x600, v153
	v_lshrrev_b32_e32 v7, 4, v7
	v_mul_u32_u24_e32 v7, 0x110, v7
	v_add3_u32 v149, 0, v7, v2
	v_add_u32_e32 v7, 0xa00, v153
	v_lshrrev_b32_e32 v7, 4, v7
	v_mul_u32_u24_e32 v7, 0x110, v7
	v_add3_u32 v150, 0, v7, v2
	v_add_u32_e32 v7, 0xe00, v153
	s_movk_i32 s0, 0x110
	v_lshrrev_b32_e32 v7, 4, v7
	s_add_i32 s7, 0, 0x11000
	v_mul_lo_u32 v14, v6, s0
	v_mul_u32_u24_e32 v6, 0x110, v16
	v_mul_u32_u24_e32 v7, 0x110, v7
	v_mov_b32_e32 v135, v3
	v_add3_u32 v125, 0, v6, v2
	v_add3_u32 v151, 0, v7, v2
	v_add3_u32 v154, s7, v6, v2
	s_lshl_b64 s[0:1], s[12:13], 26
	v_lshlrev_b64 v[6:7], 12, v[134:135]
	v_lshl_add_u64 v[136:137], s[0:1], 0, v[6:7]
	s_lshl_b32 s0, s16, 6
	v_or_b32_e32 v2, s8, v136
	s_and_b32 s0, s0, 0x1c0
	v_lshlrev_b32_e32 v6, 1, v130
	v_or3_b32 v136, v2, s0, v6
	v_lshl_or_b32 v2, v130, 4, s10
	v_or_b32_e32 v138, v2, v4
	v_mov_b32_e32 v139, s11
	s_mov_b64 s[0:1], 0x3c010000
	v_add_u32_e32 v11, 0, v5
	v_add_u32_e32 v12, s7, v5
	v_lshl_add_u32 v13, v15, 3, s6
	v_mul_u32_u24_e32 v15, 0x210, v130
	v_mul_u32_u24_e32 v17, 0x110, v130
	v_lshl_add_u64 v[140:141], v[138:139], 0, s[0:1]
	v_or3_b32 v8, v8, s8, v5
	s_mov_b64 s[0:1], 0x1c100100
	s_lshl_b32 s15, s17, 8
	v_mov_b32_e32 v126, v122
	v_mov_b32_e32 v127, v122
	v_lshl_or_b32 v138, v16, 8, v2
	v_lshl_add_u64 v[142:143], v[8:9], 0, s[0:1]
	s_movk_i32 s10, 0x7f
	s_mov_b32 s11, 0x38010000
	s_mov_b32 s12, 0x38012000
	s_mov_b32 s13, 0x38014000
	s_mov_b32 s16, 0x38016000
	s_mov_b32 s17, 0x38018000
	s_mov_b32 s18, 0x3801a000
	s_mov_b32 s19, 0x3801c000
	s_mov_b32 s20, 0x3801e000
	s_movk_i32 s21, 0x7fff
	s_mov_b32 s22, 0xf000000
	s_mov_b32 s23, 0xf001000
	s_mov_b32 s24, 0xf002000
	s_mov_b32 s25, 0xf003000
	s_mov_b32 s26, 0xffff0000
	s_mov_b64 s[0:1], 0x80000
	s_mov_b64 s[6:7], 0x10000
	s_mov_b64 s[8:9], 0x100000
	v_add_u32_e32 v129, v10, v15
	v_add_u32_e32 v146, v11, v14
	v_add_u32_e32 v147, v12, v17
	v_add_u32_e32 v131, v13, v15
	v_mov_b32_e32 v2, v3
	v_mov_b32_e32 v4, v3
	v_mov_b32_e32 v5, v3
	v_mov_b32_e32 v6, v3
	v_mov_b32_e32 v7, v3
	v_mov_b32_e32 v8, v3
	v_mov_b32_e32 v9, v3
	v_mov_b32_e32 v10, v3
	v_mov_b32_e32 v11, v3
	v_mov_b32_e32 v12, v3
	v_mov_b32_e32 v13, v3
	v_mov_b32_e32 v14, v3
	v_mov_b32_e32 v15, v3
	v_mov_b32_e32 v16, v3
	v_mov_b32_e32 v17, v3
	s_waitcnt vmcnt(0)
.LBB0_639:
	s_waitcnt vmcnt(8)
	v_mov_b64_e32 v[100:101], v[64:65]
	v_mov_b64_e32 v[96:97], v[48:49]
	v_mov_b64_e32 v[52:53], v[32:33]
	v_mov_b64_e32 v[44:45], v[24:25]
	v_mov_b64_e32 v[98:99], v[62:63]
	v_mov_b64_e32 v[94:95], v[46:47]
	v_mov_b64_e32 v[50:51], v[30:31]
	v_mov_b64_e32 v[42:43], v[22:23]
	ds_write_b128 v125, v[18:21]
	ds_write_b128 v133, v[26:29]
	ds_write_b128 v125, v[34:37] offset:17408
	ds_write_b128 v149, v[38:41]
	ds_write_b128 v125, v[54:57] offset:34816
	ds_write_b128 v150, v[58:61]
	ds_write_b128 v125, v[66:69] offset:52224
	ds_write_b128 v151, v[74:77]
	ds_write_b128 v154, v[70:73]
	s_waitcnt lgkmcnt(0)
	s_barrier
	ds_read_b128 v[46:49], v129
	ds_read_b128 v[54:57], v129 offset:64
	ds_read_b128 v[62:65], v129 offset:8448
	ds_read_b128 v[66:69], v129 offset:8512
	ds_read_b128 v[70:73], v129 offset:128
	ds_read_b128 v[22:25], v129 offset:192
	ds_read_b128 v[74:77], v129 offset:8576
	ds_read_b128 v[30:33], v129 offset:8640
	ds_read_b128 v[18:21], v129 offset:256
	ds_read_b128 v[58:61], v129 offset:320
	ds_read_b128 v[26:29], v129 offset:8704
	ds_read_b128 v[118:121], v129 offset:8768
	ds_read_b128 v[110:113], v129 offset:384
	ds_read_b128 v[106:109], v129 offset:448
	ds_read_b128 v[114:117], v129 offset:8832
	ds_read_b128 v[102:105], v129 offset:8896
	s_waitcnt lgkmcnt(14)
	v_mfma_f32_16x16x32_bf16 v[46:49], v[90:93], v[46:49], 0
	ds_read_b128 v[156:159], v146
	ds_read_b128 v[160:163], v147
	v_mov_b32_e32 v123, v122
	v_lshl_add_u64 v[34:35], s[78:79], 0, v[138:139]
	s_waitcnt lgkmcnt(14)
	v_mfma_f32_16x16x32_bf16 v[62:65], v[90:93], v[62:65], 0
	ds_read_b128 v[90:93], v146 offset:64
	ds_read_b128 v[164:167], v146 offset:4352
	ds_read_b128 v[168:171], v146 offset:4416
	v_pk_mul_f32 v[6:7], v[126:127], v[6:7]
	v_pk_mul_f32 v[2:3], v[126:127], v[2:3]
	v_mfma_f32_16x16x32_bf16 v[46:49], v[86:89], v[54:57], v[46:49]
	ds_read_b128 v[54:57], v147 offset:64
	ds_read_b128 v[172:175], v147 offset:4352
	ds_read_b128 v[176:179], v147 offset:4416
	v_pk_mul_f32 v[8:9], v[122:123], v[8:9]
	v_pk_mul_f32 v[4:5], v[122:123], v[4:5]
	v_pk_mul_f32 v[10:11], v[126:127], v[10:11]
	s_waitcnt lgkmcnt(4)
	v_mfma_f32_16x16x32_bf16 v[6:9], v[164:167], v[160:163], v[6:9]
	v_mul_f32_e64 v12, v122, v12
	v_mul_f32_e64 v13, v123, v13
	v_pk_mul_f32 v[14:15], v[126:127], v[14:15]
	v_pk_mul_f32 v[16:17], v[122:123], v[16:17]
	s_waitcnt lgkmcnt(1)
	v_mfma_f32_16x16x32_bf16 v[2:5], v[164:167], v[172:175], v[2:5]
	v_add_co_u32_e32 v164, vcc, s11, v34
	v_lshl_add_u64 v[40:41], s[78:79], 0, v[136:137]
	s_nop 0
	v_addc_co_u32_e32 v165, vcc, 0, v35, vcc
	v_add_co_u32_e32 v166, vcc, s12, v34
	v_mfma_f32_16x16x32_bf16 v[10:13], v[156:159], v[172:175], v[10:13]
	s_nop 0
	v_addc_co_u32_e32 v167, vcc, 0, v35, vcc
	v_add_co_u32_e32 v172, vcc, s13, v34
	v_mfma_f32_16x16x32_bf16 v[6:9], v[168:171], v[54:57], v[6:9]
	s_nop 0
	v_addc_co_u32_e32 v173, vcc, 0, v35, vcc
	v_add_co_u32_e32 v174, vcc, s16, v34
	s_waitcnt lgkmcnt(0)
	v_mfma_f32_16x16x32_bf16 v[2:5], v[168:171], v[176:179], v[2:5]
	v_addc_co_u32_e32 v175, vcc, 0, v35, vcc
	v_add_co_u32_e32 v168, vcc, s17, v34
	v_mfma_f32_16x16x32_bf16 v[14:17], v[156:159], v[160:163], v[14:17]
	s_nop 0
	v_addc_co_u32_e32 v169, vcc, 0, v35, vcc
	v_add_co_u32_e32 v170, vcc, s18, v34
	v_mfma_f32_16x16x32_bf16 v[62:65], v[86:89], v[66:69], v[62:65]
	s_nop 0
	v_addc_co_u32_e32 v171, vcc, 0, v35, vcc
	ds_read_b128 v[66:69], v146 offset:128
	ds_read_b128 v[180:183], v146 offset:192
	v_mfma_f32_16x16x32_bf16 v[46:49], v[82:85], v[70:73], v[46:49]
	ds_read_b128 v[184:187], v146 offset:4480
	ds_read_b128 v[188:191], v146 offset:4544
	ds_read_b128 v[156:159], v147 offset:128
	ds_read_b128 v[192:195], v147 offset:192
	ds_read_b128 v[160:163], v147 offset:4480
	ds_read_b128 v[196:199], v147 offset:4544
	v_mfma_f32_16x16x32_bf16 v[10:13], v[90:93], v[176:179], v[10:13]
	v_add_co_u32_e32 v176, vcc, s19, v34
	v_lshl_add_u64 v[38:39], s[78:79], 0, v[140:141]
	s_nop 0
	v_addc_co_u32_e32 v177, vcc, 0, v35, vcc
	v_mfma_f32_16x16x32_bf16 v[14:17], v[90:93], v[54:57], v[14:17]
	v_add_co_u32_e32 v178, vcc, s20, v34
	v_lshl_add_u64 v[36:37], s[78:79], 0, v[142:143]
	v_mfma_f32_16x16x32_bf16 v[62:65], v[82:85], v[74:77], v[62:65]
	v_addc_co_u32_e32 v179, vcc, 0, v35, vcc
	global_load_dwordx4 v[70:73], v[38:39], off
	global_load_dwordx4 v[90:93], v[36:37], off offset:-256
	global_load_dwordx4 v[86:89], v[36:37], off offset:-192
	v_mfma_f32_16x16x32_bf16 v[54:57], v[78:81], v[22:25], v[46:49]
	s_add_i32 s10, s10, -1
	v_lshl_add_u64 v[136:137], v[136:137], 0, s[0:1]
	v_lshl_add_u64 v[140:141], v[140:141], 0, s[6:7]
	s_waitcnt lgkmcnt(1)
	v_mfma_f32_16x16x32_bf16 v[10:13], v[66:69], v[160:163], v[10:13]
	v_lshl_add_u64 v[138:139], v[138:139], 0, s[6:7]
	v_lshl_add_u64 v[142:143], v[142:143], 0, s[8:9]
	s_cmp_lg_u32 s10, 0
	v_mfma_f32_16x16x32_bf16 v[2:5], v[184:187], v[160:163], v[2:5]
	v_add_co_u32_e32 v160, vcc, s22, v40
	v_add_u32_e32 v135, 0x2000, v131
	s_nop 0
	v_addc_co_u32_e32 v161, vcc, 0, v41, vcc
	v_mfma_f32_16x16x32_bf16 v[14:17], v[66:69], v[156:159], v[14:17]
	v_add_co_u32_e32 v162, vcc, s23, v40
	v_mfma_f32_16x16x32_bf16 v[74:77], v[78:81], v[30:33], v[62:65]
	s_nop 0
	v_addc_co_u32_e32 v163, vcc, 0, v41, vcc
	global_load_dwordx4 v[82:85], v[36:37], off offset:-128
	global_load_dwordx4 v[78:81], v[36:37], off offset:-64
	global_load_dwordx4 v[62:65], v[36:37], off
	v_mfma_f32_16x16x32_bf16 v[66:69], v[98:101], v[18:21], v[54:57]
	global_load_dwordx4 v[46:49], v[36:37], off offset:64
	global_load_dwordx4 v[30:33], v[36:37], off offset:128
	global_load_dwordx4 v[22:25], v[36:37], off offset:192
	v_mfma_f32_16x16x32_bf16 v[6:9], v[184:187], v[156:159], v[6:9]
	v_add_co_u32_e32 v184, vcc, s24, v40
	s_nop 1
	v_addc_co_u32_e32 v185, vcc, 0, v41, vcc
	v_mfma_f32_16x16x32_bf16 v[14:17], v[180:183], v[192:195], v[14:17]
	s_waitcnt lgkmcnt(0)
	v_mfma_f32_16x16x32_bf16 v[10:13], v[180:183], v[196:199], v[10:13]
	v_add_co_u32_e32 v180, vcc, s25, v40
	v_mfma_f32_16x16x32_bf16 v[98:101], v[98:101], v[26:29], v[74:77]
	s_nop 0
	v_addc_co_u32_e32 v181, vcc, 0, v41, vcc
	global_load_dwordx4 v[18:21], v[164:165], off
	global_load_dwordx4 v[26:29], v[166:167], off
	global_load_dwordx4 v[34:37], v[172:173], off
	global_load_dwordx4 v[38:41], v[174:175], off
	global_load_dwordx4 v[54:57], v[168:169], off
	v_mfma_f32_16x16x32_bf16 v[156:159], v[94:97], v[58:61], v[66:69]
	global_load_dwordx4 v[58:61], v[170:171], off
	s_nop 1
	global_load_dwordx4 v[66:69], v[176:177], off
	global_load_dwordx4 v[74:77], v[178:179], off
	v_mfma_f32_16x16x32_bf16 v[6:9], v[188:191], v[192:195], v[6:9]
	v_mfma_f32_16x16x32_bf16 v[2:5], v[188:191], v[196:199], v[2:5]
	v_mfma_f32_16x16x32_bf16 v[94:97], v[94:97], v[118:121], v[98:101]
	v_bfe_u32 v118, v10, 16, 1
	v_bfe_u32 v120, v12, 16, 1
	v_bfe_u32 v119, v11, 16, 1
	v_bfe_u32 v98, v14, 16, 1
	v_bfe_u32 v99, v15, 16, 1
	v_bfe_u32 v100, v16, 16, 1
	v_bfe_u32 v101, v17, 16, 1
	v_bfe_u32 v121, v13, 16, 1
	v_bfe_u32 v155, v6, 16, 1
	v_bfe_u32 v164, v7, 16, 1
	v_bfe_u32 v165, v8, 16, 1
	v_bfe_u32 v166, v9, 16, 1
	v_bfe_u32 v167, v2, 16, 1
	v_bfe_u32 v168, v3, 16, 1
	v_bfe_u32 v169, v4, 16, 1
	v_bfe_u32 v170, v5, 16, 1
	v_add3_u32 v98, v14, v98, s21
	v_add3_u32 v171, v15, v99, s21
	v_add3_u32 v99, v16, v100, s21
	v_add3_u32 v172, v17, v101, s21
	v_add3_u32 v100, v10, v118, s21
	v_add3_u32 v101, v12, v120, s21
	v_add3_u32 v118, v11, v119, s21
	v_add3_u32 v119, v13, v121, s21
	v_add3_u32 v120, v6, v155, s21
	v_add3_u32 v121, v7, v164, s21
	v_add3_u32 v155, v8, v165, s21
	v_add3_u32 v164, v9, v166, s21
	v_add3_u32 v165, v2, v167, s21
	v_add3_u32 v166, v3, v168, s21
	v_add3_u32 v167, v4, v169, s21
	v_add3_u32 v168, v5, v170, s21
	v_lshrrev_b32_e32 v169, 16, v98
	v_lshrrev_b32_e32 v170, 16, v99
	v_lshrrev_b32_e32 v173, 16, v100
	v_lshrrev_b32_e32 v174, 16, v101
	v_mfma_f32_16x16x32_bf16 v[98:101], v[50:53], v[110:113], v[156:159]
	v_lshrrev_b32_e32 v120, 16, v120
	v_lshrrev_b32_e32 v155, 16, v155
	v_lshrrev_b32_e32 v165, 16, v165
	v_mfma_f32_16x16x32_bf16 v[50:53], v[50:53], v[114:117], v[94:97]
	v_lshrrev_b32_e32 v156, 16, v167
	v_and_or_b32 v110, v171, s26, v169
	v_and_or_b32 v111, v172, s26, v170
	v_mfma_f32_16x16x32_bf16 v[94:97], v[42:45], v[106:109], v[98:101]
	v_and_or_b32 v114, v121, s26, v120
	v_and_or_b32 v115, v164, s26, v155
	v_and_or_b32 v112, v118, s26, v173
	v_mfma_f32_16x16x32_bf16 v[42:45], v[42:45], v[102:105], v[50:53]
	v_and_or_b32 v113, v119, s26, v174
	v_and_or_b32 v98, v166, s26, v165
	v_and_or_b32 v99, v168, s26, v156
	s_nop 0
	v_mul_f32_e32 v50, v148, v94
	v_mul_f32_e32 v51, v145, v95
	s_nop 1
	v_mul_f32_e32 v42, v148, v42
	v_mul_f32_e32 v43, v145, v43
	v_mul_f32_e32 v52, v144, v96
	v_mul_f32_e32 v44, v144, v44
	v_mul_f32_e32 v53, v1, v97
	v_mul_f32_e32 v45, v1, v45
	v_bfe_u32 v94, v50, 16, 1
	v_bfe_u32 v95, v42, 16, 1
	v_bfe_u32 v96, v51, 16, 1
	v_bfe_u32 v97, v43, 16, 1
	v_bfe_u32 v100, v52, 16, 1
	v_bfe_u32 v101, v44, 16, 1
	v_bfe_u32 v102, v53, 16, 1
	v_bfe_u32 v103, v45, 16, 1
	v_add3_u32 v50, v50, v94, s21
	v_add3_u32 v42, v42, v95, s21
	v_add3_u32 v51, v51, v96, s21
	v_add3_u32 v43, v43, v97, s21
	v_add3_u32 v52, v52, v100, s21
	v_add3_u32 v44, v44, v101, s21
	v_add3_u32 v53, v53, v102, s21
	v_add3_u32 v45, v45, v103, s21
	global_store_short_d16_hi v[160:161], v50, off offset:2048
	global_store_short_d16_hi v[160:161], v42, off offset:2080
	global_store_short_d16_hi v[162:163], v51, off offset:2048
	global_store_short_d16_hi v[162:163], v43, off offset:2080
	global_store_short_d16_hi v[184:185], v52, off offset:2048
	global_store_short_d16_hi v[184:185], v44, off offset:2080
	global_store_short_d16_hi v[180:181], v53, off offset:2048
	global_store_short_d16_hi v[180:181], v45, off offset:2080
	s_barrier
	ds_write2_b64 v131, v[110:111], v[114:115] offset1:4
	ds_write2_b64 v135, v[112:113], v[98:99] offset0:32 offset1:36
	s_cbranch_scc1 .LBB0_639
	s_waitcnt vmcnt(15)
	ds_write_b128 v125, v[18:21]
	s_waitcnt vmcnt(14)
	ds_write_b128 v133, v[26:29]
	s_waitcnt vmcnt(13)
	ds_write_b128 v125, v[34:37] offset:17408
	s_waitcnt vmcnt(12)
	ds_write_b128 v149, v[38:41]
	s_waitcnt vmcnt(11)
	ds_write_b128 v125, v[54:57] offset:34816
	s_waitcnt vmcnt(10)
	ds_write_b128 v150, v[58:61]
	s_waitcnt vmcnt(9)
	ds_write_b128 v125, v[66:69] offset:52224
	s_waitcnt vmcnt(8)
	ds_write_b128 v151, v[74:77]
	ds_write_b128 v154, v[70:73]
	s_waitcnt lgkmcnt(0)
	s_barrier
	ds_read_b128 v[18:21], v129
	ds_read_b128 v[26:29], v129 offset:64
	ds_read_b128 v[34:37], v129 offset:8448
	ds_read_b128 v[38:41], v129 offset:8512
	s_waitcnt lgkmcnt(3)
	v_mfma_f32_16x16x32_bf16 v[18:21], v[90:93], v[18:21], 0
	s_lshl_b32 s0, s15, 1
	s_add_u32 s0, s78, s0
	s_addc_u32 s1, s79, 0
	s_waitcnt lgkmcnt(1)
	v_mfma_f32_16x16x32_bf16 v[34:37], v[90:93], v[34:37], 0
	s_lshl_b32 s6, s14, 1
	s_add_u32 s0, s0, s6
	v_mov_b32_e32 v51, 0
	v_mfma_f32_16x16x32_bf16 v[18:21], v[86:89], v[26:29], v[18:21]
	s_addc_u32 s1, s1, 0
	v_lshlrev_b32_e32 v50, 1, v130
	v_mov_b32_e32 v135, v51
	s_waitcnt lgkmcnt(0)
	v_mfma_f32_16x16x32_bf16 v[26:29], v[86:89], v[38:41], v[34:37]
	s_nop 2
	ds_read_b128 v[34:37], v129 offset:128
	ds_read_b128 v[38:41], v129 offset:192
	s_or_b32 s4, s4, 0x3f80
	v_lshl_add_u64 v[52:53], s[0:1], 0, v[50:51]
	s_waitcnt lgkmcnt(1)
	v_mfma_f32_16x16x32_bf16 v[18:21], v[82:85], v[34:37], v[18:21]
	ds_read_b128 v[34:37], v129 offset:8576
	ds_read_b128 v[42:45], v129 offset:8640
	s_mov_b64 s[0:1], 0xf000800
	v_lshl_add_u64 v[54:55], v[52:53], 0, s[0:1]
	s_waitcnt lgkmcnt(1)
	v_mfma_f32_16x16x32_bf16 v[26:29], v[82:85], v[34:37], v[26:29]
	ds_read_b128 v[34:37], v129 offset:256
	s_movk_i32 s0, 0x7fff
	v_mov_b32_e32 v133, v51
	v_mfma_f32_16x16x32_bf16 v[18:21], v[78:81], v[38:41], v[18:21]
	v_mul_f32_e64 v16, v122, v16
	v_mul_f32_e64 v17, v123, v17
	v_pk_mul_f32 v[14:15], v[126:127], v[14:15]
	v_pk_mul_f32 v[8:9], v[122:123], v[8:9]
	s_waitcnt lgkmcnt(1)
	v_mfma_f32_16x16x32_bf16 v[26:29], v[78:81], v[42:45], v[26:29]
	ds_read_b128 v[38:41], v129 offset:8704
	ds_read_b128 v[42:45], v129 offset:320
	v_pk_mul_f32 v[6:7], v[126:127], v[6:7]
	v_pk_mul_f32 v[12:13], v[122:123], v[12:13]
	s_waitcnt lgkmcnt(2)
	v_mfma_f32_16x16x32_bf16 v[18:21], v[62:65], v[34:37], v[18:21]
	ds_read_b128 v[34:37], v129 offset:8768
	v_pk_mul_f32 v[10:11], v[126:127], v[10:11]
	v_mov_b32_e32 v125, v51
	s_waitcnt lgkmcnt(2)
	v_mfma_f32_16x16x32_bf16 v[26:29], v[62:65], v[38:41], v[26:29]
	ds_read_b128 v[38:41], v129 offset:384
	v_pk_mul_f32 v[4:5], v[122:123], v[4:5]
	v_pk_mul_f32 v[2:3], v[126:127], v[2:3]
	s_waitcnt lgkmcnt(2)
	v_mfma_f32_16x16x32_bf16 v[18:21], v[46:49], v[42:45], v[18:21]
	s_mov_b32 s1, 0xffff0000
	s_waitcnt lgkmcnt(1)
	v_mfma_f32_16x16x32_bf16 v[26:29], v[46:49], v[34:37], v[26:29]
	ds_read_b128 v[34:37], v129 offset:8832
	ds_read_b128 v[42:45], v129 offset:448
	s_waitcnt lgkmcnt(2)
	v_mfma_f32_16x16x32_bf16 v[18:21], v[30:33], v[38:41], v[18:21]
	ds_read_b128 v[38:41], v129 offset:8896
	v_mov_b32_e32 v129, v51
	s_waitcnt lgkmcnt(2)
	v_mfma_f32_16x16x32_bf16 v[26:29], v[30:33], v[34:37], v[26:29]
	v_lshl_add_u64 v[30:31], s[4:5], 0, v[134:135]
	v_lshlrev_b64 v[30:31], 12, v[30:31]
	s_waitcnt lgkmcnt(1)
	v_mfma_f32_16x16x32_bf16 v[18:21], v[22:25], v[42:45], v[18:21]
	s_waitcnt lgkmcnt(0)
	v_mfma_f32_16x16x32_bf16 v[22:25], v[22:25], v[38:41], v[26:29]
	s_nop 2
	v_lshl_add_u64 v[26:27], v[54:55], 0, v[30:31]
	s_nop 1
	v_mul_f32_e32 v18, v148, v18
	v_bfe_u32 v28, v18, 16, 1
	v_add3_u32 v18, v18, v28, s0
	global_store_short_d16_hi v[26:27], v18, off
	v_mul_f32_e32 v18, v148, v22
	v_bfe_u32 v22, v18, 16, 1
	v_add3_u32 v18, v18, v22, s0
	global_store_short_d16_hi v[26:27], v18, off offset:32
	ds_read_b128 v[26:29], v146
	v_lshl_add_u64 v[30:31], s[4:5], 0, v[132:133]
	v_lshlrev_b64 v[56:57], 12, v[30:31]
	ds_read_b128 v[30:33], v147
	ds_read_b128 v[34:37], v146 offset:4352
	ds_read_b128 v[38:41], v147 offset:4352
	ds_read_b128 v[42:45], v146 offset:64
	ds_read_b128 v[46:49], v147 offset:64
	v_mul_f32_e32 v18, v145, v19
	v_bfe_u32 v19, v18, 16, 1
	s_waitcnt lgkmcnt(4)
	v_mfma_f32_16x16x32_bf16 v[14:17], v[26:29], v[30:33], v[14:17]
	v_add3_u32 v18, v18, v19, s0
	ds_read_b128 v[50:53], v147 offset:4416
	v_mul_f32_e32 v20, v144, v20
	s_waitcnt lgkmcnt(4)
	v_mfma_f32_16x16x32_bf16 v[6:9], v[34:37], v[30:33], v[6:9]
	v_lshl_add_u64 v[30:31], v[54:55], 0, v[56:57]
	global_store_short_d16_hi v[30:31], v18, off
	v_mul_f32_e32 v18, v145, v23
	v_bfe_u32 v19, v18, 16, 1
	s_waitcnt lgkmcnt(3)
	v_mfma_f32_16x16x32_bf16 v[10:13], v[26:29], v[38:41], v[10:13]
	ds_read_b128 v[26:29], v146 offset:4416
	v_add3_u32 v18, v18, v19, s0
	global_store_short_d16_hi v[30:31], v18, off offset:32
	ds_read_b128 v[30:33], v146 offset:128
	v_mfma_f32_16x16x32_bf16 v[2:5], v[34:37], v[38:41], v[2:5]
	v_lshl_add_u64 v[18:19], s[4:5], 0, v[128:129]
	v_lshlrev_b64 v[18:19], 12, v[18:19]
	v_bfe_u32 v22, v20, 16, 1
	s_waitcnt lgkmcnt(3)
	v_mfma_f32_16x16x32_bf16 v[14:17], v[42:45], v[46:49], v[14:17]
	v_lshl_add_u64 v[18:19], v[54:55], 0, v[18:19]
	v_add3_u32 v20, v20, v22, s0
	s_waitcnt lgkmcnt(2)
	v_mfma_f32_16x16x32_bf16 v[10:13], v[42:45], v[50:53], v[10:13]
	s_waitcnt lgkmcnt(1)
	v_mfma_f32_16x16x32_bf16 v[6:9], v[26:29], v[46:49], v[6:9]
	v_mfma_f32_16x16x32_bf16 v[2:5], v[26:29], v[50:53], v[2:5]
	ds_read_b128 v[26:29], v147 offset:128
	ds_read_b128 v[34:37], v146 offset:4480
	ds_read_b128 v[38:41], v147 offset:4480
	ds_read_b128 v[42:45], v146 offset:192
	ds_read_b128 v[46:49], v147 offset:192
	global_store_short_d16_hi v[18:19], v20, off
	v_mul_f32_e32 v20, v144, v24
	s_waitcnt lgkmcnt(4)
	v_mfma_f32_16x16x32_bf16 v[14:17], v[30:33], v[26:29], v[14:17]
	v_bfe_u32 v22, v20, 16, 1
	v_add3_u32 v20, v20, v22, s0
	global_store_short_d16_hi v[18:19], v20, off offset:32
	v_lshl_add_u64 v[18:19], s[4:5], 0, v[124:125]
	v_mul_f32_e32 v20, v1, v21
	v_lshlrev_b64 v[18:19], 12, v[18:19]
	s_waitcnt lgkmcnt(0)
	v_mfma_f32_16x16x32_bf16 v[14:17], v[42:45], v[46:49], v[14:17]
	v_bfe_u32 v21, v20, 16, 1
	ds_read_b128 v[50:53], v147 offset:4544
	v_lshl_add_u64 v[18:19], v[54:55], 0, v[18:19]
	v_add3_u32 v20, v20, v21, s0
	v_mul_f32_e32 v1, v1, v25
	v_mfma_f32_16x16x32_bf16 v[10:13], v[30:33], v[38:41], v[10:13]
	global_store_short_d16_hi v[18:19], v20, off
	v_bfe_u32 v20, v1, 16, 1
	ds_read_b128 v[30:33], v146 offset:4544
	v_add3_u32 v1, v1, v20, s0
	global_store_short_d16_hi v[18:19], v1, off offset:32
	v_bfe_u32 v1, v14, 16, 1
	v_add3_u32 v1, v14, v1, s0
	v_bfe_u32 v14, v15, 16, 1
	s_waitcnt lgkmcnt(1)
	v_mfma_f32_16x16x32_bf16 v[10:13], v[42:45], v[50:53], v[10:13]
	v_lshrrev_b32_e32 v1, 16, v1
	v_add3_u32 v14, v15, v14, s0
	v_and_or_b32 v14, v14, s1, v1
	v_bfe_u32 v1, v16, 16, 1
	v_mfma_f32_16x16x32_bf16 v[6:9], v[34:37], v[26:29], v[6:9]
	v_add3_u32 v1, v16, v1, s0
	v_bfe_u32 v15, v17, 16, 1
	v_lshrrev_b32_e32 v1, 16, v1
	v_add3_u32 v15, v17, v15, s0
	v_and_or_b32 v15, v15, s1, v1
	v_bfe_u32 v1, v10, 16, 1
	v_add3_u32 v1, v10, v1, s0
	v_bfe_u32 v10, v11, 16, 1
	s_waitcnt lgkmcnt(0)
	v_mfma_f32_16x16x32_bf16 v[6:9], v[30:33], v[46:49], v[6:9]
	v_lshrrev_b32_e32 v1, 16, v1
	v_add3_u32 v10, v11, v10, s0
	v_and_or_b32 v10, v10, s1, v1
	v_bfe_u32 v1, v12, 16, 1
	v_mfma_f32_16x16x32_bf16 v[2:5], v[34:37], v[38:41], v[2:5]
	v_add3_u32 v1, v12, v1, s0
	v_bfe_u32 v11, v13, 16, 1
	v_lshrrev_b32_e32 v1, 16, v1
	v_add3_u32 v11, v13, v11, s0
	v_and_or_b32 v11, v11, s1, v1
	v_bfe_u32 v1, v6, 16, 1
	v_add3_u32 v1, v6, v1, s0
	v_bfe_u32 v6, v7, 16, 1
	v_mfma_f32_16x16x32_bf16 v[2:5], v[30:33], v[50:53], v[2:5]
	v_lshrrev_b32_e32 v1, 16, v1
	v_add3_u32 v6, v7, v6, s0
	v_and_or_b32 v6, v6, s1, v1
	v_bfe_u32 v1, v8, 16, 1
	v_add3_u32 v1, v8, v1, s0
	v_bfe_u32 v7, v9, 16, 1
	v_lshrrev_b32_e32 v1, 16, v1
	v_add3_u32 v7, v9, v7, s0
	v_and_or_b32 v7, v7, s1, v1
	v_bfe_u32 v1, v2, 16, 1
	v_add3_u32 v1, v2, v1, s0
	v_bfe_u32 v2, v3, 16, 1
	v_lshrrev_b32_e32 v1, 16, v1
	v_add3_u32 v2, v3, v2, s0
	v_and_or_b32 v2, v2, s1, v1
	v_bfe_u32 v1, v4, 16, 1
	v_add3_u32 v1, v4, v1, s0
	v_bfe_u32 v3, v5, 16, 1
	v_lshrrev_b32_e32 v1, 16, v1
	v_add3_u32 v3, v5, v3, s0
	v_and_or_b32 v3, v3, s1, v1
	v_add_u32_e32 v1, 0x2000, v131
	s_barrier
	ds_write2_b64 v131, v[14:15], v[6:7] offset1:4
	ds_write2_b64 v1, v[10:11], v[2:3] offset0:32 offset1:36
	s_waitcnt lgkmcnt(0)
	s_barrier

.LBB0_649:
	s_and_b64 vcc, exec, s[0:1]
	s_cbranch_vccz .LBB0_676
	s_cmpk_lt_u32 s3, 0x100
	s_mov_b64 s[0:1], -1
	s_cbranch_scc0 .LBB0_654
	v_lshrrev_b32_e32 v1, 4, v152
	v_lshl_or_b32 v1, s50, 2, v1
	v_and_b32_e32 v118, 15, v153
	v_lshlrev_b32_e32 v6, 4, v118
	v_mov_b32_e32 v7, 0
	v_lshlrev_b32_e32 v8, 2, v1
	v_add_u32_e32 v8, 0x9300, v8
	v_add_u32_e32 v120, 0x400, v8
	v_lshlrev_b32_e32 v9, 2, v1
	v_add_u32_e32 v9, 0x9b00, v9
	v_lshlrev_b32_e32 v119, 2, v152
	v_add_u32_e32 v119, 0xab00, v119
	v_cmp_eq_u32_e32 vcc, 0, v118
	s_nop 1
	v_cndmask_b32_e32 v9, v119, v9, vcc
	v_add_u32_e32 v119, 0x400, v9
	v_mov_b32_e32 v2, 0
	v_mov_b32_e32 v3, 0
	v_mov_b32_e32 v4, 0
	v_mov_b32_e32 v5, 0
	s_mov_b32 s0, 0
	s_mov_b32 s1, 0x11b00
	s_waitcnt vmcnt(0) lgkmcnt(0)
	s_barrier
.LBB0_652:
	ds_read_b128 v[20:23], v6 offset:0
	ds_read_b128 v[28:31], v6 offset:512
	ds_read_b128 v[24:27], v6 offset:256
	ds_read_b128 v[32:35], v6 offset:768
	ds_read_b128 v[56:59], v7 offset:36864
	ds_read_b128 v[36:39], v6 offset:1024
	ds_read_b128 v[40:43], v6 offset:1280
	ds_read2_b32 v[64:65], v8 offset0:0 offset1:16
	ds_read_b128 v[48:51], v6 offset:1792
	ds_read_b128 v[44:47], v6 offset:1536
	ds_read_b128 v[52:55], v6 offset:2048
	ds_read_b128 v[60:63], v7 offset:36880
	s_waitcnt lgkmcnt(7)
	v_pk_mul_f32 v[10:11], v[4:5], v[22:23]
	ds_read_b128 v[68:71], v6 offset:2304
	v_pk_mul_f32 v[12:13], v[4:5], v[30:31]
	v_pk_fma_f32 v[10:11], v[2:3], v[20:21], v[10:11]
	v_pk_fma_f32 v[12:13], v[2:3], v[28:29], v[12:13]
	ds_read_b128 v[76:79], v6 offset:2816
	v_pk_mul_f32 v[14:15], v[4:5], v[26:27]
	v_add_f32_e32 v10, v10, v11
	v_add_f32_e32 v12, v12, v13
	ds_read_b128 v[72:75], v6 offset:2560
	v_pk_mul_f32 v[16:17], v[4:5], v[34:35]
	v_fma_f32 v12, -v56, v10, v12
	v_add_f32_dpp v10, v10, v10 row_ror:8 row_mask:0xf bank_mask:0xf bound_ctrl:1
	ds_read_b128 v[80:83], v6 offset:3072
	v_pk_fma_f32 v[14:15], v[2:3], v[24:25], v[14:15]
	v_add_f32_dpp v12, v12, v12 row_ror:8 row_mask:0xf bank_mask:0xf bound_ctrl:1
	v_add_f32_dpp v10, v10, v10 row_ror:4 row_mask:0xf bank_mask:0xf bound_ctrl:1
	ds_read_b128 v[104:107], v7 offset:36912
	v_pk_fma_f32 v[16:17], v[2:3], v[32:33], v[16:17]
	v_add_f32_dpp v12, v12, v12 row_ror:4 row_mask:0xf bank_mask:0xf bound_ctrl:1
	v_add_f32_dpp v10, v10, v10 row_ror:2 row_mask:0xf bank_mask:0xf bound_ctrl:1
	ds_read_b128 v[84:87], v6 offset:3328
	s_waitcnt lgkmcnt(10)
	v_pk_mul_f32 v[114:115], v[2:3], v[36:37]
	v_add_f32_dpp v12, v12, v12 row_ror:2 row_mask:0xf bank_mask:0xf bound_ctrl:1
	v_add_f32_dpp v10, v10, v10 row_ror:1 row_mask:0xf bank_mask:0xf bound_ctrl:1
	ds_read_b128 v[88:91], v6 offset:3584
	v_pk_mul_f32 v[116:117], v[4:5], v[38:39]
	v_add_f32_dpp v12, v12, v12 row_ror:1 row_mask:0xf bank_mask:0xf bound_ctrl:1
	v_add_f32_e32 v14, v14, v15
	ds_read2_b32 v[112:113], v8 offset0:32 offset1:48
	v_pk_fma_f32 v[114:115], v[40:41], v[64:65], v[114:115] op_sel_hi:[1,0,1]
	v_add_f32_e32 v16, v16, v17
	v_pk_fma_f32 v[116:117], v[42:43], v[64:65], v[116:117] op_sel_hi:[1,0,1]
	ds_read_b128 v[96:99], v6 offset:4096
	v_fmac_f32_e32 v12, v64, v57
	v_fmac_f32_e32 v14, v64, v59
	s_waitcnt lgkmcnt(9)
	v_pk_fma_f32 v[114:115], v[48:49], v[64:65], v[114:115] op_sel:[0,1,0] op_sel_hi:[1,1,1]
	ds_read_b128 v[92:95], v6 offset:3840
	v_fmac_f32_e32 v16, v64, v61
	v_pk_fma_f32 v[116:117], v[50:51], v[64:65], v[116:117] op_sel:[0,1,0] op_sel_hi:[1,1,1]
	v_fma_f32 v14, -v10, v58, v14
	ds_read_b128 v[100:103], v6 offset:4352
	v_fmac_f32_e32 v16, v65, v63
	v_pk_fma_f32 v[114:115], v[44:45], v[10:11], v[114:115] op_sel_hi:[1,0,1] neg_lo:[1,0,0] neg_hi:[1,0,0]
	v_fma_f32 v16, -v10, v60, v16
	ds_read_b128 v[108:111], v7 offset:36928
	v_pk_fma_f32 v[116:117], v[46:47], v[10:11], v[116:117] op_sel_hi:[1,0,1] neg_lo:[1,0,0] neg_hi:[1,0,0]
	v_add_f32_dpp v14, v14, v14 row_ror:8 row_mask:0xf bank_mask:0xf bound_ctrl:1
	v_fma_f32 v16, -v12, v62, v16
	v_pk_fma_f32 v[2:3], v[52:53], v[12:13], v[114:115] op_sel_hi:[1,0,1] neg_lo:[1,0,0] neg_hi:[1,0,0]
	v_add_f32_dpp v14, v14, v14 row_ror:4 row_mask:0xf bank_mask:0xf bound_ctrl:1
	v_pk_fma_f32 v[4:5], v[54:55], v[12:13], v[116:117] op_sel_hi:[1,0,1] neg_lo:[1,0,0] neg_hi:[1,0,0]
	v_add_f32_dpp v16, v16, v16 row_ror:8 row_mask:0xf bank_mask:0xf bound_ctrl:1
	v_add_f32_dpp v14, v14, v14 row_ror:2 row_mask:0xf bank_mask:0xf bound_ctrl:1
	s_nop 0
	v_add_f32_dpp v16, v16, v16 row_ror:4 row_mask:0xf bank_mask:0xf bound_ctrl:1
	v_add_f32_dpp v14, v14, v14 row_ror:1 row_mask:0xf bank_mask:0xf bound_ctrl:1
	s_nop 0
	v_add_f32_dpp v16, v16, v16 row_ror:2 row_mask:0xf bank_mask:0xf bound_ctrl:1
	s_nop 1
	v_add_f32_dpp v16, v16, v16 row_ror:1 row_mask:0xf bank_mask:0xf bound_ctrl:1
	ds_write2_b32 v9, v14, v16 offset0:0 offset1:16
	s_waitcnt lgkmcnt(8)
	v_pk_mul_f32 v[10:11], v[4:5], v[70:71]
	ds_read_b128 v[20:23], v6 offset:4608
	v_pk_mul_f32 v[12:13], v[4:5], v[78:79]
	v_pk_fma_f32 v[10:11], v[2:3], v[68:69], v[10:11]
	v_pk_fma_f32 v[12:13], v[2:3], v[76:77], v[12:13]
	ds_read_b128 v[28:31], v6 offset:5120
	v_pk_mul_f32 v[14:15], v[4:5], v[74:75]
	v_add_f32_e32 v10, v10, v11
	v_add_f32_e32 v12, v12, v13
	ds_read_b128 v[24:27], v6 offset:4864
	v_pk_mul_f32 v[16:17], v[4:5], v[82:83]
	v_fma_f32 v12, -v104, v10, v12
	v_add_f32_dpp v10, v10, v10 row_ror:8 row_mask:0xf bank_mask:0xf bound_ctrl:1
	ds_read_b128 v[32:35], v6 offset:5376
	v_pk_fma_f32 v[14:15], v[2:3], v[72:73], v[14:15]
	v_add_f32_dpp v12, v12, v12 row_ror:8 row_mask:0xf bank_mask:0xf bound_ctrl:1
	v_add_f32_dpp v10, v10, v10 row_ror:4 row_mask:0xf bank_mask:0xf bound_ctrl:1
	ds_read_b128 v[56:59], v7 offset:36960
	v_pk_fma_f32 v[16:17], v[2:3], v[80:81], v[16:17]
	v_add_f32_dpp v12, v12, v12 row_ror:4 row_mask:0xf bank_mask:0xf bound_ctrl:1
	v_add_f32_dpp v10, v10, v10 row_ror:2 row_mask:0xf bank_mask:0xf bound_ctrl:1
	ds_read_b128 v[36:39], v6 offset:5632
	s_waitcnt lgkmcnt(11)
	v_pk_mul_f32 v[114:115], v[2:3], v[84:85]
	v_add_f32_dpp v12, v12, v12 row_ror:2 row_mask:0xf bank_mask:0xf bound_ctrl:1
	v_add_f32_dpp v10, v10, v10 row_ror:1 row_mask:0xf bank_mask:0xf bound_ctrl:1
	ds_read_b128 v[40:43], v6 offset:5888
	v_pk_mul_f32 v[116:117], v[4:5], v[86:87]
	v_add_f32_dpp v12, v12, v12 row_ror:1 row_mask:0xf bank_mask:0xf bound_ctrl:1
	v_add_f32_e32 v14, v14, v15
	ds_read2_b32 v[64:65], v8 offset0:64 offset1:80
	v_pk_fma_f32 v[114:115], v[88:89], v[112:113], v[114:115] op_sel_hi:[1,0,1]
	v_add_f32_e32 v16, v16, v17
	v_pk_fma_f32 v[116:117], v[90:91], v[112:113], v[116:117] op_sel_hi:[1,0,1]
	ds_read_b128 v[48:51], v6 offset:6400
	v_fmac_f32_e32 v12, v112, v105
	v_fmac_f32_e32 v14, v112, v107
	s_waitcnt lgkmcnt(10)
	v_pk_fma_f32 v[114:115], v[96:97], v[112:113], v[114:115] op_sel:[0,1,0] op_sel_hi:[1,1,1]
	ds_read_b128 v[44:47], v6 offset:6144
	v_fmac_f32_e32 v16, v112, v109
	v_pk_fma_f32 v[116:117], v[98:99], v[112:113], v[116:117] op_sel:[0,1,0] op_sel_hi:[1,1,1]
	v_fma_f32 v14, -v10, v106, v14
	ds_read_b128 v[52:55], v6 offset:6656
	v_fmac_f32_e32 v16, v113, v111
	v_pk_fma_f32 v[114:115], v[92:93], v[10:11], v[114:115] op_sel_hi:[1,0,1] neg_lo:[1,0,0] neg_hi:[1,0,0]
	v_fma_f32 v16, -v10, v108, v16
	ds_read_b128 v[60:63], v7 offset:36976
	v_pk_fma_f32 v[116:117], v[94:95], v[10:11], v[116:117] op_sel_hi:[1,0,1] neg_lo:[1,0,0] neg_hi:[1,0,0]
	v_add_f32_dpp v14, v14, v14 row_ror:8 row_mask:0xf bank_mask:0xf bound_ctrl:1
	v_fma_f32 v16, -v12, v110, v16
	v_pk_fma_f32 v[2:3], v[100:101], v[12:13], v[114:115] op_sel_hi:[1,0,1] neg_lo:[1,0,0] neg_hi:[1,0,0]
	v_add_f32_dpp v14, v14, v14 row_ror:4 row_mask:0xf bank_mask:0xf bound_ctrl:1
	v_pk_fma_f32 v[4:5], v[102:103], v[12:13], v[116:117] op_sel_hi:[1,0,1] neg_lo:[1,0,0] neg_hi:[1,0,0]
	v_add_f32_dpp v16, v16, v16 row_ror:8 row_mask:0xf bank_mask:0xf bound_ctrl:1
	v_add_f32_dpp v14, v14, v14 row_ror:2 row_mask:0xf bank_mask:0xf bound_ctrl:1
	s_nop 0
	v_add_f32_dpp v16, v16, v16 row_ror:4 row_mask:0xf bank_mask:0xf bound_ctrl:1
	v_add_f32_dpp v14, v14, v14 row_ror:1 row_mask:0xf bank_mask:0xf bound_ctrl:1
	s_nop 0
	v_add_f32_dpp v16, v16, v16 row_ror:2 row_mask:0xf bank_mask:0xf bound_ctrl:1
	s_nop 1
	v_add_f32_dpp v16, v16, v16 row_ror:1 row_mask:0xf bank_mask:0xf bound_ctrl:1
	ds_write2_b32 v9, v14, v16 offset0:32 offset1:48
	s_waitcnt lgkmcnt(8)
	v_pk_mul_f32 v[10:11], v[4:5], v[22:23]
	ds_read_b128 v[68:71], v6 offset:6912
	v_pk_mul_f32 v[12:13], v[4:5], v[30:31]
	v_pk_fma_f32 v[10:11], v[2:3], v[20:21], v[10:11]
	v_pk_fma_f32 v[12:13], v[2:3], v[28:29], v[12:13]
	ds_read_b128 v[76:79], v6 offset:7424
	v_pk_mul_f32 v[14:15], v[4:5], v[26:27]
	v_add_f32_e32 v10, v10, v11
	v_add_f32_e32 v12, v12, v13
	ds_read_b128 v[72:75], v6 offset:7168
	v_pk_mul_f32 v[16:17], v[4:5], v[34:35]
	v_fma_f32 v12, -v56, v10, v12
	v_add_f32_dpp v10, v10, v10 row_ror:8 row_mask:0xf bank_mask:0xf bound_ctrl:1
	ds_read_b128 v[80:83], v6 offset:7680
	v_pk_fma_f32 v[14:15], v[2:3], v[24:25], v[14:15]
	v_add_f32_dpp v12, v12, v12 row_ror:8 row_mask:0xf bank_mask:0xf bound_ctrl:1
	v_add_f32_dpp v10, v10, v10 row_ror:4 row_mask:0xf bank_mask:0xf bound_ctrl:1
	ds_read_b128 v[104:107], v7 offset:37008
	v_pk_fma_f32 v[16:17], v[2:3], v[32:33], v[16:17]
	v_add_f32_dpp v12, v12, v12 row_ror:4 row_mask:0xf bank_mask:0xf bound_ctrl:1
	v_add_f32_dpp v10, v10, v10 row_ror:2 row_mask:0xf bank_mask:0xf bound_ctrl:1
	ds_read_b128 v[84:87], v6 offset:7936
	s_waitcnt lgkmcnt(11)
	v_pk_mul_f32 v[114:115], v[2:3], v[36:37]
	v_add_f32_dpp v12, v12, v12 row_ror:2 row_mask:0xf bank_mask:0xf bound_ctrl:1
	v_add_f32_dpp v10, v10, v10 row_ror:1 row_mask:0xf bank_mask:0xf bound_ctrl:1
	ds_read_b128 v[88:91], v6 offset:8192
	v_pk_mul_f32 v[116:117], v[4:5], v[38:39]
	v_add_f32_dpp v12, v12, v12 row_ror:1 row_mask:0xf bank_mask:0xf bound_ctrl:1
	v_add_f32_e32 v14, v14, v15
	ds_read2_b32 v[112:113], v8 offset0:96 offset1:112
	v_pk_fma_f32 v[114:115], v[40:41], v[64:65], v[114:115] op_sel_hi:[1,0,1]
	v_add_f32_e32 v16, v16, v17
	v_pk_fma_f32 v[116:117], v[42:43], v[64:65], v[116:117] op_sel_hi:[1,0,1]
	ds_read_b128 v[96:99], v6 offset:8704
	v_fmac_f32_e32 v12, v64, v57
	v_fmac_f32_e32 v14, v64, v59
	s_waitcnt lgkmcnt(10)
	v_pk_fma_f32 v[114:115], v[48:49], v[64:65], v[114:115] op_sel:[0,1,0] op_sel_hi:[1,1,1]
	ds_read_b128 v[92:95], v6 offset:8448
	v_fmac_f32_e32 v16, v64, v61
	v_pk_fma_f32 v[116:117], v[50:51], v[64:65], v[116:117] op_sel:[0,1,0] op_sel_hi:[1,1,1]
	v_fma_f32 v14, -v10, v58, v14
	ds_read_b128 v[100:103], v6 offset:8960
	v_fmac_f32_e32 v16, v65, v63
	v_pk_fma_f32 v[114:115], v[44:45], v[10:11], v[114:115] op_sel_hi:[1,0,1] neg_lo:[1,0,0] neg_hi:[1,0,0]
	v_fma_f32 v16, -v10, v60, v16
	ds_read_b128 v[108:111], v7 offset:37024
	v_pk_fma_f32 v[116:117], v[46:47], v[10:11], v[116:117] op_sel_hi:[1,0,1] neg_lo:[1,0,0] neg_hi:[1,0,0]
	v_add_f32_dpp v14, v14, v14 row_ror:8 row_mask:0xf bank_mask:0xf bound_ctrl:1
	v_fma_f32 v16, -v12, v62, v16
	v_pk_fma_f32 v[2:3], v[52:53], v[12:13], v[114:115] op_sel_hi:[1,0,1] neg_lo:[1,0,0] neg_hi:[1,0,0]
	v_add_f32_dpp v14, v14, v14 row_ror:4 row_mask:0xf bank_mask:0xf bound_ctrl:1
	v_pk_fma_f32 v[4:5], v[54:55], v[12:13], v[116:117] op_sel_hi:[1,0,1] neg_lo:[1,0,0] neg_hi:[1,0,0]
	v_add_f32_dpp v16, v16, v16 row_ror:8 row_mask:0xf bank_mask:0xf bound_ctrl:1
	v_add_f32_dpp v14, v14, v14 row_ror:2 row_mask:0xf bank_mask:0xf bound_ctrl:1
	s_nop 0
	v_add_f32_dpp v16, v16, v16 row_ror:4 row_mask:0xf bank_mask:0xf bound_ctrl:1
	v_add_f32_dpp v14, v14, v14 row_ror:1 row_mask:0xf bank_mask:0xf bound_ctrl:1
	s_nop 0
	v_add_f32_dpp v16, v16, v16 row_ror:2 row_mask:0xf bank_mask:0xf bound_ctrl:1
	s_nop 1
	v_add_f32_dpp v16, v16, v16 row_ror:1 row_mask:0xf bank_mask:0xf bound_ctrl:1
	ds_write2_b32 v9, v14, v16 offset0:64 offset1:80
	s_waitcnt lgkmcnt(8)
	v_pk_mul_f32 v[10:11], v[4:5], v[70:71]
	ds_read_b128 v[20:23], v6 offset:9216
	v_pk_mul_f32 v[12:13], v[4:5], v[78:79]
	v_pk_fma_f32 v[10:11], v[2:3], v[68:69], v[10:11]
	v_pk_fma_f32 v[12:13], v[2:3], v[76:77], v[12:13]
	ds_read_b128 v[28:31], v6 offset:9728
	v_pk_mul_f32 v[14:15], v[4:5], v[74:75]
	v_add_f32_e32 v10, v10, v11
	v_add_f32_e32 v12, v12, v13
	ds_read_b128 v[24:27], v6 offset:9472
	v_pk_mul_f32 v[16:17], v[4:5], v[82:83]
	v_fma_f32 v12, -v104, v10, v12
	v_add_f32_dpp v10, v10, v10 row_ror:8 row_mask:0xf bank_mask:0xf bound_ctrl:1
	ds_read_b128 v[32:35], v6 offset:9984
	v_pk_fma_f32 v[14:15], v[2:3], v[72:73], v[14:15]
	v_add_f32_dpp v12, v12, v12 row_ror:8 row_mask:0xf bank_mask:0xf bound_ctrl:1
	v_add_f32_dpp v10, v10, v10 row_ror:4 row_mask:0xf bank_mask:0xf bound_ctrl:1
	ds_read_b128 v[56:59], v7 offset:37056
	v_pk_fma_f32 v[16:17], v[2:3], v[80:81], v[16:17]
	v_add_f32_dpp v12, v12, v12 row_ror:4 row_mask:0xf bank_mask:0xf bound_ctrl:1
	v_add_f32_dpp v10, v10, v10 row_ror:2 row_mask:0xf bank_mask:0xf bound_ctrl:1
	ds_read_b128 v[36:39], v6 offset:10240
	s_waitcnt lgkmcnt(11)
	v_pk_mul_f32 v[114:115], v[2:3], v[84:85]
	v_add_f32_dpp v12, v12, v12 row_ror:2 row_mask:0xf bank_mask:0xf bound_ctrl:1
	v_add_f32_dpp v10, v10, v10 row_ror:1 row_mask:0xf bank_mask:0xf bound_ctrl:1
	ds_read_b128 v[40:43], v6 offset:10496
	v_pk_mul_f32 v[116:117], v[4:5], v[86:87]
	v_add_f32_dpp v12, v12, v12 row_ror:1 row_mask:0xf bank_mask:0xf bound_ctrl:1
	v_add_f32_e32 v14, v14, v15
	ds_read2_b32 v[64:65], v8 offset0:128 offset1:144
	v_pk_fma_f32 v[114:115], v[88:89], v[112:113], v[114:115] op_sel_hi:[1,0,1]
	v_add_f32_e32 v16, v16, v17
	v_pk_fma_f32 v[116:117], v[90:91], v[112:113], v[116:117] op_sel_hi:[1,0,1]
	ds_read_b128 v[48:51], v6 offset:11008
	v_fmac_f32_e32 v12, v112, v105
	v_fmac_f32_e32 v14, v112, v107
	s_waitcnt lgkmcnt(10)
	v_pk_fma_f32 v[114:115], v[96:97], v[112:113], v[114:115] op_sel:[0,1,0] op_sel_hi:[1,1,1]
	ds_read_b128 v[44:47], v6 offset:10752
	v_fmac_f32_e32 v16, v112, v109
	v_pk_fma_f32 v[116:117], v[98:99], v[112:113], v[116:117] op_sel:[0,1,0] op_sel_hi:[1,1,1]
	v_fma_f32 v14, -v10, v106, v14
	ds_read_b128 v[52:55], v6 offset:11264
	v_fmac_f32_e32 v16, v113, v111
	v_pk_fma_f32 v[114:115], v[92:93], v[10:11], v[114:115] op_sel_hi:[1,0,1] neg_lo:[1,0,0] neg_hi:[1,0,0]
	v_fma_f32 v16, -v10, v108, v16
	ds_read_b128 v[60:63], v7 offset:37072
	v_pk_fma_f32 v[116:117], v[94:95], v[10:11], v[116:117] op_sel_hi:[1,0,1] neg_lo:[1,0,0] neg_hi:[1,0,0]
	v_add_f32_dpp v14, v14, v14 row_ror:8 row_mask:0xf bank_mask:0xf bound_ctrl:1
	v_fma_f32 v16, -v12, v110, v16
	v_pk_fma_f32 v[2:3], v[100:101], v[12:13], v[114:115] op_sel_hi:[1,0,1] neg_lo:[1,0,0] neg_hi:[1,0,0]
	v_add_f32_dpp v14, v14, v14 row_ror:4 row_mask:0xf bank_mask:0xf bound_ctrl:1
	v_pk_fma_f32 v[4:5], v[102:103], v[12:13], v[116:117] op_sel_hi:[1,0,1] neg_lo:[1,0,0] neg_hi:[1,0,0]
	v_add_f32_dpp v16, v16, v16 row_ror:8 row_mask:0xf bank_mask:0xf bound_ctrl:1
	v_add_f32_dpp v14, v14, v14 row_ror:2 row_mask:0xf bank_mask:0xf bound_ctrl:1
	s_nop 0
	v_add_f32_dpp v16, v16, v16 row_ror:4 row_mask:0xf bank_mask:0xf bound_ctrl:1
	v_add_f32_dpp v14, v14, v14 row_ror:1 row_mask:0xf bank_mask:0xf bound_ctrl:1
	s_nop 0
	v_add_f32_dpp v16, v16, v16 row_ror:2 row_mask:0xf bank_mask:0xf bound_ctrl:1
	s_nop 1
	v_add_f32_dpp v16, v16, v16 row_ror:1 row_mask:0xf bank_mask:0xf bound_ctrl:1
	ds_write2_b32 v9, v14, v16 offset0:96 offset1:112
	s_waitcnt lgkmcnt(8)
	v_pk_mul_f32 v[10:11], v[4:5], v[22:23]
	ds_read_b128 v[68:71], v6 offset:11520
	v_pk_mul_f32 v[12:13], v[4:5], v[30:31]
	v_pk_fma_f32 v[10:11], v[2:3], v[20:21], v[10:11]
	v_pk_fma_f32 v[12:13], v[2:3], v[28:29], v[12:13]
	ds_read_b128 v[76:79], v6 offset:12032
	v_pk_mul_f32 v[14:15], v[4:5], v[26:27]
	v_add_f32_e32 v10, v10, v11
	v_add_f32_e32 v12, v12, v13
	ds_read_b128 v[72:75], v6 offset:11776
	v_pk_mul_f32 v[16:17], v[4:5], v[34:35]
	v_fma_f32 v12, -v56, v10, v12
	v_add_f32_dpp v10, v10, v10 row_ror:8 row_mask:0xf bank_mask:0xf bound_ctrl:1
	ds_read_b128 v[80:83], v6 offset:12288
	v_pk_fma_f32 v[14:15], v[2:3], v[24:25], v[14:15]
	v_add_f32_dpp v12, v12, v12 row_ror:8 row_mask:0xf bank_mask:0xf bound_ctrl:1
	v_add_f32_dpp v10, v10, v10 row_ror:4 row_mask:0xf bank_mask:0xf bound_ctrl:1
	ds_read_b128 v[104:107], v7 offset:37104
	v_pk_fma_f32 v[16:17], v[2:3], v[32:33], v[16:17]
	v_add_f32_dpp v12, v12, v12 row_ror:4 row_mask:0xf bank_mask:0xf bound_ctrl:1
	v_add_f32_dpp v10, v10, v10 row_ror:2 row_mask:0xf bank_mask:0xf bound_ctrl:1
	ds_read_b128 v[84:87], v6 offset:12544
	s_waitcnt lgkmcnt(11)
	v_pk_mul_f32 v[114:115], v[2:3], v[36:37]
	v_add_f32_dpp v12, v12, v12 row_ror:2 row_mask:0xf bank_mask:0xf bound_ctrl:1
	v_add_f32_dpp v10, v10, v10 row_ror:1 row_mask:0xf bank_mask:0xf bound_ctrl:1
	ds_read_b128 v[88:91], v6 offset:12800
	v_pk_mul_f32 v[116:117], v[4:5], v[38:39]
	v_add_f32_dpp v12, v12, v12 row_ror:1 row_mask:0xf bank_mask:0xf bound_ctrl:1
	v_add_f32_e32 v14, v14, v15
	ds_read2_b32 v[112:113], v8 offset0:160 offset1:176
	v_pk_fma_f32 v[114:115], v[40:41], v[64:65], v[114:115] op_sel_hi:[1,0,1]
	v_add_f32_e32 v16, v16, v17
	v_pk_fma_f32 v[116:117], v[42:43], v[64:65], v[116:117] op_sel_hi:[1,0,1]
	ds_read_b128 v[96:99], v6 offset:13312
	v_fmac_f32_e32 v12, v64, v57
	v_fmac_f32_e32 v14, v64, v59
	s_waitcnt lgkmcnt(10)
	v_pk_fma_f32 v[114:115], v[48:49], v[64:65], v[114:115] op_sel:[0,1,0] op_sel_hi:[1,1,1]
	ds_read_b128 v[92:95], v6 offset:13056
	v_fmac_f32_e32 v16, v64, v61
	v_pk_fma_f32 v[116:117], v[50:51], v[64:65], v[116:117] op_sel:[0,1,0] op_sel_hi:[1,1,1]
	v_fma_f32 v14, -v10, v58, v14
	ds_read_b128 v[100:103], v6 offset:13568
	v_fmac_f32_e32 v16, v65, v63
	v_pk_fma_f32 v[114:115], v[44:45], v[10:11], v[114:115] op_sel_hi:[1,0,1] neg_lo:[1,0,0] neg_hi:[1,0,0]
	v_fma_f32 v16, -v10, v60, v16
	ds_read_b128 v[108:111], v7 offset:37120
	v_pk_fma_f32 v[116:117], v[46:47], v[10:11], v[116:117] op_sel_hi:[1,0,1] neg_lo:[1,0,0] neg_hi:[1,0,0]
	v_add_f32_dpp v14, v14, v14 row_ror:8 row_mask:0xf bank_mask:0xf bound_ctrl:1
	v_fma_f32 v16, -v12, v62, v16
	v_pk_fma_f32 v[2:3], v[52:53], v[12:13], v[114:115] op_sel_hi:[1,0,1] neg_lo:[1,0,0] neg_hi:[1,0,0]
	v_add_f32_dpp v14, v14, v14 row_ror:4 row_mask:0xf bank_mask:0xf bound_ctrl:1
	v_pk_fma_f32 v[4:5], v[54:55], v[12:13], v[116:117] op_sel_hi:[1,0,1] neg_lo:[1,0,0] neg_hi:[1,0,0]
	v_add_f32_dpp v16, v16, v16 row_ror:8 row_mask:0xf bank_mask:0xf bound_ctrl:1
	v_add_f32_dpp v14, v14, v14 row_ror:2 row_mask:0xf bank_mask:0xf bound_ctrl:1
	s_nop 0
	v_add_f32_dpp v16, v16, v16 row_ror:4 row_mask:0xf bank_mask:0xf bound_ctrl:1
	v_add_f32_dpp v14, v14, v14 row_ror:1 row_mask:0xf bank_mask:0xf bound_ctrl:1
	s_nop 0
	v_add_f32_dpp v16, v16, v16 row_ror:2 row_mask:0xf bank_mask:0xf bound_ctrl:1
	s_nop 1
	v_add_f32_dpp v16, v16, v16 row_ror:1 row_mask:0xf bank_mask:0xf bound_ctrl:1
	ds_write2_b32 v9, v14, v16 offset0:128 offset1:144
	s_waitcnt lgkmcnt(8)
	v_pk_mul_f32 v[10:11], v[4:5], v[70:71]
	ds_read_b128 v[20:23], v6 offset:13824
	v_pk_mul_f32 v[12:13], v[4:5], v[78:79]
	v_pk_fma_f32 v[10:11], v[2:3], v[68:69], v[10:11]
	v_pk_fma_f32 v[12:13], v[2:3], v[76:77], v[12:13]
	ds_read_b128 v[28:31], v6 offset:14336
	v_pk_mul_f32 v[14:15], v[4:5], v[74:75]
	v_add_f32_e32 v10, v10, v11
	v_add_f32_e32 v12, v12, v13
	ds_read_b128 v[24:27], v6 offset:14080
	v_pk_mul_f32 v[16:17], v[4:5], v[82:83]
	v_fma_f32 v12, -v104, v10, v12
	v_add_f32_dpp v10, v10, v10 row_ror:8 row_mask:0xf bank_mask:0xf bound_ctrl:1
	ds_read_b128 v[32:35], v6 offset:14592
	v_pk_fma_f32 v[14:15], v[2:3], v[72:73], v[14:15]
	v_add_f32_dpp v12, v12, v12 row_ror:8 row_mask:0xf bank_mask:0xf bound_ctrl:1
	v_add_f32_dpp v10, v10, v10 row_ror:4 row_mask:0xf bank_mask:0xf bound_ctrl:1
	ds_read_b128 v[56:59], v7 offset:37152
	v_pk_fma_f32 v[16:17], v[2:3], v[80:81], v[16:17]
	v_add_f32_dpp v12, v12, v12 row_ror:4 row_mask:0xf bank_mask:0xf bound_ctrl:1
	v_add_f32_dpp v10, v10, v10 row_ror:2 row_mask:0xf bank_mask:0xf bound_ctrl:1
	ds_read_b128 v[36:39], v6 offset:14848
	s_waitcnt lgkmcnt(11)
	v_pk_mul_f32 v[114:115], v[2:3], v[84:85]
	v_add_f32_dpp v12, v12, v12 row_ror:2 row_mask:0xf bank_mask:0xf bound_ctrl:1
	v_add_f32_dpp v10, v10, v10 row_ror:1 row_mask:0xf bank_mask:0xf bound_ctrl:1
	ds_read_b128 v[40:43], v6 offset:15104
	v_pk_mul_f32 v[116:117], v[4:5], v[86:87]
	v_add_f32_dpp v12, v12, v12 row_ror:1 row_mask:0xf bank_mask:0xf bound_ctrl:1
	v_add_f32_e32 v14, v14, v15
	ds_read2_b32 v[64:65], v8 offset0:192 offset1:208
	v_pk_fma_f32 v[114:115], v[88:89], v[112:113], v[114:115] op_sel_hi:[1,0,1]
	v_add_f32_e32 v16, v16, v17
	v_pk_fma_f32 v[116:117], v[90:91], v[112:113], v[116:117] op_sel_hi:[1,0,1]
	ds_read_b128 v[48:51], v6 offset:15616
	v_fmac_f32_e32 v12, v112, v105
	v_fmac_f32_e32 v14, v112, v107
	s_waitcnt lgkmcnt(10)
	v_pk_fma_f32 v[114:115], v[96:97], v[112:113], v[114:115] op_sel:[0,1,0] op_sel_hi:[1,1,1]
	ds_read_b128 v[44:47], v6 offset:15360
	v_fmac_f32_e32 v16, v112, v109
	v_pk_fma_f32 v[116:117], v[98:99], v[112:113], v[116:117] op_sel:[0,1,0] op_sel_hi:[1,1,1]
	v_fma_f32 v14, -v10, v106, v14
	ds_read_b128 v[52:55], v6 offset:15872
	v_fmac_f32_e32 v16, v113, v111
	v_pk_fma_f32 v[114:115], v[92:93], v[10:11], v[114:115] op_sel_hi:[1,0,1] neg_lo:[1,0,0] neg_hi:[1,0,0]
	v_fma_f32 v16, -v10, v108, v16
	ds_read_b128 v[60:63], v7 offset:37168
	v_pk_fma_f32 v[116:117], v[94:95], v[10:11], v[116:117] op_sel_hi:[1,0,1] neg_lo:[1,0,0] neg_hi:[1,0,0]
	v_add_f32_dpp v14, v14, v14 row_ror:8 row_mask:0xf bank_mask:0xf bound_ctrl:1
	v_fma_f32 v16, -v12, v110, v16
	v_pk_fma_f32 v[2:3], v[100:101], v[12:13], v[114:115] op_sel_hi:[1,0,1] neg_lo:[1,0,0] neg_hi:[1,0,0]
	v_add_f32_dpp v14, v14, v14 row_ror:4 row_mask:0xf bank_mask:0xf bound_ctrl:1
	v_pk_fma_f32 v[4:5], v[102:103], v[12:13], v[116:117] op_sel_hi:[1,0,1] neg_lo:[1,0,0] neg_hi:[1,0,0]
	v_add_f32_dpp v16, v16, v16 row_ror:8 row_mask:0xf bank_mask:0xf bound_ctrl:1
	v_add_f32_dpp v14, v14, v14 row_ror:2 row_mask:0xf bank_mask:0xf bound_ctrl:1
	s_nop 0
	v_add_f32_dpp v16, v16, v16 row_ror:4 row_mask:0xf bank_mask:0xf bound_ctrl:1
	v_add_f32_dpp v14, v14, v14 row_ror:1 row_mask:0xf bank_mask:0xf bound_ctrl:1
	s_nop 0
	v_add_f32_dpp v16, v16, v16 row_ror:2 row_mask:0xf bank_mask:0xf bound_ctrl:1
	s_nop 1
	v_add_f32_dpp v16, v16, v16 row_ror:1 row_mask:0xf bank_mask:0xf bound_ctrl:1
	ds_write2_b32 v9, v14, v16 offset0:160 offset1:176
	s_waitcnt lgkmcnt(8)
	v_pk_mul_f32 v[10:11], v[4:5], v[22:23]
	ds_read_b128 v[68:71], v6 offset:16128
	v_pk_mul_f32 v[12:13], v[4:5], v[30:31]
	v_pk_fma_f32 v[10:11], v[2:3], v[20:21], v[10:11]
	v_pk_fma_f32 v[12:13], v[2:3], v[28:29], v[12:13]
	ds_read_b128 v[76:79], v6 offset:16640
	v_pk_mul_f32 v[14:15], v[4:5], v[26:27]
	v_add_f32_e32 v10, v10, v11
	v_add_f32_e32 v12, v12, v13
	ds_read_b128 v[72:75], v6 offset:16384
	v_pk_mul_f32 v[16:17], v[4:5], v[34:35]
	v_fma_f32 v12, -v56, v10, v12
	v_add_f32_dpp v10, v10, v10 row_ror:8 row_mask:0xf bank_mask:0xf bound_ctrl:1
	ds_read_b128 v[80:83], v6 offset:16896
	v_pk_fma_f32 v[14:15], v[2:3], v[24:25], v[14:15]
	v_add_f32_dpp v12, v12, v12 row_ror:8 row_mask:0xf bank_mask:0xf bound_ctrl:1
	v_add_f32_dpp v10, v10, v10 row_ror:4 row_mask:0xf bank_mask:0xf bound_ctrl:1
	ds_read_b128 v[104:107], v7 offset:37200
	v_pk_fma_f32 v[16:17], v[2:3], v[32:33], v[16:17]
	v_add_f32_dpp v12, v12, v12 row_ror:4 row_mask:0xf bank_mask:0xf bound_ctrl:1
	v_add_f32_dpp v10, v10, v10 row_ror:2 row_mask:0xf bank_mask:0xf bound_ctrl:1
	ds_read_b128 v[84:87], v6 offset:17152
	s_waitcnt lgkmcnt(11)
	v_pk_mul_f32 v[114:115], v[2:3], v[36:37]
	v_add_f32_dpp v12, v12, v12 row_ror:2 row_mask:0xf bank_mask:0xf bound_ctrl:1
	v_add_f32_dpp v10, v10, v10 row_ror:1 row_mask:0xf bank_mask:0xf bound_ctrl:1
	ds_read_b128 v[88:91], v6 offset:17408
	v_pk_mul_f32 v[116:117], v[4:5], v[38:39]
	v_add_f32_dpp v12, v12, v12 row_ror:1 row_mask:0xf bank_mask:0xf bound_ctrl:1
	v_add_f32_e32 v14, v14, v15
	ds_read2_b32 v[112:113], v8 offset0:224 offset1:240
	v_pk_fma_f32 v[114:115], v[40:41], v[64:65], v[114:115] op_sel_hi:[1,0,1]
	v_add_f32_e32 v16, v16, v17
	v_pk_fma_f32 v[116:117], v[42:43], v[64:65], v[116:117] op_sel_hi:[1,0,1]
	ds_read_b128 v[96:99], v6 offset:17920
	v_fmac_f32_e32 v12, v64, v57
	v_fmac_f32_e32 v14, v64, v59
	s_waitcnt lgkmcnt(10)
	v_pk_fma_f32 v[114:115], v[48:49], v[64:65], v[114:115] op_sel:[0,1,0] op_sel_hi:[1,1,1]
	ds_read_b128 v[92:95], v6 offset:17664
	v_fmac_f32_e32 v16, v64, v61
	v_pk_fma_f32 v[116:117], v[50:51], v[64:65], v[116:117] op_sel:[0,1,0] op_sel_hi:[1,1,1]
	v_fma_f32 v14, -v10, v58, v14
	ds_read_b128 v[100:103], v6 offset:18176
	v_fmac_f32_e32 v16, v65, v63
	v_pk_fma_f32 v[114:115], v[44:45], v[10:11], v[114:115] op_sel_hi:[1,0,1] neg_lo:[1,0,0] neg_hi:[1,0,0]
	v_fma_f32 v16, -v10, v60, v16
	ds_read_b128 v[108:111], v7 offset:37216
	v_pk_fma_f32 v[116:117], v[46:47], v[10:11], v[116:117] op_sel_hi:[1,0,1] neg_lo:[1,0,0] neg_hi:[1,0,0]
	v_add_f32_dpp v14, v14, v14 row_ror:8 row_mask:0xf bank_mask:0xf bound_ctrl:1
	v_fma_f32 v16, -v12, v62, v16
	v_pk_fma_f32 v[2:3], v[52:53], v[12:13], v[114:115] op_sel_hi:[1,0,1] neg_lo:[1,0,0] neg_hi:[1,0,0]
	v_add_f32_dpp v14, v14, v14 row_ror:4 row_mask:0xf bank_mask:0xf bound_ctrl:1
	v_pk_fma_f32 v[4:5], v[54:55], v[12:13], v[116:117] op_sel_hi:[1,0,1] neg_lo:[1,0,0] neg_hi:[1,0,0]
	v_add_f32_dpp v16, v16, v16 row_ror:8 row_mask:0xf bank_mask:0xf bound_ctrl:1
	v_add_f32_dpp v14, v14, v14 row_ror:2 row_mask:0xf bank_mask:0xf bound_ctrl:1
	s_nop 0
	v_add_f32_dpp v16, v16, v16 row_ror:4 row_mask:0xf bank_mask:0xf bound_ctrl:1
	v_add_f32_dpp v14, v14, v14 row_ror:1 row_mask:0xf bank_mask:0xf bound_ctrl:1
	s_nop 0
	v_add_f32_dpp v16, v16, v16 row_ror:2 row_mask:0xf bank_mask:0xf bound_ctrl:1
	s_nop 1
	v_add_f32_dpp v16, v16, v16 row_ror:1 row_mask:0xf bank_mask:0xf bound_ctrl:1
	ds_write2_b32 v9, v14, v16 offset0:192 offset1:208
	s_waitcnt lgkmcnt(8)
	v_pk_mul_f32 v[10:11], v[4:5], v[70:71]
	ds_read_b128 v[20:23], v6 offset:18432
	v_pk_mul_f32 v[12:13], v[4:5], v[78:79]
	v_pk_fma_f32 v[10:11], v[2:3], v[68:69], v[10:11]
	v_pk_fma_f32 v[12:13], v[2:3], v[76:77], v[12:13]
	ds_read_b128 v[28:31], v6 offset:18944
	v_pk_mul_f32 v[14:15], v[4:5], v[74:75]
	v_add_f32_e32 v10, v10, v11
	v_add_f32_e32 v12, v12, v13
	ds_read_b128 v[24:27], v6 offset:18688
	v_pk_mul_f32 v[16:17], v[4:5], v[82:83]
	v_fma_f32 v12, -v104, v10, v12
	v_add_f32_dpp v10, v10, v10 row_ror:8 row_mask:0xf bank_mask:0xf bound_ctrl:1
	ds_read_b128 v[32:35], v6 offset:19200
	v_pk_fma_f32 v[14:15], v[2:3], v[72:73], v[14:15]
	v_add_f32_dpp v12, v12, v12 row_ror:8 row_mask:0xf bank_mask:0xf bound_ctrl:1
	v_add_f32_dpp v10, v10, v10 row_ror:4 row_mask:0xf bank_mask:0xf bound_ctrl:1
	ds_read_b128 v[56:59], v7 offset:37248
	v_pk_fma_f32 v[16:17], v[2:3], v[80:81], v[16:17]
	v_add_f32_dpp v12, v12, v12 row_ror:4 row_mask:0xf bank_mask:0xf bound_ctrl:1
	v_add_f32_dpp v10, v10, v10 row_ror:2 row_mask:0xf bank_mask:0xf bound_ctrl:1
	ds_read_b128 v[36:39], v6 offset:19456
	s_waitcnt lgkmcnt(11)
	v_pk_mul_f32 v[114:115], v[2:3], v[84:85]
	v_add_f32_dpp v12, v12, v12 row_ror:2 row_mask:0xf bank_mask:0xf bound_ctrl:1
	v_add_f32_dpp v10, v10, v10 row_ror:1 row_mask:0xf bank_mask:0xf bound_ctrl:1
	ds_read_b128 v[40:43], v6 offset:19712
	v_pk_mul_f32 v[116:117], v[4:5], v[86:87]
	v_add_f32_dpp v12, v12, v12 row_ror:1 row_mask:0xf bank_mask:0xf bound_ctrl:1
	v_add_f32_e32 v14, v14, v15
	ds_read2_b32 v[64:65], v120 offset0:0 offset1:16
	v_pk_fma_f32 v[114:115], v[88:89], v[112:113], v[114:115] op_sel_hi:[1,0,1]
	v_add_f32_e32 v16, v16, v17
	v_pk_fma_f32 v[116:117], v[90:91], v[112:113], v[116:117] op_sel_hi:[1,0,1]
	ds_read_b128 v[48:51], v6 offset:20224
	v_fmac_f32_e32 v12, v112, v105
	v_fmac_f32_e32 v14, v112, v107
	s_waitcnt lgkmcnt(10)
	v_pk_fma_f32 v[114:115], v[96:97], v[112:113], v[114:115] op_sel:[0,1,0] op_sel_hi:[1,1,1]
	ds_read_b128 v[44:47], v6 offset:19968
	v_fmac_f32_e32 v16, v112, v109
	v_pk_fma_f32 v[116:117], v[98:99], v[112:113], v[116:117] op_sel:[0,1,0] op_sel_hi:[1,1,1]
	v_fma_f32 v14, -v10, v106, v14
	ds_read_b128 v[52:55], v6 offset:20480
	v_fmac_f32_e32 v16, v113, v111
	v_pk_fma_f32 v[114:115], v[92:93], v[10:11], v[114:115] op_sel_hi:[1,0,1] neg_lo:[1,0,0] neg_hi:[1,0,0]
	v_fma_f32 v16, -v10, v108, v16
	ds_read_b128 v[60:63], v7 offset:37264
	v_pk_fma_f32 v[116:117], v[94:95], v[10:11], v[116:117] op_sel_hi:[1,0,1] neg_lo:[1,0,0] neg_hi:[1,0,0]
	v_add_f32_dpp v14, v14, v14 row_ror:8 row_mask:0xf bank_mask:0xf bound_ctrl:1
	v_fma_f32 v16, -v12, v110, v16
	v_pk_fma_f32 v[2:3], v[100:101], v[12:13], v[114:115] op_sel_hi:[1,0,1] neg_lo:[1,0,0] neg_hi:[1,0,0]
	v_add_f32_dpp v14, v14, v14 row_ror:4 row_mask:0xf bank_mask:0xf bound_ctrl:1
	v_pk_fma_f32 v[4:5], v[102:103], v[12:13], v[116:117] op_sel_hi:[1,0,1] neg_lo:[1,0,0] neg_hi:[1,0,0]
	v_add_f32_dpp v16, v16, v16 row_ror:8 row_mask:0xf bank_mask:0xf bound_ctrl:1
	v_add_f32_dpp v14, v14, v14 row_ror:2 row_mask:0xf bank_mask:0xf bound_ctrl:1
	s_nop 0
	v_add_f32_dpp v16, v16, v16 row_ror:4 row_mask:0xf bank_mask:0xf bound_ctrl:1
	v_add_f32_dpp v14, v14, v14 row_ror:1 row_mask:0xf bank_mask:0xf bound_ctrl:1
	s_nop 0
	v_add_f32_dpp v16, v16, v16 row_ror:2 row_mask:0xf bank_mask:0xf bound_ctrl:1
	s_nop 1
	v_add_f32_dpp v16, v16, v16 row_ror:1 row_mask:0xf bank_mask:0xf bound_ctrl:1
	ds_write2_b32 v9, v14, v16 offset0:224 offset1:240
	s_waitcnt lgkmcnt(8)
	v_pk_mul_f32 v[10:11], v[4:5], v[22:23]
	ds_read_b128 v[68:71], v6 offset:20736
	v_pk_mul_f32 v[12:13], v[4:5], v[30:31]
	v_pk_fma_f32 v[10:11], v[2:3], v[20:21], v[10:11]
	v_pk_fma_f32 v[12:13], v[2:3], v[28:29], v[12:13]
	ds_read_b128 v[76:79], v6 offset:21248
	v_pk_mul_f32 v[14:15], v[4:5], v[26:27]
	v_add_f32_e32 v10, v10, v11
	v_add_f32_e32 v12, v12, v13
	ds_read_b128 v[72:75], v6 offset:20992
	v_pk_mul_f32 v[16:17], v[4:5], v[34:35]
	v_fma_f32 v12, -v56, v10, v12
	v_add_f32_dpp v10, v10, v10 row_ror:8 row_mask:0xf bank_mask:0xf bound_ctrl:1
	ds_read_b128 v[80:83], v6 offset:21504
	v_pk_fma_f32 v[14:15], v[2:3], v[24:25], v[14:15]
	v_add_f32_dpp v12, v12, v12 row_ror:8 row_mask:0xf bank_mask:0xf bound_ctrl:1
	v_add_f32_dpp v10, v10, v10 row_ror:4 row_mask:0xf bank_mask:0xf bound_ctrl:1
	ds_read_b128 v[104:107], v7 offset:37296
	v_pk_fma_f32 v[16:17], v[2:3], v[32:33], v[16:17]
	v_add_f32_dpp v12, v12, v12 row_ror:4 row_mask:0xf bank_mask:0xf bound_ctrl:1
	v_add_f32_dpp v10, v10, v10 row_ror:2 row_mask:0xf bank_mask:0xf bound_ctrl:1
	ds_read_b128 v[84:87], v6 offset:21760
	s_waitcnt lgkmcnt(11)
	v_pk_mul_f32 v[114:115], v[2:3], v[36:37]
	v_add_f32_dpp v12, v12, v12 row_ror:2 row_mask:0xf bank_mask:0xf bound_ctrl:1
	v_add_f32_dpp v10, v10, v10 row_ror:1 row_mask:0xf bank_mask:0xf bound_ctrl:1
	ds_read_b128 v[88:91], v6 offset:22016
	v_pk_mul_f32 v[116:117], v[4:5], v[38:39]
	v_add_f32_dpp v12, v12, v12 row_ror:1 row_mask:0xf bank_mask:0xf bound_ctrl:1
	v_add_f32_e32 v14, v14, v15
	ds_read2_b32 v[112:113], v120 offset0:32 offset1:48
	v_pk_fma_f32 v[114:115], v[40:41], v[64:65], v[114:115] op_sel_hi:[1,0,1]
	v_add_f32_e32 v16, v16, v17
	v_pk_fma_f32 v[116:117], v[42:43], v[64:65], v[116:117] op_sel_hi:[1,0,1]
	ds_read_b128 v[96:99], v6 offset:22528
	v_fmac_f32_e32 v12, v64, v57
	v_fmac_f32_e32 v14, v64, v59
	s_waitcnt lgkmcnt(10)
	v_pk_fma_f32 v[114:115], v[48:49], v[64:65], v[114:115] op_sel:[0,1,0] op_sel_hi:[1,1,1]
	ds_read_b128 v[92:95], v6 offset:22272
	v_fmac_f32_e32 v16, v64, v61
	v_pk_fma_f32 v[116:117], v[50:51], v[64:65], v[116:117] op_sel:[0,1,0] op_sel_hi:[1,1,1]
	v_fma_f32 v14, -v10, v58, v14
	ds_read_b128 v[100:103], v6 offset:22784
	v_fmac_f32_e32 v16, v65, v63
	v_pk_fma_f32 v[114:115], v[44:45], v[10:11], v[114:115] op_sel_hi:[1,0,1] neg_lo:[1,0,0] neg_hi:[1,0,0]
	v_fma_f32 v16, -v10, v60, v16
	ds_read_b128 v[108:111], v7 offset:37312
	v_pk_fma_f32 v[116:117], v[46:47], v[10:11], v[116:117] op_sel_hi:[1,0,1] neg_lo:[1,0,0] neg_hi:[1,0,0]
	v_add_f32_dpp v14, v14, v14 row_ror:8 row_mask:0xf bank_mask:0xf bound_ctrl:1
	v_fma_f32 v16, -v12, v62, v16
	v_pk_fma_f32 v[2:3], v[52:53], v[12:13], v[114:115] op_sel_hi:[1,0,1] neg_lo:[1,0,0] neg_hi:[1,0,0]
	v_add_f32_dpp v14, v14, v14 row_ror:4 row_mask:0xf bank_mask:0xf bound_ctrl:1
	v_pk_fma_f32 v[4:5], v[54:55], v[12:13], v[116:117] op_sel_hi:[1,0,1] neg_lo:[1,0,0] neg_hi:[1,0,0]
	v_add_f32_dpp v16, v16, v16 row_ror:8 row_mask:0xf bank_mask:0xf bound_ctrl:1
	v_add_f32_dpp v14, v14, v14 row_ror:2 row_mask:0xf bank_mask:0xf bound_ctrl:1
	s_nop 0
	v_add_f32_dpp v16, v16, v16 row_ror:4 row_mask:0xf bank_mask:0xf bound_ctrl:1
	v_add_f32_dpp v14, v14, v14 row_ror:1 row_mask:0xf bank_mask:0xf bound_ctrl:1
	s_nop 0
	v_add_f32_dpp v16, v16, v16 row_ror:2 row_mask:0xf bank_mask:0xf bound_ctrl:1
	s_nop 1
	v_add_f32_dpp v16, v16, v16 row_ror:1 row_mask:0xf bank_mask:0xf bound_ctrl:1
	ds_write2_b32 v119, v14, v16 offset0:0 offset1:16
	s_waitcnt lgkmcnt(8)
	v_pk_mul_f32 v[10:11], v[4:5], v[70:71]
	ds_read_b128 v[20:23], v6 offset:23040
	v_pk_mul_f32 v[12:13], v[4:5], v[78:79]
	v_pk_fma_f32 v[10:11], v[2:3], v[68:69], v[10:11]
	v_pk_fma_f32 v[12:13], v[2:3], v[76:77], v[12:13]
	ds_read_b128 v[28:31], v6 offset:23552
	v_pk_mul_f32 v[14:15], v[4:5], v[74:75]
	v_add_f32_e32 v10, v10, v11
	v_add_f32_e32 v12, v12, v13
	ds_read_b128 v[24:27], v6 offset:23296
	v_pk_mul_f32 v[16:17], v[4:5], v[82:83]
	v_fma_f32 v12, -v104, v10, v12
	v_add_f32_dpp v10, v10, v10 row_ror:8 row_mask:0xf bank_mask:0xf bound_ctrl:1
	ds_read_b128 v[32:35], v6 offset:23808
	v_pk_fma_f32 v[14:15], v[2:3], v[72:73], v[14:15]
	v_add_f32_dpp v12, v12, v12 row_ror:8 row_mask:0xf bank_mask:0xf bound_ctrl:1
	v_add_f32_dpp v10, v10, v10 row_ror:4 row_mask:0xf bank_mask:0xf bound_ctrl:1
	ds_read_b128 v[56:59], v7 offset:37344
	v_pk_fma_f32 v[16:17], v[2:3], v[80:81], v[16:17]
	v_add_f32_dpp v12, v12, v12 row_ror:4 row_mask:0xf bank_mask:0xf bound_ctrl:1
	v_add_f32_dpp v10, v10, v10 row_ror:2 row_mask:0xf bank_mask:0xf bound_ctrl:1
	ds_read_b128 v[36:39], v6 offset:24064
	s_waitcnt lgkmcnt(11)
	v_pk_mul_f32 v[114:115], v[2:3], v[84:85]
	v_add_f32_dpp v12, v12, v12 row_ror:2 row_mask:0xf bank_mask:0xf bound_ctrl:1
	v_add_f32_dpp v10, v10, v10 row_ror:1 row_mask:0xf bank_mask:0xf bound_ctrl:1
	ds_read_b128 v[40:43], v6 offset:24320
	v_pk_mul_f32 v[116:117], v[4:5], v[86:87]
	v_add_f32_dpp v12, v12, v12 row_ror:1 row_mask:0xf bank_mask:0xf bound_ctrl:1
	v_add_f32_e32 v14, v14, v15
	ds_read2_b32 v[64:65], v120 offset0:64 offset1:80
	v_pk_fma_f32 v[114:115], v[88:89], v[112:113], v[114:115] op_sel_hi:[1,0,1]
	v_add_f32_e32 v16, v16, v17
	v_pk_fma_f32 v[116:117], v[90:91], v[112:113], v[116:117] op_sel_hi:[1,0,1]
	ds_read_b128 v[48:51], v6 offset:24832
	v_fmac_f32_e32 v12, v112, v105
	v_fmac_f32_e32 v14, v112, v107
	s_waitcnt lgkmcnt(10)
	v_pk_fma_f32 v[114:115], v[96:97], v[112:113], v[114:115] op_sel:[0,1,0] op_sel_hi:[1,1,1]
	ds_read_b128 v[44:47], v6 offset:24576
	v_fmac_f32_e32 v16, v112, v109
	v_pk_fma_f32 v[116:117], v[98:99], v[112:113], v[116:117] op_sel:[0,1,0] op_sel_hi:[1,1,1]
	v_fma_f32 v14, -v10, v106, v14
	ds_read_b128 v[52:55], v6 offset:25088
	v_fmac_f32_e32 v16, v113, v111
	v_pk_fma_f32 v[114:115], v[92:93], v[10:11], v[114:115] op_sel_hi:[1,0,1] neg_lo:[1,0,0] neg_hi:[1,0,0]
	v_fma_f32 v16, -v10, v108, v16
	ds_read_b128 v[60:63], v7 offset:37360
	v_pk_fma_f32 v[116:117], v[94:95], v[10:11], v[116:117] op_sel_hi:[1,0,1] neg_lo:[1,0,0] neg_hi:[1,0,0]
	v_add_f32_dpp v14, v14, v14 row_ror:8 row_mask:0xf bank_mask:0xf bound_ctrl:1
	v_fma_f32 v16, -v12, v110, v16
	v_pk_fma_f32 v[2:3], v[100:101], v[12:13], v[114:115] op_sel_hi:[1,0,1] neg_lo:[1,0,0] neg_hi:[1,0,0]
	v_add_f32_dpp v14, v14, v14 row_ror:4 row_mask:0xf bank_mask:0xf bound_ctrl:1
	v_pk_fma_f32 v[4:5], v[102:103], v[12:13], v[116:117] op_sel_hi:[1,0,1] neg_lo:[1,0,0] neg_hi:[1,0,0]
	v_add_f32_dpp v16, v16, v16 row_ror:8 row_mask:0xf bank_mask:0xf bound_ctrl:1
	v_add_f32_dpp v14, v14, v14 row_ror:2 row_mask:0xf bank_mask:0xf bound_ctrl:1
	s_nop 0
	v_add_f32_dpp v16, v16, v16 row_ror:4 row_mask:0xf bank_mask:0xf bound_ctrl:1
	v_add_f32_dpp v14, v14, v14 row_ror:1 row_mask:0xf bank_mask:0xf bound_ctrl:1
	s_nop 0
	v_add_f32_dpp v16, v16, v16 row_ror:2 row_mask:0xf bank_mask:0xf bound_ctrl:1
	s_nop 1
	v_add_f32_dpp v16, v16, v16 row_ror:1 row_mask:0xf bank_mask:0xf bound_ctrl:1
	ds_write2_b32 v119, v14, v16 offset0:32 offset1:48
	s_waitcnt lgkmcnt(8)
	v_pk_mul_f32 v[10:11], v[4:5], v[22:23]
	ds_read_b128 v[68:71], v6 offset:25344
	v_pk_mul_f32 v[12:13], v[4:5], v[30:31]
	v_pk_fma_f32 v[10:11], v[2:3], v[20:21], v[10:11]
	v_pk_fma_f32 v[12:13], v[2:3], v[28:29], v[12:13]
	ds_read_b128 v[76:79], v6 offset:25856
	v_pk_mul_f32 v[14:15], v[4:5], v[26:27]
	v_add_f32_e32 v10, v10, v11
	v_add_f32_e32 v12, v12, v13
	ds_read_b128 v[72:75], v6 offset:25600
	v_pk_mul_f32 v[16:17], v[4:5], v[34:35]
	v_fma_f32 v12, -v56, v10, v12
	v_add_f32_dpp v10, v10, v10 row_ror:8 row_mask:0xf bank_mask:0xf bound_ctrl:1
	ds_read_b128 v[80:83], v6 offset:26112
	v_pk_fma_f32 v[14:15], v[2:3], v[24:25], v[14:15]
	v_add_f32_dpp v12, v12, v12 row_ror:8 row_mask:0xf bank_mask:0xf bound_ctrl:1
	v_add_f32_dpp v10, v10, v10 row_ror:4 row_mask:0xf bank_mask:0xf bound_ctrl:1
	ds_read_b128 v[104:107], v7 offset:37392
	v_pk_fma_f32 v[16:17], v[2:3], v[32:33], v[16:17]
	v_add_f32_dpp v12, v12, v12 row_ror:4 row_mask:0xf bank_mask:0xf bound_ctrl:1
	v_add_f32_dpp v10, v10, v10 row_ror:2 row_mask:0xf bank_mask:0xf bound_ctrl:1
	ds_read_b128 v[84:87], v6 offset:26368
	s_waitcnt lgkmcnt(11)
	v_pk_mul_f32 v[114:115], v[2:3], v[36:37]
	v_add_f32_dpp v12, v12, v12 row_ror:2 row_mask:0xf bank_mask:0xf bound_ctrl:1
	v_add_f32_dpp v10, v10, v10 row_ror:1 row_mask:0xf bank_mask:0xf bound_ctrl:1
	ds_read_b128 v[88:91], v6 offset:26624
	v_pk_mul_f32 v[116:117], v[4:5], v[38:39]
	v_add_f32_dpp v12, v12, v12 row_ror:1 row_mask:0xf bank_mask:0xf bound_ctrl:1
	v_add_f32_e32 v14, v14, v15
	ds_read2_b32 v[112:113], v120 offset0:96 offset1:112
	v_pk_fma_f32 v[114:115], v[40:41], v[64:65], v[114:115] op_sel_hi:[1,0,1]
	v_add_f32_e32 v16, v16, v17
	v_pk_fma_f32 v[116:117], v[42:43], v[64:65], v[116:117] op_sel_hi:[1,0,1]
	ds_read_b128 v[96:99], v6 offset:27136
	v_fmac_f32_e32 v12, v64, v57
	v_fmac_f32_e32 v14, v64, v59
	s_waitcnt lgkmcnt(10)
	v_pk_fma_f32 v[114:115], v[48:49], v[64:65], v[114:115] op_sel:[0,1,0] op_sel_hi:[1,1,1]
	ds_read_b128 v[92:95], v6 offset:26880
	v_fmac_f32_e32 v16, v64, v61
	v_pk_fma_f32 v[116:117], v[50:51], v[64:65], v[116:117] op_sel:[0,1,0] op_sel_hi:[1,1,1]
	v_fma_f32 v14, -v10, v58, v14
	ds_read_b128 v[100:103], v6 offset:27392
	v_fmac_f32_e32 v16, v65, v63
	v_pk_fma_f32 v[114:115], v[44:45], v[10:11], v[114:115] op_sel_hi:[1,0,1] neg_lo:[1,0,0] neg_hi:[1,0,0]
	v_fma_f32 v16, -v10, v60, v16
	ds_read_b128 v[108:111], v7 offset:37408
	v_pk_fma_f32 v[116:117], v[46:47], v[10:11], v[116:117] op_sel_hi:[1,0,1] neg_lo:[1,0,0] neg_hi:[1,0,0]
	v_add_f32_dpp v14, v14, v14 row_ror:8 row_mask:0xf bank_mask:0xf bound_ctrl:1
	v_fma_f32 v16, -v12, v62, v16
	v_pk_fma_f32 v[2:3], v[52:53], v[12:13], v[114:115] op_sel_hi:[1,0,1] neg_lo:[1,0,0] neg_hi:[1,0,0]
	v_add_f32_dpp v14, v14, v14 row_ror:4 row_mask:0xf bank_mask:0xf bound_ctrl:1
	v_pk_fma_f32 v[4:5], v[54:55], v[12:13], v[116:117] op_sel_hi:[1,0,1] neg_lo:[1,0,0] neg_hi:[1,0,0]
	v_add_f32_dpp v16, v16, v16 row_ror:8 row_mask:0xf bank_mask:0xf bound_ctrl:1
	v_add_f32_dpp v14, v14, v14 row_ror:2 row_mask:0xf bank_mask:0xf bound_ctrl:1
	s_nop 0
	v_add_f32_dpp v16, v16, v16 row_ror:4 row_mask:0xf bank_mask:0xf bound_ctrl:1
	v_add_f32_dpp v14, v14, v14 row_ror:1 row_mask:0xf bank_mask:0xf bound_ctrl:1
	s_nop 0
	v_add_f32_dpp v16, v16, v16 row_ror:2 row_mask:0xf bank_mask:0xf bound_ctrl:1
	s_nop 1
	v_add_f32_dpp v16, v16, v16 row_ror:1 row_mask:0xf bank_mask:0xf bound_ctrl:1
	ds_write2_b32 v119, v14, v16 offset0:64 offset1:80
	s_waitcnt lgkmcnt(8)
	v_pk_mul_f32 v[10:11], v[4:5], v[70:71]
	ds_read_b128 v[20:23], v6 offset:27648
	v_pk_mul_f32 v[12:13], v[4:5], v[78:79]
	v_pk_fma_f32 v[10:11], v[2:3], v[68:69], v[10:11]
	v_pk_fma_f32 v[12:13], v[2:3], v[76:77], v[12:13]
	ds_read_b128 v[28:31], v6 offset:28160
	v_pk_mul_f32 v[14:15], v[4:5], v[74:75]
	v_add_f32_e32 v10, v10, v11
	v_add_f32_e32 v12, v12, v13
	ds_read_b128 v[24:27], v6 offset:27904
	v_pk_mul_f32 v[16:17], v[4:5], v[82:83]
	v_fma_f32 v12, -v104, v10, v12
	v_add_f32_dpp v10, v10, v10 row_ror:8 row_mask:0xf bank_mask:0xf bound_ctrl:1
	ds_read_b128 v[32:35], v6 offset:28416
	v_pk_fma_f32 v[14:15], v[2:3], v[72:73], v[14:15]
	v_add_f32_dpp v12, v12, v12 row_ror:8 row_mask:0xf bank_mask:0xf bound_ctrl:1
	v_add_f32_dpp v10, v10, v10 row_ror:4 row_mask:0xf bank_mask:0xf bound_ctrl:1
	ds_read_b128 v[56:59], v7 offset:37440
	v_pk_fma_f32 v[16:17], v[2:3], v[80:81], v[16:17]
	v_add_f32_dpp v12, v12, v12 row_ror:4 row_mask:0xf bank_mask:0xf bound_ctrl:1
	v_add_f32_dpp v10, v10, v10 row_ror:2 row_mask:0xf bank_mask:0xf bound_ctrl:1
	ds_read_b128 v[36:39], v6 offset:28672
	s_waitcnt lgkmcnt(11)
	v_pk_mul_f32 v[114:115], v[2:3], v[84:85]
	v_add_f32_dpp v12, v12, v12 row_ror:2 row_mask:0xf bank_mask:0xf bound_ctrl:1
	v_add_f32_dpp v10, v10, v10 row_ror:1 row_mask:0xf bank_mask:0xf bound_ctrl:1
	ds_read_b128 v[40:43], v6 offset:28928
	v_pk_mul_f32 v[116:117], v[4:5], v[86:87]
	v_add_f32_dpp v12, v12, v12 row_ror:1 row_mask:0xf bank_mask:0xf bound_ctrl:1
	v_add_f32_e32 v14, v14, v15
	ds_read2_b32 v[64:65], v120 offset0:128 offset1:144
	v_pk_fma_f32 v[114:115], v[88:89], v[112:113], v[114:115] op_sel_hi:[1,0,1]
	v_add_f32_e32 v16, v16, v17
	v_pk_fma_f32 v[116:117], v[90:91], v[112:113], v[116:117] op_sel_hi:[1,0,1]
	ds_read_b128 v[48:51], v6 offset:29440
	v_fmac_f32_e32 v12, v112, v105
	v_fmac_f32_e32 v14, v112, v107
	s_waitcnt lgkmcnt(10)
	v_pk_fma_f32 v[114:115], v[96:97], v[112:113], v[114:115] op_sel:[0,1,0] op_sel_hi:[1,1,1]
	ds_read_b128 v[44:47], v6 offset:29184
	v_fmac_f32_e32 v16, v112, v109
	v_pk_fma_f32 v[116:117], v[98:99], v[112:113], v[116:117] op_sel:[0,1,0] op_sel_hi:[1,1,1]
	v_fma_f32 v14, -v10, v106, v14
	ds_read_b128 v[52:55], v6 offset:29696
	v_fmac_f32_e32 v16, v113, v111
	v_pk_fma_f32 v[114:115], v[92:93], v[10:11], v[114:115] op_sel_hi:[1,0,1] neg_lo:[1,0,0] neg_hi:[1,0,0]
	v_fma_f32 v16, -v10, v108, v16
	ds_read_b128 v[60:63], v7 offset:37456
	v_pk_fma_f32 v[116:117], v[94:95], v[10:11], v[116:117] op_sel_hi:[1,0,1] neg_lo:[1,0,0] neg_hi:[1,0,0]
	v_add_f32_dpp v14, v14, v14 row_ror:8 row_mask:0xf bank_mask:0xf bound_ctrl:1
	v_fma_f32 v16, -v12, v110, v16
	v_pk_fma_f32 v[2:3], v[100:101], v[12:13], v[114:115] op_sel_hi:[1,0,1] neg_lo:[1,0,0] neg_hi:[1,0,0]
	v_add_f32_dpp v14, v14, v14 row_ror:4 row_mask:0xf bank_mask:0xf bound_ctrl:1
	v_pk_fma_f32 v[4:5], v[102:103], v[12:13], v[116:117] op_sel_hi:[1,0,1] neg_lo:[1,0,0] neg_hi:[1,0,0]
	v_add_f32_dpp v16, v16, v16 row_ror:8 row_mask:0xf bank_mask:0xf bound_ctrl:1
	v_add_f32_dpp v14, v14, v14 row_ror:2 row_mask:0xf bank_mask:0xf bound_ctrl:1
	s_nop 0
	v_add_f32_dpp v16, v16, v16 row_ror:4 row_mask:0xf bank_mask:0xf bound_ctrl:1
	v_add_f32_dpp v14, v14, v14 row_ror:1 row_mask:0xf bank_mask:0xf bound_ctrl:1
	s_nop 0
	v_add_f32_dpp v16, v16, v16 row_ror:2 row_mask:0xf bank_mask:0xf bound_ctrl:1
	s_nop 1
	v_add_f32_dpp v16, v16, v16 row_ror:1 row_mask:0xf bank_mask:0xf bound_ctrl:1
	ds_write2_b32 v119, v14, v16 offset0:96 offset1:112
	s_waitcnt lgkmcnt(8)
	v_pk_mul_f32 v[10:11], v[4:5], v[22:23]
	ds_read_b128 v[68:71], v6 offset:29952
	v_pk_mul_f32 v[12:13], v[4:5], v[30:31]
	v_pk_fma_f32 v[10:11], v[2:3], v[20:21], v[10:11]
	v_pk_fma_f32 v[12:13], v[2:3], v[28:29], v[12:13]
	ds_read_b128 v[76:79], v6 offset:30464
	v_pk_mul_f32 v[14:15], v[4:5], v[26:27]
	v_add_f32_e32 v10, v10, v11
	v_add_f32_e32 v12, v12, v13
	ds_read_b128 v[72:75], v6 offset:30208
	v_pk_mul_f32 v[16:17], v[4:5], v[34:35]
	v_fma_f32 v12, -v56, v10, v12
	v_add_f32_dpp v10, v10, v10 row_ror:8 row_mask:0xf bank_mask:0xf bound_ctrl:1
	ds_read_b128 v[80:83], v6 offset:30720
	v_pk_fma_f32 v[14:15], v[2:3], v[24:25], v[14:15]
	v_add_f32_dpp v12, v12, v12 row_ror:8 row_mask:0xf bank_mask:0xf bound_ctrl:1
	v_add_f32_dpp v10, v10, v10 row_ror:4 row_mask:0xf bank_mask:0xf bound_ctrl:1
	ds_read_b128 v[104:107], v7 offset:37488
	v_pk_fma_f32 v[16:17], v[2:3], v[32:33], v[16:17]
	v_add_f32_dpp v12, v12, v12 row_ror:4 row_mask:0xf bank_mask:0xf bound_ctrl:1
	v_add_f32_dpp v10, v10, v10 row_ror:2 row_mask:0xf bank_mask:0xf bound_ctrl:1
	ds_read_b128 v[84:87], v6 offset:30976
	s_waitcnt lgkmcnt(11)
	v_pk_mul_f32 v[114:115], v[2:3], v[36:37]
	v_add_f32_dpp v12, v12, v12 row_ror:2 row_mask:0xf bank_mask:0xf bound_ctrl:1
	v_add_f32_dpp v10, v10, v10 row_ror:1 row_mask:0xf bank_mask:0xf bound_ctrl:1
	ds_read_b128 v[88:91], v6 offset:31232
	v_pk_mul_f32 v[116:117], v[4:5], v[38:39]
	v_add_f32_dpp v12, v12, v12 row_ror:1 row_mask:0xf bank_mask:0xf bound_ctrl:1
	v_add_f32_e32 v14, v14, v15
	ds_read2_b32 v[112:113], v120 offset0:160 offset1:176
	v_pk_fma_f32 v[114:115], v[40:41], v[64:65], v[114:115] op_sel_hi:[1,0,1]
	v_add_f32_e32 v16, v16, v17
	v_pk_fma_f32 v[116:117], v[42:43], v[64:65], v[116:117] op_sel_hi:[1,0,1]
	ds_read_b128 v[96:99], v6 offset:31744
	v_fmac_f32_e32 v12, v64, v57
	v_fmac_f32_e32 v14, v64, v59
	s_waitcnt lgkmcnt(10)
	v_pk_fma_f32 v[114:115], v[48:49], v[64:65], v[114:115] op_sel:[0,1,0] op_sel_hi:[1,1,1]
	ds_read_b128 v[92:95], v6 offset:31488
	v_fmac_f32_e32 v16, v64, v61
	v_pk_fma_f32 v[116:117], v[50:51], v[64:65], v[116:117] op_sel:[0,1,0] op_sel_hi:[1,1,1]
	v_fma_f32 v14, -v10, v58, v14
	ds_read_b128 v[100:103], v6 offset:32000
	v_fmac_f32_e32 v16, v65, v63
	v_pk_fma_f32 v[114:115], v[44:45], v[10:11], v[114:115] op_sel_hi:[1,0,1] neg_lo:[1,0,0] neg_hi:[1,0,0]
	v_fma_f32 v16, -v10, v60, v16
	ds_read_b128 v[108:111], v7 offset:37504
	v_pk_fma_f32 v[116:117], v[46:47], v[10:11], v[116:117] op_sel_hi:[1,0,1] neg_lo:[1,0,0] neg_hi:[1,0,0]
	v_add_f32_dpp v14, v14, v14 row_ror:8 row_mask:0xf bank_mask:0xf bound_ctrl:1
	v_fma_f32 v16, -v12, v62, v16
	v_pk_fma_f32 v[2:3], v[52:53], v[12:13], v[114:115] op_sel_hi:[1,0,1] neg_lo:[1,0,0] neg_hi:[1,0,0]
	v_add_f32_dpp v14, v14, v14 row_ror:4 row_mask:0xf bank_mask:0xf bound_ctrl:1
	v_pk_fma_f32 v[4:5], v[54:55], v[12:13], v[116:117] op_sel_hi:[1,0,1] neg_lo:[1,0,0] neg_hi:[1,0,0]
	v_add_f32_dpp v16, v16, v16 row_ror:8 row_mask:0xf bank_mask:0xf bound_ctrl:1
	v_add_f32_dpp v14, v14, v14 row_ror:2 row_mask:0xf bank_mask:0xf bound_ctrl:1
	s_nop 0
	v_add_f32_dpp v16, v16, v16 row_ror:4 row_mask:0xf bank_mask:0xf bound_ctrl:1
	v_add_f32_dpp v14, v14, v14 row_ror:1 row_mask:0xf bank_mask:0xf bound_ctrl:1
	s_nop 0
	v_add_f32_dpp v16, v16, v16 row_ror:2 row_mask:0xf bank_mask:0xf bound_ctrl:1
	s_nop 1
	v_add_f32_dpp v16, v16, v16 row_ror:1 row_mask:0xf bank_mask:0xf bound_ctrl:1
	ds_write2_b32 v119, v14, v16 offset0:128 offset1:144
	s_waitcnt lgkmcnt(8)
	v_pk_mul_f32 v[10:11], v[4:5], v[70:71]
	ds_read_b128 v[20:23], v6 offset:32256
	v_pk_mul_f32 v[12:13], v[4:5], v[78:79]
	v_pk_fma_f32 v[10:11], v[2:3], v[68:69], v[10:11]
	v_pk_fma_f32 v[12:13], v[2:3], v[76:77], v[12:13]
	ds_read_b128 v[28:31], v6 offset:32768
	v_pk_mul_f32 v[14:15], v[4:5], v[74:75]
	v_add_f32_e32 v10, v10, v11
	v_add_f32_e32 v12, v12, v13
	ds_read_b128 v[24:27], v6 offset:32512
	v_pk_mul_f32 v[16:17], v[4:5], v[82:83]
	v_fma_f32 v12, -v104, v10, v12
	v_add_f32_dpp v10, v10, v10 row_ror:8 row_mask:0xf bank_mask:0xf bound_ctrl:1
	ds_read_b128 v[32:35], v6 offset:33024
	v_pk_fma_f32 v[14:15], v[2:3], v[72:73], v[14:15]
	v_add_f32_dpp v12, v12, v12 row_ror:8 row_mask:0xf bank_mask:0xf bound_ctrl:1
	v_add_f32_dpp v10, v10, v10 row_ror:4 row_mask:0xf bank_mask:0xf bound_ctrl:1
	ds_read_b128 v[56:59], v7 offset:37536
	v_pk_fma_f32 v[16:17], v[2:3], v[80:81], v[16:17]
	v_add_f32_dpp v12, v12, v12 row_ror:4 row_mask:0xf bank_mask:0xf bound_ctrl:1
	v_add_f32_dpp v10, v10, v10 row_ror:2 row_mask:0xf bank_mask:0xf bound_ctrl:1
	ds_read_b128 v[36:39], v6 offset:33280
	s_waitcnt lgkmcnt(11)
	v_pk_mul_f32 v[114:115], v[2:3], v[84:85]
	v_add_f32_dpp v12, v12, v12 row_ror:2 row_mask:0xf bank_mask:0xf bound_ctrl:1
	v_add_f32_dpp v10, v10, v10 row_ror:1 row_mask:0xf bank_mask:0xf bound_ctrl:1
	ds_read_b128 v[40:43], v6 offset:33536
	v_pk_mul_f32 v[116:117], v[4:5], v[86:87]
	v_add_f32_dpp v12, v12, v12 row_ror:1 row_mask:0xf bank_mask:0xf bound_ctrl:1
	v_add_f32_e32 v14, v14, v15
	ds_read2_b32 v[64:65], v120 offset0:192 offset1:208
	v_pk_fma_f32 v[114:115], v[88:89], v[112:113], v[114:115] op_sel_hi:[1,0,1]
	v_add_f32_e32 v16, v16, v17
	v_pk_fma_f32 v[116:117], v[90:91], v[112:113], v[116:117] op_sel_hi:[1,0,1]
	ds_read_b128 v[48:51], v6 offset:34048
	v_fmac_f32_e32 v12, v112, v105
	v_fmac_f32_e32 v14, v112, v107
	s_waitcnt lgkmcnt(10)
	v_pk_fma_f32 v[114:115], v[96:97], v[112:113], v[114:115] op_sel:[0,1,0] op_sel_hi:[1,1,1]
	ds_read_b128 v[44:47], v6 offset:33792
	v_fmac_f32_e32 v16, v112, v109
	v_pk_fma_f32 v[116:117], v[98:99], v[112:113], v[116:117] op_sel:[0,1,0] op_sel_hi:[1,1,1]
	v_fma_f32 v14, -v10, v106, v14
	ds_read_b128 v[52:55], v6 offset:34304
	v_fmac_f32_e32 v16, v113, v111
	v_pk_fma_f32 v[114:115], v[92:93], v[10:11], v[114:115] op_sel_hi:[1,0,1] neg_lo:[1,0,0] neg_hi:[1,0,0]
	v_fma_f32 v16, -v10, v108, v16
	ds_read_b128 v[60:63], v7 offset:37552
	v_pk_fma_f32 v[116:117], v[94:95], v[10:11], v[116:117] op_sel_hi:[1,0,1] neg_lo:[1,0,0] neg_hi:[1,0,0]
	v_add_f32_dpp v14, v14, v14 row_ror:8 row_mask:0xf bank_mask:0xf bound_ctrl:1
	v_fma_f32 v16, -v12, v110, v16
	v_pk_fma_f32 v[2:3], v[100:101], v[12:13], v[114:115] op_sel_hi:[1,0,1] neg_lo:[1,0,0] neg_hi:[1,0,0]
	v_add_f32_dpp v14, v14, v14 row_ror:4 row_mask:0xf bank_mask:0xf bound_ctrl:1
	v_pk_fma_f32 v[4:5], v[102:103], v[12:13], v[116:117] op_sel_hi:[1,0,1] neg_lo:[1,0,0] neg_hi:[1,0,0]
	v_add_f32_dpp v16, v16, v16 row_ror:8 row_mask:0xf bank_mask:0xf bound_ctrl:1
	v_add_f32_dpp v14, v14, v14 row_ror:2 row_mask:0xf bank_mask:0xf bound_ctrl:1
	s_nop 0
	v_add_f32_dpp v16, v16, v16 row_ror:4 row_mask:0xf bank_mask:0xf bound_ctrl:1
	v_add_f32_dpp v14, v14, v14 row_ror:1 row_mask:0xf bank_mask:0xf bound_ctrl:1
	s_nop 0
	v_add_f32_dpp v16, v16, v16 row_ror:2 row_mask:0xf bank_mask:0xf bound_ctrl:1
	s_nop 1
	v_add_f32_dpp v16, v16, v16 row_ror:1 row_mask:0xf bank_mask:0xf bound_ctrl:1
	ds_write2_b32 v119, v14, v16 offset0:160 offset1:176
	s_waitcnt lgkmcnt(8)
	v_pk_mul_f32 v[10:11], v[4:5], v[22:23]
	ds_read_b128 v[68:71], v6 offset:34560
	v_pk_mul_f32 v[12:13], v[4:5], v[30:31]
	v_pk_fma_f32 v[10:11], v[2:3], v[20:21], v[10:11]
	v_pk_fma_f32 v[12:13], v[2:3], v[28:29], v[12:13]
	ds_read_b128 v[76:79], v6 offset:35072
	v_pk_mul_f32 v[14:15], v[4:5], v[26:27]
	v_add_f32_e32 v10, v10, v11
	v_add_f32_e32 v12, v12, v13
	ds_read_b128 v[72:75], v6 offset:34816
	v_pk_mul_f32 v[16:17], v[4:5], v[34:35]
	v_fma_f32 v12, -v56, v10, v12
	v_add_f32_dpp v10, v10, v10 row_ror:8 row_mask:0xf bank_mask:0xf bound_ctrl:1
	ds_read_b128 v[80:83], v6 offset:35328
	v_pk_fma_f32 v[14:15], v[2:3], v[24:25], v[14:15]
	v_add_f32_dpp v12, v12, v12 row_ror:8 row_mask:0xf bank_mask:0xf bound_ctrl:1
	v_add_f32_dpp v10, v10, v10 row_ror:4 row_mask:0xf bank_mask:0xf bound_ctrl:1
	ds_read_b128 v[104:107], v7 offset:37584
	v_pk_fma_f32 v[16:17], v[2:3], v[32:33], v[16:17]
	v_add_f32_dpp v12, v12, v12 row_ror:4 row_mask:0xf bank_mask:0xf bound_ctrl:1
	v_add_f32_dpp v10, v10, v10 row_ror:2 row_mask:0xf bank_mask:0xf bound_ctrl:1
	ds_read_b128 v[84:87], v6 offset:35584
	s_waitcnt lgkmcnt(11)
	v_pk_mul_f32 v[114:115], v[2:3], v[36:37]
	v_add_f32_dpp v12, v12, v12 row_ror:2 row_mask:0xf bank_mask:0xf bound_ctrl:1
	v_add_f32_dpp v10, v10, v10 row_ror:1 row_mask:0xf bank_mask:0xf bound_ctrl:1
	ds_read_b128 v[88:91], v6 offset:35840
	v_pk_mul_f32 v[116:117], v[4:5], v[38:39]
	v_add_f32_dpp v12, v12, v12 row_ror:1 row_mask:0xf bank_mask:0xf bound_ctrl:1
	v_add_f32_e32 v14, v14, v15
	ds_read2_b32 v[112:113], v120 offset0:224 offset1:240
	v_pk_fma_f32 v[114:115], v[40:41], v[64:65], v[114:115] op_sel_hi:[1,0,1]
	v_add_f32_e32 v16, v16, v17
	v_pk_fma_f32 v[116:117], v[42:43], v[64:65], v[116:117] op_sel_hi:[1,0,1]
	ds_read_b128 v[96:99], v6 offset:36352
	v_fmac_f32_e32 v12, v64, v57
	v_fmac_f32_e32 v14, v64, v59
	s_waitcnt lgkmcnt(10)
	v_pk_fma_f32 v[114:115], v[48:49], v[64:65], v[114:115] op_sel:[0,1,0] op_sel_hi:[1,1,1]
	ds_read_b128 v[92:95], v6 offset:36096
	v_fmac_f32_e32 v16, v64, v61
	v_pk_fma_f32 v[116:117], v[50:51], v[64:65], v[116:117] op_sel:[0,1,0] op_sel_hi:[1,1,1]
	v_fma_f32 v14, -v10, v58, v14
	ds_read_b128 v[100:103], v6 offset:36608
	v_fmac_f32_e32 v16, v65, v63
	v_pk_fma_f32 v[114:115], v[44:45], v[10:11], v[114:115] op_sel_hi:[1,0,1] neg_lo:[1,0,0] neg_hi:[1,0,0]
	v_fma_f32 v16, -v10, v60, v16
	ds_read_b128 v[108:111], v7 offset:37600
	v_pk_fma_f32 v[116:117], v[46:47], v[10:11], v[116:117] op_sel_hi:[1,0,1] neg_lo:[1,0,0] neg_hi:[1,0,0]
	v_add_f32_dpp v14, v14, v14 row_ror:8 row_mask:0xf bank_mask:0xf bound_ctrl:1
	v_fma_f32 v16, -v12, v62, v16
	v_pk_fma_f32 v[2:3], v[52:53], v[12:13], v[114:115] op_sel_hi:[1,0,1] neg_lo:[1,0,0] neg_hi:[1,0,0]
	v_add_f32_dpp v14, v14, v14 row_ror:4 row_mask:0xf bank_mask:0xf bound_ctrl:1
	v_pk_fma_f32 v[4:5], v[54:55], v[12:13], v[116:117] op_sel_hi:[1,0,1] neg_lo:[1,0,0] neg_hi:[1,0,0]
	v_add_f32_dpp v16, v16, v16 row_ror:8 row_mask:0xf bank_mask:0xf bound_ctrl:1
	v_add_f32_dpp v14, v14, v14 row_ror:2 row_mask:0xf bank_mask:0xf bound_ctrl:1
	s_nop 0
	v_add_f32_dpp v16, v16, v16 row_ror:4 row_mask:0xf bank_mask:0xf bound_ctrl:1
	v_add_f32_dpp v14, v14, v14 row_ror:1 row_mask:0xf bank_mask:0xf bound_ctrl:1
	s_nop 0
	v_add_f32_dpp v16, v16, v16 row_ror:2 row_mask:0xf bank_mask:0xf bound_ctrl:1
	s_nop 1
	v_add_f32_dpp v16, v16, v16 row_ror:1 row_mask:0xf bank_mask:0xf bound_ctrl:1
	ds_write2_b32 v119, v14, v16 offset0:192 offset1:208
	s_waitcnt lgkmcnt(8)
	v_pk_mul_f32 v[10:11], v[4:5], v[70:71]
	v_pk_mul_f32 v[12:13], v[4:5], v[78:79]
	v_pk_fma_f32 v[10:11], v[2:3], v[68:69], v[10:11]
	v_pk_fma_f32 v[12:13], v[2:3], v[76:77], v[12:13]
	v_pk_mul_f32 v[14:15], v[4:5], v[74:75]
	v_add_f32_e32 v10, v10, v11
	v_add_f32_e32 v12, v12, v13
	v_pk_mul_f32 v[16:17], v[4:5], v[82:83]
	v_fma_f32 v12, -v104, v10, v12
	v_add_f32_dpp v10, v10, v10 row_ror:8 row_mask:0xf bank_mask:0xf bound_ctrl:1
	v_pk_fma_f32 v[14:15], v[2:3], v[72:73], v[14:15]
	v_add_f32_dpp v12, v12, v12 row_ror:8 row_mask:0xf bank_mask:0xf bound_ctrl:1
	v_add_f32_dpp v10, v10, v10 row_ror:4 row_mask:0xf bank_mask:0xf bound_ctrl:1
	v_pk_fma_f32 v[16:17], v[2:3], v[80:81], v[16:17]
	v_add_f32_dpp v12, v12, v12 row_ror:4 row_mask:0xf bank_mask:0xf bound_ctrl:1
	v_add_f32_dpp v10, v10, v10 row_ror:2 row_mask:0xf bank_mask:0xf bound_ctrl:1
	s_waitcnt lgkmcnt(5)
	v_pk_mul_f32 v[114:115], v[2:3], v[84:85]
	v_add_f32_dpp v12, v12, v12 row_ror:2 row_mask:0xf bank_mask:0xf bound_ctrl:1
	v_add_f32_dpp v10, v10, v10 row_ror:1 row_mask:0xf bank_mask:0xf bound_ctrl:1
	v_pk_mul_f32 v[116:117], v[4:5], v[86:87]
	v_add_f32_dpp v12, v12, v12 row_ror:1 row_mask:0xf bank_mask:0xf bound_ctrl:1
	v_add_f32_e32 v14, v14, v15
	v_pk_fma_f32 v[114:115], v[88:89], v[112:113], v[114:115] op_sel_hi:[1,0,1]
	v_add_f32_e32 v16, v16, v17
	v_pk_fma_f32 v[116:117], v[90:91], v[112:113], v[116:117] op_sel_hi:[1,0,1]
	v_fmac_f32_e32 v12, v112, v105
	v_fmac_f32_e32 v14, v112, v107
	s_waitcnt lgkmcnt(1)
	v_pk_fma_f32 v[114:115], v[96:97], v[112:113], v[114:115] op_sel:[0,1,0] op_sel_hi:[1,1,1]
	v_fmac_f32_e32 v16, v112, v109
	v_pk_fma_f32 v[116:117], v[98:99], v[112:113], v[116:117] op_sel:[0,1,0] op_sel_hi:[1,1,1]
	v_fma_f32 v14, -v10, v106, v14
	v_fmac_f32_e32 v16, v113, v111
	v_pk_fma_f32 v[114:115], v[92:93], v[10:11], v[114:115] op_sel_hi:[1,0,1] neg_lo:[1,0,0] neg_hi:[1,0,0]
	v_fma_f32 v16, -v10, v108, v16
	v_pk_fma_f32 v[116:117], v[94:95], v[10:11], v[116:117] op_sel_hi:[1,0,1] neg_lo:[1,0,0] neg_hi:[1,0,0]
	v_add_f32_dpp v14, v14, v14 row_ror:8 row_mask:0xf bank_mask:0xf bound_ctrl:1
	v_fma_f32 v16, -v12, v110, v16
	v_pk_fma_f32 v[2:3], v[100:101], v[12:13], v[114:115] op_sel_hi:[1,0,1] neg_lo:[1,0,0] neg_hi:[1,0,0]
	v_add_f32_dpp v14, v14, v14 row_ror:4 row_mask:0xf bank_mask:0xf bound_ctrl:1
	v_pk_fma_f32 v[4:5], v[102:103], v[12:13], v[116:117] op_sel_hi:[1,0,1] neg_lo:[1,0,0] neg_hi:[1,0,0]
	v_add_f32_dpp v16, v16, v16 row_ror:8 row_mask:0xf bank_mask:0xf bound_ctrl:1
	v_add_f32_dpp v14, v14, v14 row_ror:2 row_mask:0xf bank_mask:0xf bound_ctrl:1
	s_nop 0
	v_add_f32_dpp v16, v16, v16 row_ror:4 row_mask:0xf bank_mask:0xf bound_ctrl:1
	v_add_f32_dpp v14, v14, v14 row_ror:1 row_mask:0xf bank_mask:0xf bound_ctrl:1
	s_nop 0
	v_add_f32_dpp v16, v16, v16 row_ror:2 row_mask:0xf bank_mask:0xf bound_ctrl:1
	s_nop 1
	v_add_f32_dpp v16, v16, v16 row_ror:1 row_mask:0xf bank_mask:0xf bound_ctrl:1
	ds_write2_b32 v119, v14, v16 offset0:224 offset1:240
	v_add_u32_e32 v6, s1, v6
	v_add_u32_e32 v7, s1, v7
	v_add_u32_e32 v8, s1, v8
	v_add_u32_e32 v9, s1, v9
	v_add_u32_e32 v119, s1, v119
	v_add_u32_e32 v120, s1, v120
	s_sub_i32 s1, 0, s1
	s_add_i32 s0, s0, 1
	s_cmpk_eq_i32 s0, 0x200
	s_waitcnt lgkmcnt(0)
	s_barrier
	s_cbranch_scc0 .LBB0_652
	s_mov_b64 s[0:1], 0

.LBB0_663:
	s_or_b64 exec, exec, s[20:21]
	s_add_u32 s20, s78, 0xf000000
	s_addc_u32 s21, s79, 0
	s_add_u32 s7, s20, s6
	s_addc_u32 s9, s21, 0
	s_add_u32 s22, s7, s8
	s_addc_u32 s23, s9, 0
	v_mov_b32_e32 v3, 0
	s_waitcnt vmcnt(11)
	v_cvt_f32_f16_sdwa v35, v61 dst_sel:DWORD dst_unused:UNUSED_PAD src0_sel:WORD_1
	v_cvt_f32_f16_e32 v34, v61
	v_lshl_add_u64 v[32:33], s[22:23], 0, v[2:3]
	s_mov_b64 s[22:23], 0x20000
	v_lshl_add_u64 v[38:39], v[28:29], 0, s[22:23]
	v_or_b32_e32 v28, v38, v55
	v_mov_b32_e32 v29, v39
	v_or_b32_e32 v38, v38, v54
	v_lshlrev_b64 v[30:31], 12, v[30:31]
	ds_write_b64 v1, v[34:35] offset:37632
	v_lshlrev_b64 v[34:35], 1, v[28:29]
	v_lshlrev_b64 v[44:45], 1, v[38:39]
	s_mov_b32 s7, 0x40000
	v_lshl_add_u64 v[52:53], v[32:33], 0, v[30:31]
	v_lshl_add_u64 v[28:29], s[70:71], 0, v[34:35]
	v_lshl_add_u64 v[30:31], s[12:13], 0, v[34:35]
	v_lshl_add_u64 v[32:33], s[14:15], 0, v[34:35]
	v_lshl_add_u64 v[36:37], s[16:17], 0, v[34:35]
	v_lshl_add_u64 v[40:41], s[18:19], 0, v[34:35]
	v_lshl_add_u64 v[38:39], s[70:71], 0, v[44:45]
	v_lshl_add_u64 v[42:43], s[12:13], 0, v[44:45]
	v_lshl_add_u64 v[46:47], s[14:15], 0, v[44:45]
	v_add_co_u32_e32 v48, vcc, s7, v56
	global_load_dwordx2 v[28:29], v[28:29], off
	s_nop 0
	global_load_dwordx2 v[30:31], v[30:31], off
	s_nop 0
	global_load_dwordx2 v[32:33], v[32:33], off
	s_nop 0
	global_load_dwordx2 v[34:35], v[36:37], off
	s_nop 0
	global_load_dwordx2 v[36:37], v[40:41], off
	s_nop 0
	global_load_dwordx2 v[40:41], v[38:39], off
	s_nop 0
	global_load_dwordx2 v[38:39], v[42:43], off
	s_nop 0
	global_load_dwordx2 v[42:43], v[46:47], off
	v_lshl_add_u64 v[46:47], s[16:17], 0, v[44:45]
	v_lshl_add_u64 v[44:45], s[18:19], 0, v[44:45]
	v_addc_co_u32_e32 v49, vcc, 0, v57, vcc
	global_load_dwordx2 v[46:47], v[46:47], off
	s_nop 0
	global_load_dwordx2 v[44:45], v[44:45], off
	v_or_b32_e32 v3, v60, v58
	global_load_dword v81, v[48:49], off
	v_lshlrev_b32_e32 v3, 6, v3
	v_add_u32_e32 v3, 0, v3
	v_lshrrev_b32_e32 v90, 4, v3
	v_add_u32_e32 v90, 0x9b00, v90
	ds_read2_b32 v[48:49], v90 offset0:1
	s_movk_i32 s7, 0x7fff
	v_mov_b32_e32 v82, 1
	s_mov_b32 s9, 0xffff0000
	s_lshl_b32 s10, s2, 20
	s_and_b32 s10, s10, 0x4000000
	s_waitcnt lgkmcnt(0)
	v_and_b32_sdwa v50, v49, v82 dst_sel:DWORD dst_unused:UNUSED_PAD src0_sel:WORD_1 src1_sel:DWORD
	v_and_b32_sdwa v51, v48, v82 dst_sel:DWORD dst_unused:UNUSED_PAD src0_sel:WORD_1 src1_sel:DWORD
	v_add3_u32 v49, v49, v50, s7
	v_add3_u32 v48, v48, v51, s7
	v_lshrrev_b32_e32 v49, 16, v49
	v_and_or_b32 v48, v48, s9, v49
	global_store_dword v[52:53], v48, off
	v_lshlrev_b64 v[48:49], 12, v[4:5]
	v_lshl_add_u64 v[48:49], s[10:11], 0, v[48:49]
	s_lshl_b32 s10, s25, 5
	v_and_b32_e32 v50, 7, v153
	s_and_b32 s14, s10, 0x780
	v_lshlrev_b32_e32 v52, 2, v50
	v_lshlrev_b64 v[50:51], 11, v[4:5]
	v_or_b32_e32 v48, s14, v48
	s_and_b32 s15, s24, 0x60
	v_or_b32_e32 v50, s14, v50
	v_or3_b32 v48, v48, s15, v52
	v_or3_b32 v50, v50, s15, v52
	v_lshlrev_b64 v[52:53], 11, v[26:27]
	v_lshl_add_u64 v[48:49], s[78:79], 0, v[48:49]
	s_mov_b64 s[12:13], 0xf040000
	s_lshl_b32 s10, s2, 19
	v_lshl_or_b32 v52, v55, 1, v52
	v_lshl_add_u64 v[48:49], v[48:49], 0, s[12:13]
	s_and_b32 s10, s10, 0x2000000
	v_lshl_add_u64 v[50:51], s[70:71], 0, v[50:51]
	v_lshl_add_u64 v[26:27], s[70:71], 0, v[52:53]
	v_lshl_add_u64 v[52:53], s[78:79], 0, v[52:53]
	s_mov_b32 s12, 0x3d800000
	s_mov_b64 s[14:15], 0x40000
	s_mov_b32 s13, s11
	s_barrier
	s_branch .LBB0_665
.LBB0_664:
	v_lshrrev_b32_e32 v74, 4, v3
	v_add_u32_e32 v74, 0x9b00, v74
	ds_read2_b32 v[54:55], v74 offset0:1
	v_lshl_add_u64 v[50:51], v[50:51], 0, s[22:23]
	v_lshl_add_u64 v[26:27], v[26:27], 0, s[22:23]
	v_lshl_add_u64 v[52:53], v[52:53], 0, s[22:23]
	s_and_b64 vcc, exec, s[16:17]
	s_nop 0
	s_waitcnt lgkmcnt(0)
	v_and_b32_sdwa v56, v55, v82 dst_sel:DWORD dst_unused:UNUSED_PAD src0_sel:WORD_1 src1_sel:DWORD
	v_and_b32_sdwa v57, v54, v82 dst_sel:DWORD dst_unused:UNUSED_PAD src0_sel:WORD_1 src1_sel:DWORD
	v_add3_u32 v55, v55, v56, s7
	v_add3_u32 v54, v54, v57, s7
	v_lshrrev_b32_e32 v55, 16, v55
	v_and_or_b32 v54, v54, s9, v55
	global_store_dword v[48:49], v54, off
	v_lshl_add_u64 v[48:49], v[48:49], 0, s[14:15]
	s_barrier
	s_cbranch_vccnz .LBB0_675

.LBB0_669:
	v_lshrrev_b32_e32 v100, 4, v3
	v_add_u32_e32 v100, 0x1b600, v100
	ds_read2_b32 v[60:61], v100 offset0:1
	s_cmpk_gt_u32 s13, 0x1fd
	s_cselect_b64 s[16:17], -1, 0
	s_nop 0
	s_nop 0
	s_nop 0
	s_waitcnt lgkmcnt(0)
	v_and_b32_sdwa v62, v61, v82 dst_sel:DWORD dst_unused:UNUSED_PAD src0_sel:WORD_1 src1_sel:DWORD
	v_and_b32_sdwa v63, v60, v82 dst_sel:DWORD dst_unused:UNUSED_PAD src0_sel:WORD_1 src1_sel:DWORD
	v_add3_u32 v61, v61, v62, s7
	v_add3_u32 v60, v60, v63, s7
	v_lshrrev_b32_e32 v61, 16, v61
	v_and_or_b32 v62, v60, s9, v61
	v_add_co_u32_e32 v60, vcc, 0xfffe0000, v48
	s_nop 1
	v_addc_co_u32_e32 v61, vcc, -1, v49, vcc
	s_and_b64 vcc, exec, s[16:17]
	global_store_dword v[60:61], v62, off
	s_barrier
	s_cbranch_vccnz .LBB0_673
	s_waitcnt vmcnt(11)
	v_cvt_f32_f16_sdwa v65, v30 dst_sel:DWORD dst_unused:UNUSED_PAD src0_sel:WORD_1
	v_cvt_f32_f16_e32 v64, v30
	s_waitcnt vmcnt(6)
	v_cvt_f32_f16_sdwa v63, v38 dst_sel:DWORD dst_unused:UNUSED_PAD src0_sel:WORD_1
	v_cvt_f32_f16_e32 v62, v38
	v_cvt_f32_f16_sdwa v67, v31 dst_sel:DWORD dst_unused:UNUSED_PAD src0_sel:WORD_1
	v_pk_add_f32 v[84:85], v[64:65], 1.0 op_sel_hi:[1,0] neg_lo:[1,0] neg_hi:[1,0]
	v_cvt_f32_f16_sdwa v65, v39 dst_sel:DWORD dst_unused:UNUSED_PAD src0_sel:WORD_1
	v_cvt_f32_f16_e32 v64, v39
	v_cvt_f32_f16_e32 v66, v31
	v_cvt_f32_f16_sdwa v93, v40 dst_sel:DWORD dst_unused:UNUSED_PAD src0_sel:WORD_1
	v_cvt_f32_f16_e32 v92, v40
	s_waitcnt vmcnt(4)
	v_cvt_f32_f16_sdwa v95, v46 dst_sel:DWORD dst_unused:UNUSED_PAD src0_sel:WORD_1
	v_cvt_f32_f16_e32 v94, v46
	v_cvt_f32_f16_sdwa v103, v47 dst_sel:DWORD dst_unused:UNUSED_PAD src0_sel:WORD_1
	v_cvt_f32_f16_e32 v102, v47
	v_cvt_f32_f16_sdwa v105, v41 dst_sel:DWORD dst_unused:UNUSED_PAD src0_sel:WORD_1
	v_cvt_f32_f16_e32 v104, v41
	v_cvt_f32_f16_sdwa v61, v34 dst_sel:DWORD dst_unused:UNUSED_PAD src0_sel:WORD_1
	v_cvt_f32_f16_e32 v60, v34
	v_pk_add_f32 v[88:89], v[62:63], 1.0 op_sel_hi:[1,0] neg_lo:[1,0] neg_hi:[1,0]
	v_cvt_f32_f16_sdwa v91, v28 dst_sel:DWORD dst_unused:UNUSED_PAD src0_sel:WORD_1
	v_cvt_f32_f16_e32 v90, v28
	v_cvt_f32_f16_sdwa v63, v35 dst_sel:DWORD dst_unused:UNUSED_PAD src0_sel:WORD_1
	v_cvt_f32_f16_e32 v62, v35
	v_cvt_f32_f16_sdwa v101, v29 dst_sel:DWORD dst_unused:UNUSED_PAD src0_sel:WORD_1
	v_cvt_f32_f16_e32 v100, v29
	v_pk_add_f32 v[98:99], v[64:65], 1.0 op_sel_hi:[1,0] neg_lo:[1,0] neg_hi:[1,0]
	v_pk_add_f32 v[86:87], v[66:67], 1.0 op_sel_hi:[1,0] neg_lo:[1,0] neg_hi:[1,0]
	v_pk_mul_f32 v[96:97], v[88:89], v[92:93]
	v_pk_mul_f32 v[68:69], v[84:85], v[94:95]
	v_pk_mul_f32 v[70:71], v[86:87], v[102:103]
	v_pk_mul_f32 v[106:107], v[98:99], v[104:105]
	v_pk_mul_f32 v[64:65], v[84:85], v[90:91]
	v_pk_mul_f32 v[66:67], v[86:87], v[100:101]
	v_pk_mul_f32 v[72:73], v[84:85], v[96:97]
	v_pk_mul_f32 v[74:75], v[86:87], v[106:107]
	v_pk_mul_f32 v[84:85], v[84:85], v[88:89]
	v_pk_mul_f32 v[86:87], v[86:87], v[98:99]
	ds_write_b128 v80, v[60:63]
	ds_write_b128 v80, v[64:67] offset:256
	ds_write_b128 v80, v[68:71] offset:512
	ds_write_b128 v80, v[72:75] offset:768
	ds_write_b128 v80, v[84:87] offset:1024
	v_cvt_f32_f16_e32 v68, v36
	v_cvt_f32_f16_sdwa v70, v36 dst_sel:DWORD dst_unused:UNUSED_PAD src0_sel:WORD_1
	v_cvt_f32_f16_e32 v69, v32
	v_cvt_f32_f16_sdwa v71, v32 dst_sel:DWORD dst_unused:UNUSED_PAD src0_sel:WORD_1
	v_cvt_f32_f16_e32 v75, v33
	v_cvt_f32_f16_sdwa v85, v33 dst_sel:DWORD dst_unused:UNUSED_PAD src0_sel:WORD_1
	v_cvt_f32_f16_e32 v74, v37
	v_cvt_f32_f16_sdwa v84, v37 dst_sel:DWORD dst_unused:UNUSED_PAD src0_sel:WORD_1
	v_mov_b32_e32 v62, v68
	v_mov_b32_e32 v63, v70
	v_mov_b32_e32 v60, v69
	v_mov_b32_e32 v61, v71
	v_pk_mul_f32 v[64:65], v[88:89], v[62:63]
	v_mov_b32_e32 v62, v75
	v_mov_b32_e32 v63, v85
	v_pk_mul_f32 v[60:61], v[88:89], v[60:61]
	v_pk_mul_f32 v[62:63], v[98:99], v[62:63]
	v_mov_b32_e32 v66, v74
	v_mov_b32_e32 v67, v84
	v_mov_b32_e32 v72, v95
	v_pk_mul_f32 v[66:67], v[98:99], v[66:67]
	ds_write_b128 v80, v[60:63] offset:1280
	ds_write_b128 v80, v[64:67] offset:1536
	v_pk_fma_f32 v[60:61], v[94:95], v[68:69], 0 op_sel_hi:[0,1,0]
	v_pk_fma_f32 v[60:61], v[72:73], v[70:71], v[60:61] op_sel_hi:[0,1,1]
	v_mov_b32_e32 v64, v91
	v_pk_fma_f32 v[72:73], v[90:91], v[68:69], 0 op_sel_hi:[0,1,0]
	v_pk_fma_f32 v[68:69], v[96:97], v[68:69], 0 op_sel_hi:[0,1,0]
	v_pk_fma_f32 v[64:65], v[64:65], v[70:71], v[72:73] op_sel_hi:[0,1,1]
	v_pk_fma_f32 v[68:69], v[96:97], v[70:71], v[68:69] op_sel:[1,0,0]
	v_mov_b32_e32 v86, v103
	v_pk_fma_f32 v[60:61], v[102:103], v[74:75], v[60:61] op_sel_hi:[0,1,1]
	v_mov_b32_e32 v66, v101
	v_pk_fma_f32 v[64:65], v[100:101], v[74:75], v[64:65] op_sel_hi:[0,1,1]
	v_pk_fma_f32 v[68:69], v[106:107], v[74:75], v[68:69] op_sel_hi:[0,1,1]
	v_pk_fma_f32 v[60:61], v[86:87], v[84:85], v[60:61] op_sel_hi:[0,1,1]
	v_pk_fma_f32 v[64:65], v[66:67], v[84:85], v[64:65] op_sel_hi:[0,1,1]
	v_pk_fma_f32 v[68:69], v[106:107], v[84:85], v[68:69] op_sel:[1,0,0]
	v_cvt_f32_f16_e32 v85, v42
	v_cvt_f32_f16_sdwa v87, v42 dst_sel:DWORD dst_unused:UNUSED_PAD src0_sel:WORD_1
	v_cvt_f32_f16_e32 v91, v43
	v_cvt_f32_f16_sdwa v95, v43 dst_sel:DWORD dst_unused:UNUSED_PAD src0_sel:WORD_1
	s_waitcnt vmcnt(3)
	v_cvt_f32_f16_e32 v84, v44
	v_cvt_f32_f16_sdwa v86, v44 dst_sel:DWORD dst_unused:UNUSED_PAD src0_sel:WORD_1
	v_cvt_f32_f16_e32 v90, v45
	v_cvt_f32_f16_sdwa v94, v45 dst_sel:DWORD dst_unused:UNUSED_PAD src0_sel:WORD_1
	v_mov_b32_e32 v72, v85
	v_mov_b32_e32 v73, v87
	v_mov_b32_e32 v74, v91
	v_mov_b32_e32 v75, v95
	ds_write_b128 v80, v[72:75] offset:1792
	v_mov_b32_e32 v72, v84
	v_mov_b32_e32 v73, v86
	v_mov_b32_e32 v74, v90
	v_mov_b32_e32 v75, v94
	v_mov_b32_e32 v88, v93
	ds_write_b128 v80, v[72:75] offset:2048
	v_pk_fma_f32 v[72:73], v[92:93], v[84:85], 0 op_sel_hi:[0,1,0]
	v_pk_fma_f32 v[72:73], v[88:89], v[86:87], v[72:73] op_sel_hi:[0,1,1]
	v_mov_b32_e32 v96, v105
	v_pk_fma_f32 v[72:73], v[104:105], v[90:91], v[72:73] op_sel_hi:[0,1,1]
	v_pk_fma_f32 v[72:73], v[96:97], v[94:95], v[72:73] op_sel_hi:[0,1,1]
	v_mov_b32_dpp v62, v60 row_ror:8 row_mask:0xf bank_mask:0xf bound_ctrl:1
	v_mov_b32_dpp v63, v61 row_ror:8 row_mask:0xf bank_mask:0xf bound_ctrl:1
	v_mov_b32_dpp v66, v64 row_ror:8 row_mask:0xf bank_mask:0xf bound_ctrl:1
	v_mov_b32_dpp v67, v65 row_ror:8 row_mask:0xf bank_mask:0xf bound_ctrl:1
	v_mov_b32_dpp v70, v68 row_ror:8 row_mask:0xf bank_mask:0xf bound_ctrl:1
	v_mov_b32_dpp v71, v69 row_ror:8 row_mask:0xf bank_mask:0xf bound_ctrl:1
	v_mov_b32_dpp v74, v72 row_ror:8 row_mask:0xf bank_mask:0xf bound_ctrl:1
	v_mov_b32_dpp v75, v73 row_ror:8 row_mask:0xf bank_mask:0xf bound_ctrl:1
	v_pk_add_f32 v[60:61], v[60:61], v[62:63]
	v_pk_add_f32 v[64:65], v[64:65], v[66:67]
	v_pk_add_f32 v[68:69], v[68:69], v[70:71]
	v_pk_add_f32 v[72:73], v[72:73], v[74:75]
	v_mov_b32_dpp v62, v60 row_ror:4 row_mask:0xf bank_mask:0xf bound_ctrl:1
	v_mov_b32_dpp v63, v61 row_ror:4 row_mask:0xf bank_mask:0xf bound_ctrl:1
	v_mov_b32_dpp v66, v64 row_ror:4 row_mask:0xf bank_mask:0xf bound_ctrl:1
	v_mov_b32_dpp v67, v65 row_ror:4 row_mask:0xf bank_mask:0xf bound_ctrl:1
	v_mov_b32_dpp v70, v68 row_ror:4 row_mask:0xf bank_mask:0xf bound_ctrl:1
	v_mov_b32_dpp v71, v69 row_ror:4 row_mask:0xf bank_mask:0xf bound_ctrl:1
	v_mov_b32_dpp v74, v72 row_ror:4 row_mask:0xf bank_mask:0xf bound_ctrl:1
	v_mov_b32_dpp v75, v73 row_ror:4 row_mask:0xf bank_mask:0xf bound_ctrl:1
	v_pk_add_f32 v[60:61], v[60:61], v[62:63]
	v_pk_add_f32 v[64:65], v[64:65], v[66:67]
	v_pk_add_f32 v[68:69], v[68:69], v[70:71]
	v_pk_add_f32 v[72:73], v[72:73], v[74:75]
	v_mov_b32_dpp v62, v60 row_ror:2 row_mask:0xf bank_mask:0xf bound_ctrl:1
	v_mov_b32_dpp v63, v61 row_ror:2 row_mask:0xf bank_mask:0xf bound_ctrl:1
	v_mov_b32_dpp v66, v64 row_ror:2 row_mask:0xf bank_mask:0xf bound_ctrl:1
	v_mov_b32_dpp v67, v65 row_ror:2 row_mask:0xf bank_mask:0xf bound_ctrl:1
	v_mov_b32_dpp v70, v68 row_ror:2 row_mask:0xf bank_mask:0xf bound_ctrl:1
	v_mov_b32_dpp v71, v69 row_ror:2 row_mask:0xf bank_mask:0xf bound_ctrl:1
	v_mov_b32_dpp v74, v72 row_ror:2 row_mask:0xf bank_mask:0xf bound_ctrl:1
	v_mov_b32_dpp v75, v73 row_ror:2 row_mask:0xf bank_mask:0xf bound_ctrl:1
	v_pk_add_f32 v[60:61], v[60:61], v[62:63]
	v_pk_add_f32 v[64:65], v[64:65], v[66:67]
	v_pk_add_f32 v[68:69], v[68:69], v[70:71]
	v_pk_add_f32 v[72:73], v[72:73], v[74:75]
	v_mov_b32_dpp v62, v60 row_ror:1 row_mask:0xf bank_mask:0xf bound_ctrl:1
	v_mov_b32_dpp v63, v61 row_ror:1 row_mask:0xf bank_mask:0xf bound_ctrl:1
	v_mov_b32_dpp v66, v64 row_ror:1 row_mask:0xf bank_mask:0xf bound_ctrl:1
	v_mov_b32_dpp v67, v65 row_ror:1 row_mask:0xf bank_mask:0xf bound_ctrl:1
	v_mov_b32_dpp v70, v68 row_ror:1 row_mask:0xf bank_mask:0xf bound_ctrl:1
	v_mov_b32_dpp v71, v69 row_ror:1 row_mask:0xf bank_mask:0xf bound_ctrl:1
	v_mov_b32_dpp v74, v72 row_ror:1 row_mask:0xf bank_mask:0xf bound_ctrl:1
	v_mov_b32_dpp v75, v73 row_ror:1 row_mask:0xf bank_mask:0xf bound_ctrl:1
	s_and_saveexec_b64 s[18:19], s[0:1]
	s_cbranch_execz .LBB0_672
	v_pk_add_f32 v[60:61], v[60:61], v[62:63]
	v_pk_add_f32 v[62:63], v[64:65], v[66:67]
	s_nop 0
	v_pk_mul_f32 v[62:63], v[62:63], s[12:13] op_sel_hi:[1,0]
	ds_write_b128 v77, v[60:63] offset:36864
	v_pk_add_f32 v[60:61], v[68:69], v[70:71]
	v_pk_add_f32 v[62:63], v[72:73], v[74:75]
	v_pk_mul_f32 v[60:61], v[60:61], s[12:13] op_sel_hi:[1,0]
	v_pk_mul_f32 v[62:63], v[62:63], s[12:13] op_sel_hi:[1,0]
	ds_write_b128 v77, v[60:63] offset:36880

.LBB0_675:
	v_lshrrev_b32_e32 v38, 4, v3
	v_add_u32_e32 v38, 0x1b600, v38
	ds_read2_b32 v[6:7], v38 offset0:1
	s_waitcnt vmcnt(11)
	s_waitcnt vmcnt(6)
	s_waitcnt vmcnt(5)
	s_waitcnt vmcnt(3)
	v_mov_b32_e32 v1, 1
	v_lshl_add_u64 v[4:5], v[4:5], 0, s[4:5]
	s_movk_i32 s0, 0x7fff
	v_lshlrev_b64 v[4:5], 12, v[4:5]
	s_mov_b32 s7, 0
	s_waitcnt lgkmcnt(0)
	v_and_b32_sdwa v3, v7, v1 dst_sel:DWORD dst_unused:UNUSED_PAD src0_sel:WORD_1 src1_sel:DWORD
	v_and_b32_sdwa v1, v6, v1 dst_sel:DWORD dst_unused:UNUSED_PAD src0_sel:WORD_1 src1_sel:DWORD
	v_add3_u32 v3, v7, v3, s0
	v_lshl_add_u64 v[4:5], s[20:21], 0, v[4:5]
	v_add3_u32 v1, v6, v1, s0
	v_lshrrev_b32_e32 v3, 16, v3
	s_mov_b32 s0, 0xffff0000
	v_lshl_add_u64 v[4:5], v[4:5], 0, s[6:7]
	s_mov_b32 s9, s7
	v_and_or_b32 v1, v1, s0, v3
	v_lshl_add_u64 v[4:5], v[4:5], 0, s[8:9]
	v_mov_b32_e32 v3, 0
	v_lshl_add_u64 v[2:3], v[4:5], 0, v[2:3]
	v_add_co_u32_e32 v2, vcc, 0x3fe0000, v2
	s_nop 1
	v_addc_co_u32_e32 v3, vcc, 0, v3, vcc
	global_store_dword v[2:3], v1, off

.LBB0_678:
	s_addk_i32 s95, 0x4000
	v_lshl_add_u64 v[90:91], v[90:91], 0, s[76:77]
	v_lshl_add_u64 v[92:93], v[92:93], 0, s[76:77]
	v_lshl_add_u64 v[94:95], v[94:95], 0, s[76:77]
	v_lshl_add_u64 v[96:97], v[96:97], 0, s[76:77]
	v_lshl_add_u64 v[98:99], v[98:99], 0, s[76:77]
	v_lshl_add_u64 v[100:101], v[100:101], 0, s[76:77]
	v_lshl_add_u64 v[102:103], v[102:103], 0, s[76:77]
	v_lshl_add_u64 v[104:105], v[104:105], 0, s[76:77]
	s_lshl_b32 s96, s9, 1
	v_mov_b32_e32 v111, v71
	s_lshl_b32 s0, s9, 2
	s_mov_b32 s1, s97
	v_lshl_add_u64 v[120:121], v[88:89], 0, s[0:1]
	global_load_dword v182, v[120:121], off offset:0
	global_load_dword v183, v[120:121], off offset:64
	global_load_dword v184, v[120:121], off offset:128
	global_load_dword v185, v[120:121], off offset:192
	global_load_dword v186, v[120:121], off offset:256
	global_load_dword v187, v[120:121], off offset:320
	global_load_dword v188, v[120:121], off offset:384
	global_load_dword v189, v[120:121], off offset:448
	global_load_dword v190, v[120:121], off offset:512
	global_load_dword v191, v[120:121], off offset:576
	global_load_dword v192, v[120:121], off offset:640
	global_load_dword v193, v[120:121], off offset:704
	global_load_dword v194, v[120:121], off offset:768
	global_load_dword v195, v[120:121], off offset:832
	global_load_dword v196, v[120:121], off offset:896
	global_load_dword v197, v[120:121], off offset:960
	v_mov_b32_e32 v113, s11
	v_or_b32_e32 v112, s10, v86
	v_lshlrev_b64 v[114:115], 12, v[112:113]
	v_lshl_add_u64 v[114:115], s[78:79], 0, v[114:115]
	v_lshl_add_u64 v[114:115], v[114:115], 0, s[96:97]
	v_lshl_add_u64 v[114:115], v[114:115], 0, v[110:111]
	v_lshl_add_u64 v[114:115], v[114:115], 0, s[80:81]
	v_lshlrev_b64 v[118:119], 13, v[112:113]
	v_lshl_add_u64 v[118:119], s[92:93], 0, v[118:119]
	v_lshl_add_u64 v[118:119], v[118:119], 0, s[96:97]
	v_lshl_add_u64 v[118:119], v[118:119], 0, v[110:111]
	v_lshl_add_u64 v[118:119], v[118:119], 0, s[90:91]
	global_load_ushort v198, v[114:115], off offset:0
	global_load_ushort v199, v[114:115], off offset:32
	global_load_ushort v200, v[114:115], off offset:64
	global_load_ushort v201, v[114:115], off offset:96
	global_load_ushort v202, v[114:115], off offset:128
	global_load_ushort v203, v[114:115], off offset:160
	global_load_ushort v204, v[114:115], off offset:192
	global_load_ushort v205, v[114:115], off offset:224
	global_load_ushort v206, v[114:115], off offset:256
	global_load_ushort v207, v[114:115], off offset:288
	global_load_ushort v208, v[114:115], off offset:320
	global_load_ushort v209, v[114:115], off offset:352
	global_load_ushort v210, v[114:115], off offset:384
	global_load_ushort v211, v[114:115], off offset:416
	global_load_ushort v212, v[114:115], off offset:448
	global_load_ushort v213, v[114:115], off offset:480
	global_load_ushort v214, v[118:119], off offset:0
	global_load_ushort v215, v[118:119], off offset:32
	global_load_ushort v216, v[118:119], off offset:64
	global_load_ushort v217, v[118:119], off offset:96
	global_load_ushort v218, v[118:119], off offset:128
	global_load_ushort v219, v[118:119], off offset:160
	global_load_ushort v220, v[118:119], off offset:192
	global_load_ushort v221, v[118:119], off offset:224
	global_load_ushort v222, v[118:119], off offset:256
	global_load_ushort v223, v[118:119], off offset:288
	global_load_ushort v224, v[118:119], off offset:320
	global_load_ushort v225, v[118:119], off offset:352
	global_load_ushort v226, v[118:119], off offset:384
	global_load_ushort v227, v[118:119], off offset:416
	global_load_ushort v228, v[118:119], off offset:448
	global_load_ushort v229, v[118:119], off offset:480
	v_mov_b32_e32 v120, v114
	v_mov_b32_e32 v121, v115
	s_waitcnt vmcnt(16)
	v_lshlrev_b32_e32 v198, 16, v198
	v_add_f32_e32 v62, v62, v198
	v_add_f32_e32 v230, 0, v62
	v_lshlrev_b32_e32 v199, 16, v199
	v_add_f32_e32 v58, v58, v199
	v_add_f32_e32 v230, v230, v58
	v_lshlrev_b32_e32 v200, 16, v200
	v_add_f32_e32 v54, v54, v200
	v_add_f32_e32 v230, v230, v54
	v_lshlrev_b32_e32 v201, 16, v201
	v_add_f32_e32 v50, v50, v201
	v_add_f32_e32 v230, v230, v50
	v_lshlrev_b32_e32 v202, 16, v202
	v_add_f32_e32 v46, v46, v202
	v_add_f32_e32 v230, v230, v46
	v_lshlrev_b32_e32 v203, 16, v203
	v_add_f32_e32 v42, v42, v203
	v_add_f32_e32 v230, v230, v42
	v_lshlrev_b32_e32 v204, 16, v204
	v_add_f32_e32 v38, v38, v204
	v_add_f32_e32 v230, v230, v38
	v_lshlrev_b32_e32 v205, 16, v205
	v_add_f32_e32 v34, v34, v205
	v_add_f32_e32 v230, v230, v34
	v_lshlrev_b32_e32 v206, 16, v206
	v_add_f32_e32 v30, v30, v206
	v_add_f32_e32 v230, v230, v30
	v_lshlrev_b32_e32 v207, 16, v207
	v_add_f32_e32 v26, v26, v207
	v_add_f32_e32 v230, v230, v26
	v_lshlrev_b32_e32 v208, 16, v208
	v_add_f32_e32 v22, v22, v208
	v_add_f32_e32 v230, v230, v22
	v_lshlrev_b32_e32 v209, 16, v209
	v_add_f32_e32 v18, v18, v209
	v_add_f32_e32 v230, v230, v18
	v_lshlrev_b32_e32 v210, 16, v210
	v_add_f32_e32 v14, v14, v210
	v_add_f32_e32 v230, v230, v14
	v_lshlrev_b32_e32 v211, 16, v211
	v_add_f32_e32 v10, v10, v211
	v_add_f32_e32 v230, v230, v10
	v_lshlrev_b32_e32 v212, 16, v212
	v_add_f32_e32 v6, v6, v212
	v_add_f32_e32 v230, v230, v6
	v_lshlrev_b32_e32 v213, 16, v213
	v_add_f32_e32 v2, v2, v213
	v_add_f32_e32 v230, v230, v2
	v_or_b32_e32 v116, 1, v112
	v_mov_b32_e32 v117, s11
	v_lshlrev_b64 v[114:115], 12, v[116:117]
	v_lshl_add_u64 v[114:115], s[78:79], 0, v[114:115]
	v_lshl_add_u64 v[114:115], v[114:115], 0, s[96:97]
	v_lshl_add_u64 v[114:115], v[114:115], 0, v[110:111]
	v_lshl_add_u64 v[114:115], v[114:115], 0, s[80:81]
	v_lshlrev_b64 v[118:119], 13, v[116:117]
	v_lshl_add_u64 v[118:119], s[92:93], 0, v[118:119]
	v_lshl_add_u64 v[118:119], v[118:119], 0, s[96:97]
	v_lshl_add_u64 v[118:119], v[118:119], 0, v[110:111]
	v_lshl_add_u64 v[118:119], v[118:119], 0, s[90:91]
	global_load_ushort v198, v[114:115], off offset:0
	global_load_ushort v199, v[114:115], off offset:32
	global_load_ushort v200, v[114:115], off offset:64
	global_load_ushort v201, v[114:115], off offset:96
	global_load_ushort v202, v[114:115], off offset:128
	global_load_ushort v203, v[114:115], off offset:160
	global_load_ushort v204, v[114:115], off offset:192
	global_load_ushort v205, v[114:115], off offset:224
	global_load_ushort v206, v[114:115], off offset:256
	global_load_ushort v207, v[114:115], off offset:288
	global_load_ushort v208, v[114:115], off offset:320
	global_load_ushort v209, v[114:115], off offset:352
	global_load_ushort v210, v[114:115], off offset:384
	global_load_ushort v211, v[114:115], off offset:416
	global_load_ushort v212, v[114:115], off offset:448
	global_load_ushort v213, v[114:115], off offset:480
	s_nop 1
	v_add_f32_dpp v230, v230, v230 row_ror:8 row_mask:0xf bank_mask:0xf bound_ctrl:1
	s_nop 1
	v_add_f32_dpp v230, v230, v230 row_ror:4 row_mask:0xf bank_mask:0xf bound_ctrl:1
	s_nop 1
	v_add_f32_dpp v230, v230, v230 row_ror:2 row_mask:0xf bank_mask:0xf bound_ctrl:1
	s_nop 1
	v_add_f32_dpp v230, v230, v230 row_ror:1 row_mask:0xf bank_mask:0xf bound_ctrl:1
	v_fmac_f32_e32 v58, 0xbb800000, v230
	v_mul_f32_e32 v231, v58, v58
	v_fmac_f32_e32 v62, 0xbb800000, v230
	v_fmac_f32_e32 v231, v62, v62
	v_fmac_f32_e32 v54, 0xbb800000, v230
	v_fmac_f32_e32 v231, v54, v54
	v_fmac_f32_e32 v50, 0xbb800000, v230
	v_fmac_f32_e32 v231, v50, v50
	v_fmac_f32_e32 v46, 0xbb800000, v230
	v_fmac_f32_e32 v231, v46, v46
	v_fmac_f32_e32 v42, 0xbb800000, v230
	v_fmac_f32_e32 v231, v42, v42
	v_fmac_f32_e32 v38, 0xbb800000, v230
	v_fmac_f32_e32 v231, v38, v38
	v_fmac_f32_e32 v34, 0xbb800000, v230
	v_fmac_f32_e32 v231, v34, v34
	v_fmac_f32_e32 v30, 0xbb800000, v230
	v_fmac_f32_e32 v231, v30, v30
	v_fmac_f32_e32 v26, 0xbb800000, v230
	v_fmac_f32_e32 v231, v26, v26
	v_fmac_f32_e32 v22, 0xbb800000, v230
	v_fmac_f32_e32 v231, v22, v22
	v_fmac_f32_e32 v18, 0xbb800000, v230
	v_fmac_f32_e32 v231, v18, v18
	v_fmac_f32_e32 v14, 0xbb800000, v230
	v_fmac_f32_e32 v231, v14, v14
	v_fmac_f32_e32 v10, 0xbb800000, v230
	v_fmac_f32_e32 v231, v10, v10
	v_fmac_f32_e32 v6, 0xbb800000, v230
	v_fmac_f32_e32 v231, v6, v6
	v_fmac_f32_e32 v2, 0xbb800000, v230
	v_fmac_f32_e32 v231, v2, v2
	s_nop 1
	v_add_f32_dpp v232, v231, v231 row_ror:8 row_mask:0xf bank_mask:0xf bound_ctrl:1
	s_nop 1
	v_add_f32_dpp v232, v232, v232 row_ror:4 row_mask:0xf bank_mask:0xf bound_ctrl:1
	s_nop 1
	v_add_f32_dpp v232, v232, v232 row_ror:2 row_mask:0xf bank_mask:0xf bound_ctrl:1
	s_nop 1
	v_add_f32_dpp v232, v232, v232 row_ror:1 row_mask:0xf bank_mask:0xf bound_ctrl:1
	v_fmamk_f32 v232, v232, 0x3b800000, v169
	v_cmp_gt_f32_e32 vcc, s7, v232
	v_mul_f32_e32 v233, 0x4f800000, v232
	s_nop 0
	v_cndmask_b32_e32 v232, v232, v233, vcc
	v_sqrt_f32_e32 v233, v232
	s_nop 0
	v_add_u32_e32 v234, -1, v233
	v_fma_f32 v235, -v234, v233, v232
	v_cmp_ge_f32_e64 s[0:1], 0, v235
	v_add_u32_e32 v235, 1, v233
	s_nop 0
	v_cndmask_b32_e64 v234, v233, v234, s[0:1]
	v_fma_f32 v233, -v235, v233, v232
	v_cmp_lt_f32_e64 s[0:1], 0, v233
	s_nop 1
	v_cndmask_b32_e64 v233, v234, v235, s[0:1]
	v_mul_f32_e32 v234, 0x37800000, v233
	s_nop 0
	v_cndmask_b32_e32 v233, v233, v234, vcc
	v_cmp_class_f32_e32 vcc, v232, v170
	s_nop 1
	v_cndmask_b32_e32 v232, v233, v232, vcc
	v_div_scale_f32 v233, s[0:1], v232, v232, 1.0
	v_rcp_f32_e32 v234, v233
	s_nop 0
	v_fma_f32 v235, -v233, v234, 1.0
	v_fmac_f32_e32 v234, v235, v234
	v_div_scale_f32 v235, vcc, 1.0, v232, 1.0
	v_mul_f32_e32 v236, v235, v234
	v_fma_f32 v237, -v233, v236, v235
	v_fmac_f32_e32 v236, v237, v234
	v_fma_f32 v233, -v233, v236, v235
	v_div_fmas_f32 v233, v233, v234, v236
	v_div_fixup_f32 v232, v233, v232, 1.0
	s_waitcnt vmcnt(16)
	v_lshlrev_b32_e32 v174, 16, v214
	v_mul_f32_e32 v175, 0xbfb8aa3b, v174
	v_exp_f32_e32 v175, v175
	v_mul_f32_e32 v176, v62, v232
	v_mul_f32_e32 v176, v182, v176
	v_add_f32_e32 v175, 1.0, v175
	v_div_scale_f32 v177, s[0:1], v175, v175, 1.0
	v_rcp_f32_e32 v178, v177
	s_nop 0
	v_fma_f32 v179, -v177, v178, 1.0
	v_fmac_f32_e32 v178, v179, v178
	v_div_scale_f32 v179, vcc, 1.0, v175, 1.0
	v_mul_f32_e32 v180, v179, v178
	v_fma_f32 v181, -v177, v180, v179
	v_fmac_f32_e32 v180, v181, v178
	v_fma_f32 v177, -v177, v180, v179
	v_div_fmas_f32 v177, v177, v178, v180
	v_div_fixup_f32 v175, v177, v175, 1.0
	v_mul_f32_e32 v174, v175, v174
	v_mul_f32_e32 v174, v174, v176
	v_bfe_u32 v176, v174, 16, 1
	v_add3_u32 v174, v174, v176, s5
	global_store_short_d16_hi v[120:121], v174, off offset:0
	v_lshlrev_b32_e32 v230, 16, v215
	v_mul_f32_e32 v231, 0xbfb8aa3b, v230
	v_exp_f32_e32 v231, v231
	v_mul_f32_e32 v233, v58, v232
	v_mul_f32_e32 v233, v183, v233
	v_add_f32_e32 v231, 1.0, v231
	v_div_scale_f32 v234, s[0:1], v231, v231, 1.0
	v_rcp_f32_e32 v235, v234
	s_nop 0
	v_fma_f32 v236, -v234, v235, 1.0
	v_fmac_f32_e32 v235, v236, v235
	v_div_scale_f32 v236, vcc, 1.0, v231, 1.0
	v_mul_f32_e32 v237, v236, v235
	v_fma_f32 v109, -v234, v237, v236
	v_fmac_f32_e32 v237, v109, v235
	v_fma_f32 v234, -v234, v237, v236
	v_div_fmas_f32 v234, v234, v235, v237
	v_div_fixup_f32 v231, v234, v231, 1.0
	v_mul_f32_e32 v230, v231, v230
	v_mul_f32_e32 v230, v230, v233
	v_bfe_u32 v233, v230, 16, 1
	v_add3_u32 v230, v230, v233, s5
	global_store_short_d16_hi v[120:121], v230, off offset:32
	v_lshlrev_b32_e32 v174, 16, v216
	v_mul_f32_e32 v175, 0xbfb8aa3b, v174
	v_exp_f32_e32 v175, v175
	v_mul_f32_e32 v176, v54, v232
	v_mul_f32_e32 v176, v184, v176
	v_add_f32_e32 v175, 1.0, v175
	v_div_scale_f32 v177, s[0:1], v175, v175, 1.0
	v_rcp_f32_e32 v178, v177
	s_nop 0
	v_fma_f32 v179, -v177, v178, 1.0
	v_fmac_f32_e32 v178, v179, v178
	v_div_scale_f32 v179, vcc, 1.0, v175, 1.0
	v_mul_f32_e32 v180, v179, v178
	v_fma_f32 v181, -v177, v180, v179
	v_fmac_f32_e32 v180, v181, v178
	v_fma_f32 v177, -v177, v180, v179
	v_div_fmas_f32 v177, v177, v178, v180
	v_div_fixup_f32 v175, v177, v175, 1.0
	v_mul_f32_e32 v174, v175, v174
	v_mul_f32_e32 v174, v174, v176
	v_bfe_u32 v176, v174, 16, 1
	v_add3_u32 v174, v174, v176, s5
	global_store_short_d16_hi v[120:121], v174, off offset:64
	v_lshlrev_b32_e32 v230, 16, v217
	v_mul_f32_e32 v231, 0xbfb8aa3b, v230
	v_exp_f32_e32 v231, v231
	v_mul_f32_e32 v233, v50, v232
	v_mul_f32_e32 v233, v185, v233
	v_add_f32_e32 v231, 1.0, v231
	v_div_scale_f32 v234, s[0:1], v231, v231, 1.0
	v_rcp_f32_e32 v235, v234
	s_nop 0
	v_fma_f32 v236, -v234, v235, 1.0
	v_fmac_f32_e32 v235, v236, v235
	v_div_scale_f32 v236, vcc, 1.0, v231, 1.0
	v_mul_f32_e32 v237, v236, v235
	v_fma_f32 v109, -v234, v237, v236
	v_fmac_f32_e32 v237, v109, v235
	v_fma_f32 v234, -v234, v237, v236
	v_div_fmas_f32 v234, v234, v235, v237
	v_div_fixup_f32 v231, v234, v231, 1.0
	v_mul_f32_e32 v230, v231, v230
	v_mul_f32_e32 v230, v230, v233
	v_bfe_u32 v233, v230, 16, 1
	v_add3_u32 v230, v230, v233, s5
	global_store_short_d16_hi v[120:121], v230, off offset:96
	v_lshlrev_b32_e32 v174, 16, v218
	v_mul_f32_e32 v175, 0xbfb8aa3b, v174
	v_exp_f32_e32 v175, v175
	v_mul_f32_e32 v176, v46, v232
	v_mul_f32_e32 v176, v186, v176
	v_add_f32_e32 v175, 1.0, v175
	v_div_scale_f32 v177, s[0:1], v175, v175, 1.0
	v_rcp_f32_e32 v178, v177
	s_nop 0
	v_fma_f32 v179, -v177, v178, 1.0
	v_fmac_f32_e32 v178, v179, v178
	v_div_scale_f32 v179, vcc, 1.0, v175, 1.0
	v_mul_f32_e32 v180, v179, v178
	v_fma_f32 v181, -v177, v180, v179
	v_fmac_f32_e32 v180, v181, v178
	v_fma_f32 v177, -v177, v180, v179
	v_div_fmas_f32 v177, v177, v178, v180
	v_div_fixup_f32 v175, v177, v175, 1.0
	v_mul_f32_e32 v174, v175, v174
	v_mul_f32_e32 v174, v174, v176
	v_bfe_u32 v176, v174, 16, 1
	v_add3_u32 v174, v174, v176, s5
	global_store_short_d16_hi v[120:121], v174, off offset:128
	v_lshlrev_b32_e32 v230, 16, v219
	v_mul_f32_e32 v231, 0xbfb8aa3b, v230
	v_exp_f32_e32 v231, v231
	v_mul_f32_e32 v233, v42, v232
	v_mul_f32_e32 v233, v187, v233
	v_add_f32_e32 v231, 1.0, v231
	v_div_scale_f32 v234, s[0:1], v231, v231, 1.0
	v_rcp_f32_e32 v235, v234
	s_nop 0
	v_fma_f32 v236, -v234, v235, 1.0
	v_fmac_f32_e32 v235, v236, v235
	v_div_scale_f32 v236, vcc, 1.0, v231, 1.0
	v_mul_f32_e32 v237, v236, v235
	v_fma_f32 v109, -v234, v237, v236
	v_fmac_f32_e32 v237, v109, v235
	v_fma_f32 v234, -v234, v237, v236
	v_div_fmas_f32 v234, v234, v235, v237
	v_div_fixup_f32 v231, v234, v231, 1.0
	v_mul_f32_e32 v230, v231, v230
	v_mul_f32_e32 v230, v230, v233
	v_bfe_u32 v233, v230, 16, 1
	v_add3_u32 v230, v230, v233, s5
	global_store_short_d16_hi v[120:121], v230, off offset:160
	v_lshlrev_b32_e32 v174, 16, v220
	v_mul_f32_e32 v175, 0xbfb8aa3b, v174
	v_exp_f32_e32 v175, v175
	v_mul_f32_e32 v176, v38, v232
	v_mul_f32_e32 v176, v188, v176
	v_add_f32_e32 v175, 1.0, v175
	v_div_scale_f32 v177, s[0:1], v175, v175, 1.0
	v_rcp_f32_e32 v178, v177
	s_nop 0
	v_fma_f32 v179, -v177, v178, 1.0
	v_fmac_f32_e32 v178, v179, v178
	v_div_scale_f32 v179, vcc, 1.0, v175, 1.0
	v_mul_f32_e32 v180, v179, v178
	v_fma_f32 v181, -v177, v180, v179
	v_fmac_f32_e32 v180, v181, v178
	v_fma_f32 v177, -v177, v180, v179
	v_div_fmas_f32 v177, v177, v178, v180
	v_div_fixup_f32 v175, v177, v175, 1.0
	v_mul_f32_e32 v174, v175, v174
	v_mul_f32_e32 v174, v174, v176
	v_bfe_u32 v176, v174, 16, 1
	v_add3_u32 v174, v174, v176, s5
	global_store_short_d16_hi v[120:121], v174, off offset:192
	v_lshlrev_b32_e32 v230, 16, v221
	v_mul_f32_e32 v231, 0xbfb8aa3b, v230
	v_exp_f32_e32 v231, v231
	v_mul_f32_e32 v233, v34, v232
	v_mul_f32_e32 v233, v189, v233
	v_add_f32_e32 v231, 1.0, v231
	v_div_scale_f32 v234, s[0:1], v231, v231, 1.0
	v_rcp_f32_e32 v235, v234
	s_nop 0
	v_fma_f32 v236, -v234, v235, 1.0
	v_fmac_f32_e32 v235, v236, v235
	v_div_scale_f32 v236, vcc, 1.0, v231, 1.0
	v_mul_f32_e32 v237, v236, v235
	v_fma_f32 v109, -v234, v237, v236
	v_fmac_f32_e32 v237, v109, v235
	v_fma_f32 v234, -v234, v237, v236
	v_div_fmas_f32 v234, v234, v235, v237
	v_div_fixup_f32 v231, v234, v231, 1.0
	v_mul_f32_e32 v230, v231, v230
	v_mul_f32_e32 v230, v230, v233
	v_bfe_u32 v233, v230, 16, 1
	v_add3_u32 v230, v230, v233, s5
	global_store_short_d16_hi v[120:121], v230, off offset:224
	v_lshlrev_b32_e32 v174, 16, v222
	v_mul_f32_e32 v175, 0xbfb8aa3b, v174
	v_exp_f32_e32 v175, v175
	v_mul_f32_e32 v176, v30, v232
	v_mul_f32_e32 v176, v190, v176
	v_add_f32_e32 v175, 1.0, v175
	v_div_scale_f32 v177, s[0:1], v175, v175, 1.0
	v_rcp_f32_e32 v178, v177
	s_nop 0
	v_fma_f32 v179, -v177, v178, 1.0
	v_fmac_f32_e32 v178, v179, v178
	v_div_scale_f32 v179, vcc, 1.0, v175, 1.0
	v_mul_f32_e32 v180, v179, v178
	v_fma_f32 v181, -v177, v180, v179
	v_fmac_f32_e32 v180, v181, v178
	v_fma_f32 v177, -v177, v180, v179
	v_div_fmas_f32 v177, v177, v178, v180
	v_div_fixup_f32 v175, v177, v175, 1.0
	v_mul_f32_e32 v174, v175, v174
	v_mul_f32_e32 v174, v174, v176
	v_bfe_u32 v176, v174, 16, 1
	v_add3_u32 v174, v174, v176, s5
	global_store_short_d16_hi v[120:121], v174, off offset:256
	v_lshlrev_b32_e32 v230, 16, v223
	v_mul_f32_e32 v231, 0xbfb8aa3b, v230
	v_exp_f32_e32 v231, v231
	v_mul_f32_e32 v233, v26, v232
	v_mul_f32_e32 v233, v191, v233
	v_add_f32_e32 v231, 1.0, v231
	v_div_scale_f32 v234, s[0:1], v231, v231, 1.0
	v_rcp_f32_e32 v235, v234
	s_nop 0
	v_fma_f32 v236, -v234, v235, 1.0
	v_fmac_f32_e32 v235, v236, v235
	v_div_scale_f32 v236, vcc, 1.0, v231, 1.0
	v_mul_f32_e32 v237, v236, v235
	v_fma_f32 v109, -v234, v237, v236
	v_fmac_f32_e32 v237, v109, v235
	v_fma_f32 v234, -v234, v237, v236
	v_div_fmas_f32 v234, v234, v235, v237
	v_div_fixup_f32 v231, v234, v231, 1.0
	v_mul_f32_e32 v230, v231, v230
	v_mul_f32_e32 v230, v230, v233
	v_bfe_u32 v233, v230, 16, 1
	v_add3_u32 v230, v230, v233, s5
	global_store_short_d16_hi v[120:121], v230, off offset:288
	v_lshlrev_b32_e32 v174, 16, v224
	v_mul_f32_e32 v175, 0xbfb8aa3b, v174
	v_exp_f32_e32 v175, v175
	v_mul_f32_e32 v176, v22, v232
	v_mul_f32_e32 v176, v192, v176
	v_add_f32_e32 v175, 1.0, v175
	v_div_scale_f32 v177, s[0:1], v175, v175, 1.0
	v_rcp_f32_e32 v178, v177
	s_nop 0
	v_fma_f32 v179, -v177, v178, 1.0
	v_fmac_f32_e32 v178, v179, v178
	v_div_scale_f32 v179, vcc, 1.0, v175, 1.0
	v_mul_f32_e32 v180, v179, v178
	v_fma_f32 v181, -v177, v180, v179
	v_fmac_f32_e32 v180, v181, v178
	v_fma_f32 v177, -v177, v180, v179
	v_div_fmas_f32 v177, v177, v178, v180
	v_div_fixup_f32 v175, v177, v175, 1.0
	v_mul_f32_e32 v174, v175, v174
	v_mul_f32_e32 v174, v174, v176
	v_bfe_u32 v176, v174, 16, 1
	v_add3_u32 v174, v174, v176, s5
	global_store_short_d16_hi v[120:121], v174, off offset:320
	v_lshlrev_b32_e32 v230, 16, v225
	v_mul_f32_e32 v231, 0xbfb8aa3b, v230
	v_exp_f32_e32 v231, v231
	v_mul_f32_e32 v233, v18, v232
	v_mul_f32_e32 v233, v193, v233
	v_add_f32_e32 v231, 1.0, v231
	v_div_scale_f32 v234, s[0:1], v231, v231, 1.0
	v_rcp_f32_e32 v235, v234
	s_nop 0
	v_fma_f32 v236, -v234, v235, 1.0
	v_fmac_f32_e32 v235, v236, v235
	v_div_scale_f32 v236, vcc, 1.0, v231, 1.0
	v_mul_f32_e32 v237, v236, v235
	v_fma_f32 v109, -v234, v237, v236
	v_fmac_f32_e32 v237, v109, v235
	v_fma_f32 v234, -v234, v237, v236
	v_div_fmas_f32 v234, v234, v235, v237
	v_div_fixup_f32 v231, v234, v231, 1.0
	v_mul_f32_e32 v230, v231, v230
	v_mul_f32_e32 v230, v230, v233
	v_bfe_u32 v233, v230, 16, 1
	v_add3_u32 v230, v230, v233, s5
	global_store_short_d16_hi v[120:121], v230, off offset:352
	v_lshlrev_b32_e32 v174, 16, v226
	v_mul_f32_e32 v175, 0xbfb8aa3b, v174
	v_exp_f32_e32 v175, v175
	v_mul_f32_e32 v176, v14, v232
	v_mul_f32_e32 v176, v194, v176
	v_add_f32_e32 v175, 1.0, v175
	v_div_scale_f32 v177, s[0:1], v175, v175, 1.0
	v_rcp_f32_e32 v178, v177
	s_nop 0
	v_fma_f32 v179, -v177, v178, 1.0
	v_fmac_f32_e32 v178, v179, v178
	v_div_scale_f32 v179, vcc, 1.0, v175, 1.0
	v_mul_f32_e32 v180, v179, v178
	v_fma_f32 v181, -v177, v180, v179
	v_fmac_f32_e32 v180, v181, v178
	v_fma_f32 v177, -v177, v180, v179
	v_div_fmas_f32 v177, v177, v178, v180
	v_div_fixup_f32 v175, v177, v175, 1.0
	v_mul_f32_e32 v174, v175, v174
	v_mul_f32_e32 v174, v174, v176
	v_bfe_u32 v176, v174, 16, 1
	v_add3_u32 v174, v174, v176, s5
	global_store_short_d16_hi v[120:121], v174, off offset:384
	v_lshlrev_b32_e32 v230, 16, v227
	v_mul_f32_e32 v231, 0xbfb8aa3b, v230
	v_exp_f32_e32 v231, v231
	v_mul_f32_e32 v233, v10, v232
	v_mul_f32_e32 v233, v195, v233
	v_add_f32_e32 v231, 1.0, v231
	v_div_scale_f32 v234, s[0:1], v231, v231, 1.0
	v_rcp_f32_e32 v235, v234
	s_nop 0
	v_fma_f32 v236, -v234, v235, 1.0
	v_fmac_f32_e32 v235, v236, v235
	v_div_scale_f32 v236, vcc, 1.0, v231, 1.0
	v_mul_f32_e32 v237, v236, v235
	v_fma_f32 v109, -v234, v237, v236
	v_fmac_f32_e32 v237, v109, v235
	v_fma_f32 v234, -v234, v237, v236
	v_div_fmas_f32 v234, v234, v235, v237
	v_div_fixup_f32 v231, v234, v231, 1.0
	v_mul_f32_e32 v230, v231, v230
	v_mul_f32_e32 v230, v230, v233
	v_bfe_u32 v233, v230, 16, 1
	v_add3_u32 v230, v230, v233, s5
	global_store_short_d16_hi v[120:121], v230, off offset:416
	v_lshlrev_b32_e32 v174, 16, v228
	v_mul_f32_e32 v175, 0xbfb8aa3b, v174
	v_exp_f32_e32 v175, v175
	v_mul_f32_e32 v176, v6, v232
	v_mul_f32_e32 v176, v196, v176
	v_add_f32_e32 v175, 1.0, v175
	v_div_scale_f32 v177, s[0:1], v175, v175, 1.0
	v_rcp_f32_e32 v178, v177
	s_nop 0
	v_fma_f32 v179, -v177, v178, 1.0
	v_fmac_f32_e32 v178, v179, v178
	v_div_scale_f32 v179, vcc, 1.0, v175, 1.0
	v_mul_f32_e32 v180, v179, v178
	v_fma_f32 v181, -v177, v180, v179
	v_fmac_f32_e32 v180, v181, v178
	v_fma_f32 v177, -v177, v180, v179
	v_div_fmas_f32 v177, v177, v178, v180
	v_div_fixup_f32 v175, v177, v175, 1.0
	v_mul_f32_e32 v174, v175, v174
	v_mul_f32_e32 v174, v174, v176
	v_bfe_u32 v176, v174, 16, 1
	v_add3_u32 v174, v174, v176, s5
	global_store_short_d16_hi v[120:121], v174, off offset:448
	v_lshlrev_b32_e32 v230, 16, v229
	v_mul_f32_e32 v231, 0xbfb8aa3b, v230
	v_exp_f32_e32 v231, v231
	v_mul_f32_e32 v233, v2, v232
	v_mul_f32_e32 v233, v197, v233
	v_add_f32_e32 v231, 1.0, v231
	v_div_scale_f32 v234, s[0:1], v231, v231, 1.0
	v_rcp_f32_e32 v235, v234
	s_nop 0
	v_fma_f32 v236, -v234, v235, 1.0
	v_fmac_f32_e32 v235, v236, v235
	v_div_scale_f32 v236, vcc, 1.0, v231, 1.0
	v_mul_f32_e32 v237, v236, v235
	v_fma_f32 v109, -v234, v237, v236
	v_fmac_f32_e32 v237, v109, v235
	v_fma_f32 v234, -v234, v237, v236
	v_div_fmas_f32 v234, v234, v235, v237
	v_div_fixup_f32 v231, v234, v231, 1.0
	v_mul_f32_e32 v230, v231, v230
	v_mul_f32_e32 v230, v230, v233
	v_bfe_u32 v233, v230, 16, 1
	v_add3_u32 v230, v230, v233, s5
	global_store_short_d16_hi v[120:121], v230, off offset:480
	global_load_ushort v214, v[118:119], off offset:0
	global_load_ushort v215, v[118:119], off offset:32
	global_load_ushort v216, v[118:119], off offset:64
	global_load_ushort v217, v[118:119], off offset:96
	global_load_ushort v218, v[118:119], off offset:128
	global_load_ushort v219, v[118:119], off offset:160
	global_load_ushort v220, v[118:119], off offset:192
	global_load_ushort v221, v[118:119], off offset:224
	global_load_ushort v222, v[118:119], off offset:256
	global_load_ushort v223, v[118:119], off offset:288
	global_load_ushort v224, v[118:119], off offset:320
	global_load_ushort v225, v[118:119], off offset:352
	global_load_ushort v226, v[118:119], off offset:384
	global_load_ushort v227, v[118:119], off offset:416
	global_load_ushort v228, v[118:119], off offset:448
	global_load_ushort v229, v[118:119], off offset:480
	v_mov_b32_e32 v120, v114
	v_mov_b32_e32 v121, v115
	s_waitcnt vmcnt(32)
	v_lshlrev_b32_e32 v198, 16, v198
	v_add_f32_e32 v63, v63, v198
	v_add_f32_e32 v230, 0, v63
	v_lshlrev_b32_e32 v199, 16, v199
	v_add_f32_e32 v59, v59, v199
	v_add_f32_e32 v230, v230, v59
	v_lshlrev_b32_e32 v200, 16, v200
	v_add_f32_e32 v55, v55, v200
	v_add_f32_e32 v230, v230, v55
	v_lshlrev_b32_e32 v201, 16, v201
	v_add_f32_e32 v51, v51, v201
	v_add_f32_e32 v230, v230, v51
	v_lshlrev_b32_e32 v202, 16, v202
	v_add_f32_e32 v47, v47, v202
	v_add_f32_e32 v230, v230, v47
	v_lshlrev_b32_e32 v203, 16, v203
	v_add_f32_e32 v43, v43, v203
	v_add_f32_e32 v230, v230, v43
	v_lshlrev_b32_e32 v204, 16, v204
	v_add_f32_e32 v39, v39, v204
	v_add_f32_e32 v230, v230, v39
	v_lshlrev_b32_e32 v205, 16, v205
	v_add_f32_e32 v35, v35, v205
	v_add_f32_e32 v230, v230, v35
	v_lshlrev_b32_e32 v206, 16, v206
	v_add_f32_e32 v31, v31, v206
	v_add_f32_e32 v230, v230, v31
	v_lshlrev_b32_e32 v207, 16, v207
	v_add_f32_e32 v27, v27, v207
	v_add_f32_e32 v230, v230, v27
	v_lshlrev_b32_e32 v208, 16, v208
	v_add_f32_e32 v23, v23, v208
	v_add_f32_e32 v230, v230, v23
	v_lshlrev_b32_e32 v209, 16, v209
	v_add_f32_e32 v19, v19, v209
	v_add_f32_e32 v230, v230, v19
	v_lshlrev_b32_e32 v210, 16, v210
	v_add_f32_e32 v15, v15, v210
	v_add_f32_e32 v230, v230, v15
	v_lshlrev_b32_e32 v211, 16, v211
	v_add_f32_e32 v11, v11, v211
	v_add_f32_e32 v230, v230, v11
	v_lshlrev_b32_e32 v212, 16, v212
	v_add_f32_e32 v7, v7, v212
	v_add_f32_e32 v230, v230, v7
	v_lshlrev_b32_e32 v213, 16, v213
	v_add_f32_e32 v3, v3, v213
	v_add_f32_e32 v230, v230, v3
	v_or_b32_e32 v116, 2, v112
	v_mov_b32_e32 v117, s11
	v_lshlrev_b64 v[114:115], 12, v[116:117]
	v_lshl_add_u64 v[114:115], s[78:79], 0, v[114:115]
	v_lshl_add_u64 v[114:115], v[114:115], 0, s[96:97]
	v_lshl_add_u64 v[114:115], v[114:115], 0, v[110:111]
	v_lshl_add_u64 v[114:115], v[114:115], 0, s[80:81]
	v_lshlrev_b64 v[118:119], 13, v[116:117]
	v_lshl_add_u64 v[118:119], s[92:93], 0, v[118:119]
	v_lshl_add_u64 v[118:119], v[118:119], 0, s[96:97]
	v_lshl_add_u64 v[118:119], v[118:119], 0, v[110:111]
	v_lshl_add_u64 v[118:119], v[118:119], 0, s[90:91]
	global_load_ushort v198, v[114:115], off offset:0
	global_load_ushort v199, v[114:115], off offset:32
	global_load_ushort v200, v[114:115], off offset:64
	global_load_ushort v201, v[114:115], off offset:96
	global_load_ushort v202, v[114:115], off offset:128
	global_load_ushort v203, v[114:115], off offset:160
	global_load_ushort v204, v[114:115], off offset:192
	global_load_ushort v205, v[114:115], off offset:224
	global_load_ushort v206, v[114:115], off offset:256
	global_load_ushort v207, v[114:115], off offset:288
	global_load_ushort v208, v[114:115], off offset:320
	global_load_ushort v209, v[114:115], off offset:352
	global_load_ushort v210, v[114:115], off offset:384
	global_load_ushort v211, v[114:115], off offset:416
	global_load_ushort v212, v[114:115], off offset:448
	global_load_ushort v213, v[114:115], off offset:480
	s_nop 1
	v_add_f32_dpp v230, v230, v230 row_ror:8 row_mask:0xf bank_mask:0xf bound_ctrl:1
	s_nop 1
	v_add_f32_dpp v230, v230, v230 row_ror:4 row_mask:0xf bank_mask:0xf bound_ctrl:1
	s_nop 1
	v_add_f32_dpp v230, v230, v230 row_ror:2 row_mask:0xf bank_mask:0xf bound_ctrl:1
	s_nop 1
	v_add_f32_dpp v230, v230, v230 row_ror:1 row_mask:0xf bank_mask:0xf bound_ctrl:1
	v_fmac_f32_e32 v59, 0xbb800000, v230
	v_mul_f32_e32 v231, v59, v59
	v_fmac_f32_e32 v63, 0xbb800000, v230
	v_fmac_f32_e32 v231, v63, v63
	v_fmac_f32_e32 v55, 0xbb800000, v230
	v_fmac_f32_e32 v231, v55, v55
	v_fmac_f32_e32 v51, 0xbb800000, v230
	v_fmac_f32_e32 v231, v51, v51
	v_fmac_f32_e32 v47, 0xbb800000, v230
	v_fmac_f32_e32 v231, v47, v47
	v_fmac_f32_e32 v43, 0xbb800000, v230
	v_fmac_f32_e32 v231, v43, v43
	v_fmac_f32_e32 v39, 0xbb800000, v230
	v_fmac_f32_e32 v231, v39, v39
	v_fmac_f32_e32 v35, 0xbb800000, v230
	v_fmac_f32_e32 v231, v35, v35
	v_fmac_f32_e32 v31, 0xbb800000, v230
	v_fmac_f32_e32 v231, v31, v31
	v_fmac_f32_e32 v27, 0xbb800000, v230
	v_fmac_f32_e32 v231, v27, v27
	v_fmac_f32_e32 v23, 0xbb800000, v230
	v_fmac_f32_e32 v231, v23, v23
	v_fmac_f32_e32 v19, 0xbb800000, v230
	v_fmac_f32_e32 v231, v19, v19
	v_fmac_f32_e32 v15, 0xbb800000, v230
	v_fmac_f32_e32 v231, v15, v15
	v_fmac_f32_e32 v11, 0xbb800000, v230
	v_fmac_f32_e32 v231, v11, v11
	v_fmac_f32_e32 v7, 0xbb800000, v230
	v_fmac_f32_e32 v231, v7, v7
	v_fmac_f32_e32 v3, 0xbb800000, v230
	v_fmac_f32_e32 v231, v3, v3
	s_nop 1
	v_add_f32_dpp v232, v231, v231 row_ror:8 row_mask:0xf bank_mask:0xf bound_ctrl:1
	s_nop 1
	v_add_f32_dpp v232, v232, v232 row_ror:4 row_mask:0xf bank_mask:0xf bound_ctrl:1
	s_nop 1
	v_add_f32_dpp v232, v232, v232 row_ror:2 row_mask:0xf bank_mask:0xf bound_ctrl:1
	s_nop 1
	v_add_f32_dpp v232, v232, v232 row_ror:1 row_mask:0xf bank_mask:0xf bound_ctrl:1
	v_fmamk_f32 v232, v232, 0x3b800000, v169
	v_cmp_gt_f32_e32 vcc, s7, v232
	v_mul_f32_e32 v233, 0x4f800000, v232
	s_nop 0
	v_cndmask_b32_e32 v232, v232, v233, vcc
	v_sqrt_f32_e32 v233, v232
	s_nop 0
	v_add_u32_e32 v234, -1, v233
	v_fma_f32 v235, -v234, v233, v232
	v_cmp_ge_f32_e64 s[0:1], 0, v235
	v_add_u32_e32 v235, 1, v233
	s_nop 0
	v_cndmask_b32_e64 v234, v233, v234, s[0:1]
	v_fma_f32 v233, -v235, v233, v232
	v_cmp_lt_f32_e64 s[0:1], 0, v233
	s_nop 1
	v_cndmask_b32_e64 v233, v234, v235, s[0:1]
	v_mul_f32_e32 v234, 0x37800000, v233
	s_nop 0
	v_cndmask_b32_e32 v233, v233, v234, vcc
	v_cmp_class_f32_e32 vcc, v232, v170
	s_nop 1
	v_cndmask_b32_e32 v232, v233, v232, vcc
	v_div_scale_f32 v233, s[0:1], v232, v232, 1.0
	v_rcp_f32_e32 v234, v233
	s_nop 0
	v_fma_f32 v235, -v233, v234, 1.0
	v_fmac_f32_e32 v234, v235, v234
	v_div_scale_f32 v235, vcc, 1.0, v232, 1.0
	v_mul_f32_e32 v236, v235, v234
	v_fma_f32 v237, -v233, v236, v235
	v_fmac_f32_e32 v236, v237, v234
	v_fma_f32 v233, -v233, v236, v235
	v_div_fmas_f32 v233, v233, v234, v236
	v_div_fixup_f32 v232, v233, v232, 1.0
	s_waitcnt vmcnt(16)
	v_lshlrev_b32_e32 v174, 16, v214
	v_mul_f32_e32 v175, 0xbfb8aa3b, v174
	v_exp_f32_e32 v175, v175
	v_mul_f32_e32 v176, v63, v232
	v_mul_f32_e32 v176, v182, v176
	v_add_f32_e32 v175, 1.0, v175
	v_div_scale_f32 v177, s[0:1], v175, v175, 1.0
	v_rcp_f32_e32 v178, v177
	s_nop 0
	v_fma_f32 v179, -v177, v178, 1.0
	v_fmac_f32_e32 v178, v179, v178
	v_div_scale_f32 v179, vcc, 1.0, v175, 1.0
	v_mul_f32_e32 v180, v179, v178
	v_fma_f32 v181, -v177, v180, v179
	v_fmac_f32_e32 v180, v181, v178
	v_fma_f32 v177, -v177, v180, v179
	v_div_fmas_f32 v177, v177, v178, v180
	v_div_fixup_f32 v175, v177, v175, 1.0
	v_mul_f32_e32 v174, v175, v174
	v_mul_f32_e32 v174, v174, v176
	v_bfe_u32 v176, v174, 16, 1
	v_add3_u32 v174, v174, v176, s5
	global_store_short_d16_hi v[120:121], v174, off offset:0
	v_lshlrev_b32_e32 v230, 16, v215
	v_mul_f32_e32 v231, 0xbfb8aa3b, v230
	v_exp_f32_e32 v231, v231
	v_mul_f32_e32 v233, v59, v232
	v_mul_f32_e32 v233, v183, v233
	v_add_f32_e32 v231, 1.0, v231
	v_div_scale_f32 v234, s[0:1], v231, v231, 1.0
	v_rcp_f32_e32 v235, v234
	s_nop 0
	v_fma_f32 v236, -v234, v235, 1.0
	v_fmac_f32_e32 v235, v236, v235
	v_div_scale_f32 v236, vcc, 1.0, v231, 1.0
	v_mul_f32_e32 v237, v236, v235
	v_fma_f32 v109, -v234, v237, v236
	v_fmac_f32_e32 v237, v109, v235
	v_fma_f32 v234, -v234, v237, v236
	v_div_fmas_f32 v234, v234, v235, v237
	v_div_fixup_f32 v231, v234, v231, 1.0
	v_mul_f32_e32 v230, v231, v230
	v_mul_f32_e32 v230, v230, v233
	v_bfe_u32 v233, v230, 16, 1
	v_add3_u32 v230, v230, v233, s5
	global_store_short_d16_hi v[120:121], v230, off offset:32
	v_lshlrev_b32_e32 v174, 16, v216
	v_mul_f32_e32 v175, 0xbfb8aa3b, v174
	v_exp_f32_e32 v175, v175
	v_mul_f32_e32 v176, v55, v232
	v_mul_f32_e32 v176, v184, v176
	v_add_f32_e32 v175, 1.0, v175
	v_div_scale_f32 v177, s[0:1], v175, v175, 1.0
	v_rcp_f32_e32 v178, v177
	s_nop 0
	v_fma_f32 v179, -v177, v178, 1.0
	v_fmac_f32_e32 v178, v179, v178
	v_div_scale_f32 v179, vcc, 1.0, v175, 1.0
	v_mul_f32_e32 v180, v179, v178
	v_fma_f32 v181, -v177, v180, v179
	v_fmac_f32_e32 v180, v181, v178
	v_fma_f32 v177, -v177, v180, v179
	v_div_fmas_f32 v177, v177, v178, v180
	v_div_fixup_f32 v175, v177, v175, 1.0
	v_mul_f32_e32 v174, v175, v174
	v_mul_f32_e32 v174, v174, v176
	v_bfe_u32 v176, v174, 16, 1
	v_add3_u32 v174, v174, v176, s5
	global_store_short_d16_hi v[120:121], v174, off offset:64
	v_lshlrev_b32_e32 v230, 16, v217
	v_mul_f32_e32 v231, 0xbfb8aa3b, v230
	v_exp_f32_e32 v231, v231
	v_mul_f32_e32 v233, v51, v232
	v_mul_f32_e32 v233, v185, v233
	v_add_f32_e32 v231, 1.0, v231
	v_div_scale_f32 v234, s[0:1], v231, v231, 1.0
	v_rcp_f32_e32 v235, v234
	s_nop 0
	v_fma_f32 v236, -v234, v235, 1.0
	v_fmac_f32_e32 v235, v236, v235
	v_div_scale_f32 v236, vcc, 1.0, v231, 1.0
	v_mul_f32_e32 v237, v236, v235
	v_fma_f32 v109, -v234, v237, v236
	v_fmac_f32_e32 v237, v109, v235
	v_fma_f32 v234, -v234, v237, v236
	v_div_fmas_f32 v234, v234, v235, v237
	v_div_fixup_f32 v231, v234, v231, 1.0
	v_mul_f32_e32 v230, v231, v230
	v_mul_f32_e32 v230, v230, v233
	v_bfe_u32 v233, v230, 16, 1
	v_add3_u32 v230, v230, v233, s5
	global_store_short_d16_hi v[120:121], v230, off offset:96
	v_lshlrev_b32_e32 v174, 16, v218
	v_mul_f32_e32 v175, 0xbfb8aa3b, v174
	v_exp_f32_e32 v175, v175
	v_mul_f32_e32 v176, v47, v232
	v_mul_f32_e32 v176, v186, v176
	v_add_f32_e32 v175, 1.0, v175
	v_div_scale_f32 v177, s[0:1], v175, v175, 1.0
	v_rcp_f32_e32 v178, v177
	s_nop 0
	v_fma_f32 v179, -v177, v178, 1.0
	v_fmac_f32_e32 v178, v179, v178
	v_div_scale_f32 v179, vcc, 1.0, v175, 1.0
	v_mul_f32_e32 v180, v179, v178
	v_fma_f32 v181, -v177, v180, v179
	v_fmac_f32_e32 v180, v181, v178
	v_fma_f32 v177, -v177, v180, v179
	v_div_fmas_f32 v177, v177, v178, v180
	v_div_fixup_f32 v175, v177, v175, 1.0
	v_mul_f32_e32 v174, v175, v174
	v_mul_f32_e32 v174, v174, v176
	v_bfe_u32 v176, v174, 16, 1
	v_add3_u32 v174, v174, v176, s5
	global_store_short_d16_hi v[120:121], v174, off offset:128
	v_lshlrev_b32_e32 v230, 16, v219
	v_mul_f32_e32 v231, 0xbfb8aa3b, v230
	v_exp_f32_e32 v231, v231
	v_mul_f32_e32 v233, v43, v232
	v_mul_f32_e32 v233, v187, v233
	v_add_f32_e32 v231, 1.0, v231
	v_div_scale_f32 v234, s[0:1], v231, v231, 1.0
	v_rcp_f32_e32 v235, v234
	s_nop 0
	v_fma_f32 v236, -v234, v235, 1.0
	v_fmac_f32_e32 v235, v236, v235
	v_div_scale_f32 v236, vcc, 1.0, v231, 1.0
	v_mul_f32_e32 v237, v236, v235
	v_fma_f32 v109, -v234, v237, v236
	v_fmac_f32_e32 v237, v109, v235
	v_fma_f32 v234, -v234, v237, v236
	v_div_fmas_f32 v234, v234, v235, v237
	v_div_fixup_f32 v231, v234, v231, 1.0
	v_mul_f32_e32 v230, v231, v230
	v_mul_f32_e32 v230, v230, v233
	v_bfe_u32 v233, v230, 16, 1
	v_add3_u32 v230, v230, v233, s5
	global_store_short_d16_hi v[120:121], v230, off offset:160
	v_lshlrev_b32_e32 v174, 16, v220
	v_mul_f32_e32 v175, 0xbfb8aa3b, v174
	v_exp_f32_e32 v175, v175
	v_mul_f32_e32 v176, v39, v232
	v_mul_f32_e32 v176, v188, v176
	v_add_f32_e32 v175, 1.0, v175
	v_div_scale_f32 v177, s[0:1], v175, v175, 1.0
	v_rcp_f32_e32 v178, v177
	s_nop 0
	v_fma_f32 v179, -v177, v178, 1.0
	v_fmac_f32_e32 v178, v179, v178
	v_div_scale_f32 v179, vcc, 1.0, v175, 1.0
	v_mul_f32_e32 v180, v179, v178
	v_fma_f32 v181, -v177, v180, v179
	v_fmac_f32_e32 v180, v181, v178
	v_fma_f32 v177, -v177, v180, v179
	v_div_fmas_f32 v177, v177, v178, v180
	v_div_fixup_f32 v175, v177, v175, 1.0
	v_mul_f32_e32 v174, v175, v174
	v_mul_f32_e32 v174, v174, v176
	v_bfe_u32 v176, v174, 16, 1
	v_add3_u32 v174, v174, v176, s5
	global_store_short_d16_hi v[120:121], v174, off offset:192
	v_lshlrev_b32_e32 v230, 16, v221
	v_mul_f32_e32 v231, 0xbfb8aa3b, v230
	v_exp_f32_e32 v231, v231
	v_mul_f32_e32 v233, v35, v232
	v_mul_f32_e32 v233, v189, v233
	v_add_f32_e32 v231, 1.0, v231
	v_div_scale_f32 v234, s[0:1], v231, v231, 1.0
	v_rcp_f32_e32 v235, v234
	s_nop 0
	v_fma_f32 v236, -v234, v235, 1.0
	v_fmac_f32_e32 v235, v236, v235
	v_div_scale_f32 v236, vcc, 1.0, v231, 1.0
	v_mul_f32_e32 v237, v236, v235
	v_fma_f32 v109, -v234, v237, v236
	v_fmac_f32_e32 v237, v109, v235
	v_fma_f32 v234, -v234, v237, v236
	v_div_fmas_f32 v234, v234, v235, v237
	v_div_fixup_f32 v231, v234, v231, 1.0
	v_mul_f32_e32 v230, v231, v230
	v_mul_f32_e32 v230, v230, v233
	v_bfe_u32 v233, v230, 16, 1
	v_add3_u32 v230, v230, v233, s5
	global_store_short_d16_hi v[120:121], v230, off offset:224
	v_lshlrev_b32_e32 v174, 16, v222
	v_mul_f32_e32 v175, 0xbfb8aa3b, v174
	v_exp_f32_e32 v175, v175
	v_mul_f32_e32 v176, v31, v232
	v_mul_f32_e32 v176, v190, v176
	v_add_f32_e32 v175, 1.0, v175
	v_div_scale_f32 v177, s[0:1], v175, v175, 1.0
	v_rcp_f32_e32 v178, v177
	s_nop 0
	v_fma_f32 v179, -v177, v178, 1.0
	v_fmac_f32_e32 v178, v179, v178
	v_div_scale_f32 v179, vcc, 1.0, v175, 1.0
	v_mul_f32_e32 v180, v179, v178
	v_fma_f32 v181, -v177, v180, v179
	v_fmac_f32_e32 v180, v181, v178
	v_fma_f32 v177, -v177, v180, v179
	v_div_fmas_f32 v177, v177, v178, v180
	v_div_fixup_f32 v175, v177, v175, 1.0
	v_mul_f32_e32 v174, v175, v174
	v_mul_f32_e32 v174, v174, v176
	v_bfe_u32 v176, v174, 16, 1
	v_add3_u32 v174, v174, v176, s5
	global_store_short_d16_hi v[120:121], v174, off offset:256
	v_lshlrev_b32_e32 v230, 16, v223
	v_mul_f32_e32 v231, 0xbfb8aa3b, v230
	v_exp_f32_e32 v231, v231
	v_mul_f32_e32 v233, v27, v232
	v_mul_f32_e32 v233, v191, v233
	v_add_f32_e32 v231, 1.0, v231
	v_div_scale_f32 v234, s[0:1], v231, v231, 1.0
	v_rcp_f32_e32 v235, v234
	s_nop 0
	v_fma_f32 v236, -v234, v235, 1.0
	v_fmac_f32_e32 v235, v236, v235
	v_div_scale_f32 v236, vcc, 1.0, v231, 1.0
	v_mul_f32_e32 v237, v236, v235
	v_fma_f32 v109, -v234, v237, v236
	v_fmac_f32_e32 v237, v109, v235
	v_fma_f32 v234, -v234, v237, v236
	v_div_fmas_f32 v234, v234, v235, v237
	v_div_fixup_f32 v231, v234, v231, 1.0
	v_mul_f32_e32 v230, v231, v230
	v_mul_f32_e32 v230, v230, v233
	v_bfe_u32 v233, v230, 16, 1
	v_add3_u32 v230, v230, v233, s5
	global_store_short_d16_hi v[120:121], v230, off offset:288
	v_lshlrev_b32_e32 v174, 16, v224
	v_mul_f32_e32 v175, 0xbfb8aa3b, v174
	v_exp_f32_e32 v175, v175
	v_mul_f32_e32 v176, v23, v232
	v_mul_f32_e32 v176, v192, v176
	v_add_f32_e32 v175, 1.0, v175
	v_div_scale_f32 v177, s[0:1], v175, v175, 1.0
	v_rcp_f32_e32 v178, v177
	s_nop 0
	v_fma_f32 v179, -v177, v178, 1.0
	v_fmac_f32_e32 v178, v179, v178
	v_div_scale_f32 v179, vcc, 1.0, v175, 1.0
	v_mul_f32_e32 v180, v179, v178
	v_fma_f32 v181, -v177, v180, v179
	v_fmac_f32_e32 v180, v181, v178
	v_fma_f32 v177, -v177, v180, v179
	v_div_fmas_f32 v177, v177, v178, v180
	v_div_fixup_f32 v175, v177, v175, 1.0
	v_mul_f32_e32 v174, v175, v174
	v_mul_f32_e32 v174, v174, v176
	v_bfe_u32 v176, v174, 16, 1
	v_add3_u32 v174, v174, v176, s5
	global_store_short_d16_hi v[120:121], v174, off offset:320
	v_lshlrev_b32_e32 v230, 16, v225
	v_mul_f32_e32 v231, 0xbfb8aa3b, v230
	v_exp_f32_e32 v231, v231
	v_mul_f32_e32 v233, v19, v232
	v_mul_f32_e32 v233, v193, v233
	v_add_f32_e32 v231, 1.0, v231
	v_div_scale_f32 v234, s[0:1], v231, v231, 1.0
	v_rcp_f32_e32 v235, v234
	s_nop 0
	v_fma_f32 v236, -v234, v235, 1.0
	v_fmac_f32_e32 v235, v236, v235
	v_div_scale_f32 v236, vcc, 1.0, v231, 1.0
	v_mul_f32_e32 v237, v236, v235
	v_fma_f32 v109, -v234, v237, v236
	v_fmac_f32_e32 v237, v109, v235
	v_fma_f32 v234, -v234, v237, v236
	v_div_fmas_f32 v234, v234, v235, v237
	v_div_fixup_f32 v231, v234, v231, 1.0
	v_mul_f32_e32 v230, v231, v230
	v_mul_f32_e32 v230, v230, v233
	v_bfe_u32 v233, v230, 16, 1
	v_add3_u32 v230, v230, v233, s5
	global_store_short_d16_hi v[120:121], v230, off offset:352
	v_lshlrev_b32_e32 v174, 16, v226
	v_mul_f32_e32 v175, 0xbfb8aa3b, v174
	v_exp_f32_e32 v175, v175
	v_mul_f32_e32 v176, v15, v232
	v_mul_f32_e32 v176, v194, v176
	v_add_f32_e32 v175, 1.0, v175
	v_div_scale_f32 v177, s[0:1], v175, v175, 1.0
	v_rcp_f32_e32 v178, v177
	s_nop 0
	v_fma_f32 v179, -v177, v178, 1.0
	v_fmac_f32_e32 v178, v179, v178
	v_div_scale_f32 v179, vcc, 1.0, v175, 1.0
	v_mul_f32_e32 v180, v179, v178
	v_fma_f32 v181, -v177, v180, v179
	v_fmac_f32_e32 v180, v181, v178
	v_fma_f32 v177, -v177, v180, v179
	v_div_fmas_f32 v177, v177, v178, v180
	v_div_fixup_f32 v175, v177, v175, 1.0
	v_mul_f32_e32 v174, v175, v174
	v_mul_f32_e32 v174, v174, v176
	v_bfe_u32 v176, v174, 16, 1
	v_add3_u32 v174, v174, v176, s5
	global_store_short_d16_hi v[120:121], v174, off offset:384
	v_lshlrev_b32_e32 v230, 16, v227
	v_mul_f32_e32 v231, 0xbfb8aa3b, v230
	v_exp_f32_e32 v231, v231
	v_mul_f32_e32 v233, v11, v232
	v_mul_f32_e32 v233, v195, v233
	v_add_f32_e32 v231, 1.0, v231
	v_div_scale_f32 v234, s[0:1], v231, v231, 1.0
	v_rcp_f32_e32 v235, v234
	s_nop 0
	v_fma_f32 v236, -v234, v235, 1.0
	v_fmac_f32_e32 v235, v236, v235
	v_div_scale_f32 v236, vcc, 1.0, v231, 1.0
	v_mul_f32_e32 v237, v236, v235
	v_fma_f32 v109, -v234, v237, v236
	v_fmac_f32_e32 v237, v109, v235
	v_fma_f32 v234, -v234, v237, v236
	v_div_fmas_f32 v234, v234, v235, v237
	v_div_fixup_f32 v231, v234, v231, 1.0
	v_mul_f32_e32 v230, v231, v230
	v_mul_f32_e32 v230, v230, v233
	v_bfe_u32 v233, v230, 16, 1
	v_add3_u32 v230, v230, v233, s5
	global_store_short_d16_hi v[120:121], v230, off offset:416
	v_lshlrev_b32_e32 v174, 16, v228
	v_mul_f32_e32 v175, 0xbfb8aa3b, v174
	v_exp_f32_e32 v175, v175
	v_mul_f32_e32 v176, v7, v232
	v_mul_f32_e32 v176, v196, v176
	v_add_f32_e32 v175, 1.0, v175
	v_div_scale_f32 v177, s[0:1], v175, v175, 1.0
	v_rcp_f32_e32 v178, v177
	s_nop 0
	v_fma_f32 v179, -v177, v178, 1.0
	v_fmac_f32_e32 v178, v179, v178
	v_div_scale_f32 v179, vcc, 1.0, v175, 1.0
	v_mul_f32_e32 v180, v179, v178
	v_fma_f32 v181, -v177, v180, v179
	v_fmac_f32_e32 v180, v181, v178
	v_fma_f32 v177, -v177, v180, v179
	v_div_fmas_f32 v177, v177, v178, v180
	v_div_fixup_f32 v175, v177, v175, 1.0
	v_mul_f32_e32 v174, v175, v174
	v_mul_f32_e32 v174, v174, v176
	v_bfe_u32 v176, v174, 16, 1
	v_add3_u32 v174, v174, v176, s5
	global_store_short_d16_hi v[120:121], v174, off offset:448
	v_lshlrev_b32_e32 v230, 16, v229
	v_mul_f32_e32 v231, 0xbfb8aa3b, v230
	v_exp_f32_e32 v231, v231
	v_mul_f32_e32 v233, v3, v232
	v_mul_f32_e32 v233, v197, v233
	v_add_f32_e32 v231, 1.0, v231
	v_div_scale_f32 v234, s[0:1], v231, v231, 1.0
	v_rcp_f32_e32 v235, v234
	s_nop 0
	v_fma_f32 v236, -v234, v235, 1.0
	v_fmac_f32_e32 v235, v236, v235
	v_div_scale_f32 v236, vcc, 1.0, v231, 1.0
	v_mul_f32_e32 v237, v236, v235
	v_fma_f32 v109, -v234, v237, v236
	v_fmac_f32_e32 v237, v109, v235
	v_fma_f32 v234, -v234, v237, v236
	v_div_fmas_f32 v234, v234, v235, v237
	v_div_fixup_f32 v231, v234, v231, 1.0
	v_mul_f32_e32 v230, v231, v230
	v_mul_f32_e32 v230, v230, v233
	v_bfe_u32 v233, v230, 16, 1
	v_add3_u32 v230, v230, v233, s5
	global_store_short_d16_hi v[120:121], v230, off offset:480
	global_load_ushort v214, v[118:119], off offset:0
	global_load_ushort v215, v[118:119], off offset:32
	global_load_ushort v216, v[118:119], off offset:64
	global_load_ushort v217, v[118:119], off offset:96
	global_load_ushort v218, v[118:119], off offset:128
	global_load_ushort v219, v[118:119], off offset:160
	global_load_ushort v220, v[118:119], off offset:192
	global_load_ushort v221, v[118:119], off offset:224
	global_load_ushort v222, v[118:119], off offset:256
	global_load_ushort v223, v[118:119], off offset:288
	global_load_ushort v224, v[118:119], off offset:320
	global_load_ushort v225, v[118:119], off offset:352
	global_load_ushort v226, v[118:119], off offset:384
	global_load_ushort v227, v[118:119], off offset:416
	global_load_ushort v228, v[118:119], off offset:448
	global_load_ushort v229, v[118:119], off offset:480
	v_mov_b32_e32 v120, v114
	v_mov_b32_e32 v121, v115
	s_waitcnt vmcnt(32)
	v_lshlrev_b32_e32 v198, 16, v198
	v_add_f32_e32 v64, v64, v198
	v_add_f32_e32 v230, 0, v64
	v_lshlrev_b32_e32 v199, 16, v199
	v_add_f32_e32 v60, v60, v199
	v_add_f32_e32 v230, v230, v60
	v_lshlrev_b32_e32 v200, 16, v200
	v_add_f32_e32 v56, v56, v200
	v_add_f32_e32 v230, v230, v56
	v_lshlrev_b32_e32 v201, 16, v201
	v_add_f32_e32 v52, v52, v201
	v_add_f32_e32 v230, v230, v52
	v_lshlrev_b32_e32 v202, 16, v202
	v_add_f32_e32 v48, v48, v202
	v_add_f32_e32 v230, v230, v48
	v_lshlrev_b32_e32 v203, 16, v203
	v_add_f32_e32 v44, v44, v203
	v_add_f32_e32 v230, v230, v44
	v_lshlrev_b32_e32 v204, 16, v204
	v_add_f32_e32 v40, v40, v204
	v_add_f32_e32 v230, v230, v40
	v_lshlrev_b32_e32 v205, 16, v205
	v_add_f32_e32 v36, v36, v205
	v_add_f32_e32 v230, v230, v36
	v_lshlrev_b32_e32 v206, 16, v206
	v_add_f32_e32 v32, v32, v206
	v_add_f32_e32 v230, v230, v32
	v_lshlrev_b32_e32 v207, 16, v207
	v_add_f32_e32 v28, v28, v207
	v_add_f32_e32 v230, v230, v28
	v_lshlrev_b32_e32 v208, 16, v208
	v_add_f32_e32 v24, v24, v208
	v_add_f32_e32 v230, v230, v24
	v_lshlrev_b32_e32 v209, 16, v209
	v_add_f32_e32 v20, v20, v209
	v_add_f32_e32 v230, v230, v20
	v_lshlrev_b32_e32 v210, 16, v210
	v_add_f32_e32 v16, v16, v210
	v_add_f32_e32 v230, v230, v16
	v_lshlrev_b32_e32 v211, 16, v211
	v_add_f32_e32 v12, v12, v211
	v_add_f32_e32 v230, v230, v12
	v_lshlrev_b32_e32 v212, 16, v212
	v_add_f32_e32 v8, v8, v212
	v_add_f32_e32 v230, v230, v8
	v_lshlrev_b32_e32 v213, 16, v213
	v_add_f32_e32 v4, v4, v213
	v_add_f32_e32 v230, v230, v4
	v_or_b32_e32 v116, 3, v112
	v_mov_b32_e32 v117, s11
	v_lshlrev_b64 v[114:115], 12, v[116:117]
	v_lshl_add_u64 v[114:115], s[78:79], 0, v[114:115]
	v_lshl_add_u64 v[114:115], v[114:115], 0, s[96:97]
	v_lshl_add_u64 v[114:115], v[114:115], 0, v[110:111]
	v_lshl_add_u64 v[114:115], v[114:115], 0, s[80:81]
	v_lshlrev_b64 v[118:119], 13, v[116:117]
	v_lshl_add_u64 v[118:119], s[92:93], 0, v[118:119]
	v_lshl_add_u64 v[118:119], v[118:119], 0, s[96:97]
	v_lshl_add_u64 v[118:119], v[118:119], 0, v[110:111]
	v_lshl_add_u64 v[118:119], v[118:119], 0, s[90:91]
	global_load_ushort v198, v[114:115], off offset:0
	global_load_ushort v199, v[114:115], off offset:32
	global_load_ushort v200, v[114:115], off offset:64
	global_load_ushort v201, v[114:115], off offset:96
	global_load_ushort v202, v[114:115], off offset:128
	global_load_ushort v203, v[114:115], off offset:160
	global_load_ushort v204, v[114:115], off offset:192
	global_load_ushort v205, v[114:115], off offset:224
	global_load_ushort v206, v[114:115], off offset:256
	global_load_ushort v207, v[114:115], off offset:288
	global_load_ushort v208, v[114:115], off offset:320
	global_load_ushort v209, v[114:115], off offset:352
	global_load_ushort v210, v[114:115], off offset:384
	global_load_ushort v211, v[114:115], off offset:416
	global_load_ushort v212, v[114:115], off offset:448
	global_load_ushort v213, v[114:115], off offset:480
	s_nop 1
	v_add_f32_dpp v230, v230, v230 row_ror:8 row_mask:0xf bank_mask:0xf bound_ctrl:1
	s_nop 1
	v_add_f32_dpp v230, v230, v230 row_ror:4 row_mask:0xf bank_mask:0xf bound_ctrl:1
	s_nop 1
	v_add_f32_dpp v230, v230, v230 row_ror:2 row_mask:0xf bank_mask:0xf bound_ctrl:1
	s_nop 1
	v_add_f32_dpp v230, v230, v230 row_ror:1 row_mask:0xf bank_mask:0xf bound_ctrl:1
	v_fmac_f32_e32 v60, 0xbb800000, v230
	v_mul_f32_e32 v231, v60, v60
	v_fmac_f32_e32 v64, 0xbb800000, v230
	v_fmac_f32_e32 v231, v64, v64
	v_fmac_f32_e32 v56, 0xbb800000, v230
	v_fmac_f32_e32 v231, v56, v56
	v_fmac_f32_e32 v52, 0xbb800000, v230
	v_fmac_f32_e32 v231, v52, v52
	v_fmac_f32_e32 v48, 0xbb800000, v230
	v_fmac_f32_e32 v231, v48, v48
	v_fmac_f32_e32 v44, 0xbb800000, v230
	v_fmac_f32_e32 v231, v44, v44
	v_fmac_f32_e32 v40, 0xbb800000, v230
	v_fmac_f32_e32 v231, v40, v40
	v_fmac_f32_e32 v36, 0xbb800000, v230
	v_fmac_f32_e32 v231, v36, v36
	v_fmac_f32_e32 v32, 0xbb800000, v230
	v_fmac_f32_e32 v231, v32, v32
	v_fmac_f32_e32 v28, 0xbb800000, v230
	v_fmac_f32_e32 v231, v28, v28
	v_fmac_f32_e32 v24, 0xbb800000, v230
	v_fmac_f32_e32 v231, v24, v24
	v_fmac_f32_e32 v20, 0xbb800000, v230
	v_fmac_f32_e32 v231, v20, v20
	v_fmac_f32_e32 v16, 0xbb800000, v230
	v_fmac_f32_e32 v231, v16, v16
	v_fmac_f32_e32 v12, 0xbb800000, v230
	v_fmac_f32_e32 v231, v12, v12
	v_fmac_f32_e32 v8, 0xbb800000, v230
	v_fmac_f32_e32 v231, v8, v8
	v_fmac_f32_e32 v4, 0xbb800000, v230
	v_fmac_f32_e32 v231, v4, v4
	s_nop 1
	v_add_f32_dpp v232, v231, v231 row_ror:8 row_mask:0xf bank_mask:0xf bound_ctrl:1
	s_nop 1
	v_add_f32_dpp v232, v232, v232 row_ror:4 row_mask:0xf bank_mask:0xf bound_ctrl:1
	s_nop 1
	v_add_f32_dpp v232, v232, v232 row_ror:2 row_mask:0xf bank_mask:0xf bound_ctrl:1
	s_nop 1
	v_add_f32_dpp v232, v232, v232 row_ror:1 row_mask:0xf bank_mask:0xf bound_ctrl:1
	v_fmamk_f32 v232, v232, 0x3b800000, v169
	v_cmp_gt_f32_e32 vcc, s7, v232
	v_mul_f32_e32 v233, 0x4f800000, v232
	s_nop 0
	v_cndmask_b32_e32 v232, v232, v233, vcc
	v_sqrt_f32_e32 v233, v232
	s_nop 0
	v_add_u32_e32 v234, -1, v233
	v_fma_f32 v235, -v234, v233, v232
	v_cmp_ge_f32_e64 s[0:1], 0, v235
	v_add_u32_e32 v235, 1, v233
	s_nop 0
	v_cndmask_b32_e64 v234, v233, v234, s[0:1]
	v_fma_f32 v233, -v235, v233, v232
	v_cmp_lt_f32_e64 s[0:1], 0, v233
	s_nop 1
	v_cndmask_b32_e64 v233, v234, v235, s[0:1]
	v_mul_f32_e32 v234, 0x37800000, v233
	s_nop 0
	v_cndmask_b32_e32 v233, v233, v234, vcc
	v_cmp_class_f32_e32 vcc, v232, v170
	s_nop 1
	v_cndmask_b32_e32 v232, v233, v232, vcc
	v_div_scale_f32 v233, s[0:1], v232, v232, 1.0
	v_rcp_f32_e32 v234, v233
	s_nop 0
	v_fma_f32 v235, -v233, v234, 1.0
	v_fmac_f32_e32 v234, v235, v234
	v_div_scale_f32 v235, vcc, 1.0, v232, 1.0
	v_mul_f32_e32 v236, v235, v234
	v_fma_f32 v237, -v233, v236, v235
	v_fmac_f32_e32 v236, v237, v234
	v_fma_f32 v233, -v233, v236, v235
	v_div_fmas_f32 v233, v233, v234, v236
	v_div_fixup_f32 v232, v233, v232, 1.0
	s_waitcnt vmcnt(16)
	v_lshlrev_b32_e32 v174, 16, v214
	v_mul_f32_e32 v175, 0xbfb8aa3b, v174
	v_exp_f32_e32 v175, v175
	v_mul_f32_e32 v176, v64, v232
	v_mul_f32_e32 v176, v182, v176
	v_add_f32_e32 v175, 1.0, v175
	v_div_scale_f32 v177, s[0:1], v175, v175, 1.0
	v_rcp_f32_e32 v178, v177
	s_nop 0
	v_fma_f32 v179, -v177, v178, 1.0
	v_fmac_f32_e32 v178, v179, v178
	v_div_scale_f32 v179, vcc, 1.0, v175, 1.0
	v_mul_f32_e32 v180, v179, v178
	v_fma_f32 v181, -v177, v180, v179
	v_fmac_f32_e32 v180, v181, v178
	v_fma_f32 v177, -v177, v180, v179
	v_div_fmas_f32 v177, v177, v178, v180
	v_div_fixup_f32 v175, v177, v175, 1.0
	v_mul_f32_e32 v174, v175, v174
	v_mul_f32_e32 v174, v174, v176
	v_bfe_u32 v176, v174, 16, 1
	v_add3_u32 v174, v174, v176, s5
	global_store_short_d16_hi v[120:121], v174, off offset:0
	v_lshlrev_b32_e32 v230, 16, v215
	v_mul_f32_e32 v231, 0xbfb8aa3b, v230
	v_exp_f32_e32 v231, v231
	v_mul_f32_e32 v233, v60, v232
	v_mul_f32_e32 v233, v183, v233
	v_add_f32_e32 v231, 1.0, v231
	v_div_scale_f32 v234, s[0:1], v231, v231, 1.0
	v_rcp_f32_e32 v235, v234
	s_nop 0
	v_fma_f32 v236, -v234, v235, 1.0
	v_fmac_f32_e32 v235, v236, v235
	v_div_scale_f32 v236, vcc, 1.0, v231, 1.0
	v_mul_f32_e32 v237, v236, v235
	v_fma_f32 v109, -v234, v237, v236
	v_fmac_f32_e32 v237, v109, v235
	v_fma_f32 v234, -v234, v237, v236
	v_div_fmas_f32 v234, v234, v235, v237
	v_div_fixup_f32 v231, v234, v231, 1.0
	v_mul_f32_e32 v230, v231, v230
	v_mul_f32_e32 v230, v230, v233
	v_bfe_u32 v233, v230, 16, 1
	v_add3_u32 v230, v230, v233, s5
	global_store_short_d16_hi v[120:121], v230, off offset:32
	v_lshlrev_b32_e32 v174, 16, v216
	v_mul_f32_e32 v175, 0xbfb8aa3b, v174
	v_exp_f32_e32 v175, v175
	v_mul_f32_e32 v176, v56, v232
	v_mul_f32_e32 v176, v184, v176
	v_add_f32_e32 v175, 1.0, v175
	v_div_scale_f32 v177, s[0:1], v175, v175, 1.0
	v_rcp_f32_e32 v178, v177
	s_nop 0
	v_fma_f32 v179, -v177, v178, 1.0
	v_fmac_f32_e32 v178, v179, v178
	v_div_scale_f32 v179, vcc, 1.0, v175, 1.0
	v_mul_f32_e32 v180, v179, v178
	v_fma_f32 v181, -v177, v180, v179
	v_fmac_f32_e32 v180, v181, v178
	v_fma_f32 v177, -v177, v180, v179
	v_div_fmas_f32 v177, v177, v178, v180
	v_div_fixup_f32 v175, v177, v175, 1.0
	v_mul_f32_e32 v174, v175, v174
	v_mul_f32_e32 v174, v174, v176
	v_bfe_u32 v176, v174, 16, 1
	v_add3_u32 v174, v174, v176, s5
	global_store_short_d16_hi v[120:121], v174, off offset:64
	v_lshlrev_b32_e32 v230, 16, v217
	v_mul_f32_e32 v231, 0xbfb8aa3b, v230
	v_exp_f32_e32 v231, v231
	v_mul_f32_e32 v233, v52, v232
	v_mul_f32_e32 v233, v185, v233
	v_add_f32_e32 v231, 1.0, v231
	v_div_scale_f32 v234, s[0:1], v231, v231, 1.0
	v_rcp_f32_e32 v235, v234
	s_nop 0
	v_fma_f32 v236, -v234, v235, 1.0
	v_fmac_f32_e32 v235, v236, v235
	v_div_scale_f32 v236, vcc, 1.0, v231, 1.0
	v_mul_f32_e32 v237, v236, v235
	v_fma_f32 v109, -v234, v237, v236
	v_fmac_f32_e32 v237, v109, v235
	v_fma_f32 v234, -v234, v237, v236
	v_div_fmas_f32 v234, v234, v235, v237
	v_div_fixup_f32 v231, v234, v231, 1.0
	v_mul_f32_e32 v230, v231, v230
	v_mul_f32_e32 v230, v230, v233
	v_bfe_u32 v233, v230, 16, 1
	v_add3_u32 v230, v230, v233, s5
	global_store_short_d16_hi v[120:121], v230, off offset:96
	v_lshlrev_b32_e32 v174, 16, v218
	v_mul_f32_e32 v175, 0xbfb8aa3b, v174
	v_exp_f32_e32 v175, v175
	v_mul_f32_e32 v176, v48, v232
	v_mul_f32_e32 v176, v186, v176
	v_add_f32_e32 v175, 1.0, v175
	v_div_scale_f32 v177, s[0:1], v175, v175, 1.0
	v_rcp_f32_e32 v178, v177
	s_nop 0
	v_fma_f32 v179, -v177, v178, 1.0
	v_fmac_f32_e32 v178, v179, v178
	v_div_scale_f32 v179, vcc, 1.0, v175, 1.0
	v_mul_f32_e32 v180, v179, v178
	v_fma_f32 v181, -v177, v180, v179
	v_fmac_f32_e32 v180, v181, v178
	v_fma_f32 v177, -v177, v180, v179
	v_div_fmas_f32 v177, v177, v178, v180
	v_div_fixup_f32 v175, v177, v175, 1.0
	v_mul_f32_e32 v174, v175, v174
	v_mul_f32_e32 v174, v174, v176
	v_bfe_u32 v176, v174, 16, 1
	v_add3_u32 v174, v174, v176, s5
	global_store_short_d16_hi v[120:121], v174, off offset:128
	v_lshlrev_b32_e32 v230, 16, v219
	v_mul_f32_e32 v231, 0xbfb8aa3b, v230
	v_exp_f32_e32 v231, v231
	v_mul_f32_e32 v233, v44, v232
	v_mul_f32_e32 v233, v187, v233
	v_add_f32_e32 v231, 1.0, v231
	v_div_scale_f32 v234, s[0:1], v231, v231, 1.0
	v_rcp_f32_e32 v235, v234
	s_nop 0
	v_fma_f32 v236, -v234, v235, 1.0
	v_fmac_f32_e32 v235, v236, v235
	v_div_scale_f32 v236, vcc, 1.0, v231, 1.0
	v_mul_f32_e32 v237, v236, v235
	v_fma_f32 v109, -v234, v237, v236
	v_fmac_f32_e32 v237, v109, v235
	v_fma_f32 v234, -v234, v237, v236
	v_div_fmas_f32 v234, v234, v235, v237
	v_div_fixup_f32 v231, v234, v231, 1.0
	v_mul_f32_e32 v230, v231, v230
	v_mul_f32_e32 v230, v230, v233
	v_bfe_u32 v233, v230, 16, 1
	v_add3_u32 v230, v230, v233, s5
	global_store_short_d16_hi v[120:121], v230, off offset:160
	v_lshlrev_b32_e32 v174, 16, v220
	v_mul_f32_e32 v175, 0xbfb8aa3b, v174
	v_exp_f32_e32 v175, v175
	v_mul_f32_e32 v176, v40, v232
	v_mul_f32_e32 v176, v188, v176
	v_add_f32_e32 v175, 1.0, v175
	v_div_scale_f32 v177, s[0:1], v175, v175, 1.0
	v_rcp_f32_e32 v178, v177
	s_nop 0
	v_fma_f32 v179, -v177, v178, 1.0
	v_fmac_f32_e32 v178, v179, v178
	v_div_scale_f32 v179, vcc, 1.0, v175, 1.0
	v_mul_f32_e32 v180, v179, v178
	v_fma_f32 v181, -v177, v180, v179
	v_fmac_f32_e32 v180, v181, v178
	v_fma_f32 v177, -v177, v180, v179
	v_div_fmas_f32 v177, v177, v178, v180
	v_div_fixup_f32 v175, v177, v175, 1.0
	v_mul_f32_e32 v174, v175, v174
	v_mul_f32_e32 v174, v174, v176
	v_bfe_u32 v176, v174, 16, 1
	v_add3_u32 v174, v174, v176, s5
	global_store_short_d16_hi v[120:121], v174, off offset:192
	v_lshlrev_b32_e32 v230, 16, v221
	v_mul_f32_e32 v231, 0xbfb8aa3b, v230
	v_exp_f32_e32 v231, v231
	v_mul_f32_e32 v233, v36, v232
	v_mul_f32_e32 v233, v189, v233
	v_add_f32_e32 v231, 1.0, v231
	v_div_scale_f32 v234, s[0:1], v231, v231, 1.0
	v_rcp_f32_e32 v235, v234
	s_nop 0
	v_fma_f32 v236, -v234, v235, 1.0
	v_fmac_f32_e32 v235, v236, v235
	v_div_scale_f32 v236, vcc, 1.0, v231, 1.0
	v_mul_f32_e32 v237, v236, v235
	v_fma_f32 v109, -v234, v237, v236
	v_fmac_f32_e32 v237, v109, v235
	v_fma_f32 v234, -v234, v237, v236
	v_div_fmas_f32 v234, v234, v235, v237
	v_div_fixup_f32 v231, v234, v231, 1.0
	v_mul_f32_e32 v230, v231, v230
	v_mul_f32_e32 v230, v230, v233
	v_bfe_u32 v233, v230, 16, 1
	v_add3_u32 v230, v230, v233, s5
	global_store_short_d16_hi v[120:121], v230, off offset:224
	v_lshlrev_b32_e32 v174, 16, v222
	v_mul_f32_e32 v175, 0xbfb8aa3b, v174
	v_exp_f32_e32 v175, v175
	v_mul_f32_e32 v176, v32, v232
	v_mul_f32_e32 v176, v190, v176
	v_add_f32_e32 v175, 1.0, v175
	v_div_scale_f32 v177, s[0:1], v175, v175, 1.0
	v_rcp_f32_e32 v178, v177
	s_nop 0
	v_fma_f32 v179, -v177, v178, 1.0
	v_fmac_f32_e32 v178, v179, v178
	v_div_scale_f32 v179, vcc, 1.0, v175, 1.0
	v_mul_f32_e32 v180, v179, v178
	v_fma_f32 v181, -v177, v180, v179
	v_fmac_f32_e32 v180, v181, v178
	v_fma_f32 v177, -v177, v180, v179
	v_div_fmas_f32 v177, v177, v178, v180
	v_div_fixup_f32 v175, v177, v175, 1.0
	v_mul_f32_e32 v174, v175, v174
	v_mul_f32_e32 v174, v174, v176
	v_bfe_u32 v176, v174, 16, 1
	v_add3_u32 v174, v174, v176, s5
	global_store_short_d16_hi v[120:121], v174, off offset:256
	v_lshlrev_b32_e32 v230, 16, v223
	v_mul_f32_e32 v231, 0xbfb8aa3b, v230
	v_exp_f32_e32 v231, v231
	v_mul_f32_e32 v233, v28, v232
	v_mul_f32_e32 v233, v191, v233
	v_add_f32_e32 v231, 1.0, v231
	v_div_scale_f32 v234, s[0:1], v231, v231, 1.0
	v_rcp_f32_e32 v235, v234
	s_nop 0
	v_fma_f32 v236, -v234, v235, 1.0
	v_fmac_f32_e32 v235, v236, v235
	v_div_scale_f32 v236, vcc, 1.0, v231, 1.0
	v_mul_f32_e32 v237, v236, v235
	v_fma_f32 v109, -v234, v237, v236
	v_fmac_f32_e32 v237, v109, v235
	v_fma_f32 v234, -v234, v237, v236
	v_div_fmas_f32 v234, v234, v235, v237
	v_div_fixup_f32 v231, v234, v231, 1.0
	v_mul_f32_e32 v230, v231, v230
	v_mul_f32_e32 v230, v230, v233
	v_bfe_u32 v233, v230, 16, 1
	v_add3_u32 v230, v230, v233, s5
	global_store_short_d16_hi v[120:121], v230, off offset:288
	v_lshlrev_b32_e32 v174, 16, v224
	v_mul_f32_e32 v175, 0xbfb8aa3b, v174
	v_exp_f32_e32 v175, v175
	v_mul_f32_e32 v176, v24, v232
	v_mul_f32_e32 v176, v192, v176
	v_add_f32_e32 v175, 1.0, v175
	v_div_scale_f32 v177, s[0:1], v175, v175, 1.0
	v_rcp_f32_e32 v178, v177
	s_nop 0
	v_fma_f32 v179, -v177, v178, 1.0
	v_fmac_f32_e32 v178, v179, v178
	v_div_scale_f32 v179, vcc, 1.0, v175, 1.0
	v_mul_f32_e32 v180, v179, v178
	v_fma_f32 v181, -v177, v180, v179
	v_fmac_f32_e32 v180, v181, v178
	v_fma_f32 v177, -v177, v180, v179
	v_div_fmas_f32 v177, v177, v178, v180
	v_div_fixup_f32 v175, v177, v175, 1.0
	v_mul_f32_e32 v174, v175, v174
	v_mul_f32_e32 v174, v174, v176
	v_bfe_u32 v176, v174, 16, 1
	v_add3_u32 v174, v174, v176, s5
	global_store_short_d16_hi v[120:121], v174, off offset:320
	v_lshlrev_b32_e32 v230, 16, v225
	v_mul_f32_e32 v231, 0xbfb8aa3b, v230
	v_exp_f32_e32 v231, v231
	v_mul_f32_e32 v233, v20, v232
	v_mul_f32_e32 v233, v193, v233
	v_add_f32_e32 v231, 1.0, v231
	v_div_scale_f32 v234, s[0:1], v231, v231, 1.0
	v_rcp_f32_e32 v235, v234
	s_nop 0
	v_fma_f32 v236, -v234, v235, 1.0
	v_fmac_f32_e32 v235, v236, v235
	v_div_scale_f32 v236, vcc, 1.0, v231, 1.0
	v_mul_f32_e32 v237, v236, v235
	v_fma_f32 v109, -v234, v237, v236
	v_fmac_f32_e32 v237, v109, v235
	v_fma_f32 v234, -v234, v237, v236
	v_div_fmas_f32 v234, v234, v235, v237
	v_div_fixup_f32 v231, v234, v231, 1.0
	v_mul_f32_e32 v230, v231, v230
	v_mul_f32_e32 v230, v230, v233
	v_bfe_u32 v233, v230, 16, 1
	v_add3_u32 v230, v230, v233, s5
	global_store_short_d16_hi v[120:121], v230, off offset:352
	v_lshlrev_b32_e32 v174, 16, v226
	v_mul_f32_e32 v175, 0xbfb8aa3b, v174
	v_exp_f32_e32 v175, v175
	v_mul_f32_e32 v176, v16, v232
	v_mul_f32_e32 v176, v194, v176
	v_add_f32_e32 v175, 1.0, v175
	v_div_scale_f32 v177, s[0:1], v175, v175, 1.0
	v_rcp_f32_e32 v178, v177
	s_nop 0
	v_fma_f32 v179, -v177, v178, 1.0
	v_fmac_f32_e32 v178, v179, v178
	v_div_scale_f32 v179, vcc, 1.0, v175, 1.0
	v_mul_f32_e32 v180, v179, v178
	v_fma_f32 v181, -v177, v180, v179
	v_fmac_f32_e32 v180, v181, v178
	v_fma_f32 v177, -v177, v180, v179
	v_div_fmas_f32 v177, v177, v178, v180
	v_div_fixup_f32 v175, v177, v175, 1.0
	v_mul_f32_e32 v174, v175, v174
	v_mul_f32_e32 v174, v174, v176
	v_bfe_u32 v176, v174, 16, 1
	v_add3_u32 v174, v174, v176, s5
	global_store_short_d16_hi v[120:121], v174, off offset:384
	v_lshlrev_b32_e32 v230, 16, v227
	v_mul_f32_e32 v231, 0xbfb8aa3b, v230
	v_exp_f32_e32 v231, v231
	v_mul_f32_e32 v233, v12, v232
	v_mul_f32_e32 v233, v195, v233
	v_add_f32_e32 v231, 1.0, v231
	v_div_scale_f32 v234, s[0:1], v231, v231, 1.0
	v_rcp_f32_e32 v235, v234
	s_nop 0
	v_fma_f32 v236, -v234, v235, 1.0
	v_fmac_f32_e32 v235, v236, v235
	v_div_scale_f32 v236, vcc, 1.0, v231, 1.0
	v_mul_f32_e32 v237, v236, v235
	v_fma_f32 v109, -v234, v237, v236
	v_fmac_f32_e32 v237, v109, v235
	v_fma_f32 v234, -v234, v237, v236
	v_div_fmas_f32 v234, v234, v235, v237
	v_div_fixup_f32 v231, v234, v231, 1.0
	v_mul_f32_e32 v230, v231, v230
	v_mul_f32_e32 v230, v230, v233
	v_bfe_u32 v233, v230, 16, 1
	v_add3_u32 v230, v230, v233, s5
	global_store_short_d16_hi v[120:121], v230, off offset:416
	v_lshlrev_b32_e32 v174, 16, v228
	v_mul_f32_e32 v175, 0xbfb8aa3b, v174
	v_exp_f32_e32 v175, v175
	v_mul_f32_e32 v176, v8, v232
	v_mul_f32_e32 v176, v196, v176
	v_add_f32_e32 v175, 1.0, v175
	v_div_scale_f32 v177, s[0:1], v175, v175, 1.0
	v_rcp_f32_e32 v178, v177
	s_nop 0
	v_fma_f32 v179, -v177, v178, 1.0
	v_fmac_f32_e32 v178, v179, v178
	v_div_scale_f32 v179, vcc, 1.0, v175, 1.0
	v_mul_f32_e32 v180, v179, v178
	v_fma_f32 v181, -v177, v180, v179
	v_fmac_f32_e32 v180, v181, v178
	v_fma_f32 v177, -v177, v180, v179
	v_div_fmas_f32 v177, v177, v178, v180
	v_div_fixup_f32 v175, v177, v175, 1.0
	v_mul_f32_e32 v174, v175, v174
	v_mul_f32_e32 v174, v174, v176
	v_bfe_u32 v176, v174, 16, 1
	v_add3_u32 v174, v174, v176, s5
	global_store_short_d16_hi v[120:121], v174, off offset:448
	v_lshlrev_b32_e32 v230, 16, v229
	v_mul_f32_e32 v231, 0xbfb8aa3b, v230
	v_exp_f32_e32 v231, v231
	v_mul_f32_e32 v233, v4, v232
	v_mul_f32_e32 v233, v197, v233
	v_add_f32_e32 v231, 1.0, v231
	v_div_scale_f32 v234, s[0:1], v231, v231, 1.0
	v_rcp_f32_e32 v235, v234
	s_nop 0
	v_fma_f32 v236, -v234, v235, 1.0
	v_fmac_f32_e32 v235, v236, v235
	v_div_scale_f32 v236, vcc, 1.0, v231, 1.0
	v_mul_f32_e32 v237, v236, v235
	v_fma_f32 v109, -v234, v237, v236
	v_fmac_f32_e32 v237, v109, v235
	v_fma_f32 v234, -v234, v237, v236
	v_div_fmas_f32 v234, v234, v235, v237
	v_div_fixup_f32 v231, v234, v231, 1.0
	v_mul_f32_e32 v230, v231, v230
	v_mul_f32_e32 v230, v230, v233
	v_bfe_u32 v233, v230, 16, 1
	v_add3_u32 v230, v230, v233, s5
	global_store_short_d16_hi v[120:121], v230, off offset:480
	global_load_ushort v214, v[118:119], off offset:0
	global_load_ushort v215, v[118:119], off offset:32
	global_load_ushort v216, v[118:119], off offset:64
	global_load_ushort v217, v[118:119], off offset:96
	global_load_ushort v218, v[118:119], off offset:128
	global_load_ushort v219, v[118:119], off offset:160
	global_load_ushort v220, v[118:119], off offset:192
	global_load_ushort v221, v[118:119], off offset:224
	global_load_ushort v222, v[118:119], off offset:256
	global_load_ushort v223, v[118:119], off offset:288
	global_load_ushort v224, v[118:119], off offset:320
	global_load_ushort v225, v[118:119], off offset:352
	global_load_ushort v226, v[118:119], off offset:384
	global_load_ushort v227, v[118:119], off offset:416
	global_load_ushort v228, v[118:119], off offset:448
	global_load_ushort v229, v[118:119], off offset:480
	v_mov_b32_e32 v120, v114
	v_mov_b32_e32 v121, v115
	s_waitcnt vmcnt(32)
	v_lshlrev_b32_e32 v198, 16, v198
	v_add_f32_e32 v65, v65, v198
	v_add_f32_e32 v230, 0, v65
	v_lshlrev_b32_e32 v199, 16, v199
	v_add_f32_e32 v61, v61, v199
	v_add_f32_e32 v230, v230, v61
	v_lshlrev_b32_e32 v200, 16, v200
	v_add_f32_e32 v57, v57, v200
	v_add_f32_e32 v230, v230, v57
	v_lshlrev_b32_e32 v201, 16, v201
	v_add_f32_e32 v53, v53, v201
	v_add_f32_e32 v230, v230, v53
	v_lshlrev_b32_e32 v202, 16, v202
	v_add_f32_e32 v49, v49, v202
	v_add_f32_e32 v230, v230, v49
	v_lshlrev_b32_e32 v203, 16, v203
	v_add_f32_e32 v45, v45, v203
	v_add_f32_e32 v230, v230, v45
	v_lshlrev_b32_e32 v204, 16, v204
	v_add_f32_e32 v41, v41, v204
	v_add_f32_e32 v230, v230, v41
	v_lshlrev_b32_e32 v205, 16, v205
	v_add_f32_e32 v37, v37, v205
	v_add_f32_e32 v230, v230, v37
	v_lshlrev_b32_e32 v206, 16, v206
	v_add_f32_e32 v33, v33, v206
	v_add_f32_e32 v230, v230, v33
	v_lshlrev_b32_e32 v207, 16, v207
	v_add_f32_e32 v29, v29, v207
	v_add_f32_e32 v230, v230, v29
	v_lshlrev_b32_e32 v208, 16, v208
	v_add_f32_e32 v25, v25, v208
	v_add_f32_e32 v230, v230, v25
	v_lshlrev_b32_e32 v209, 16, v209
	v_add_f32_e32 v21, v21, v209
	v_add_f32_e32 v230, v230, v21
	v_lshlrev_b32_e32 v210, 16, v210
	v_add_f32_e32 v17, v17, v210
	v_add_f32_e32 v230, v230, v17
	v_lshlrev_b32_e32 v211, 16, v211
	v_add_f32_e32 v13, v13, v211
	v_add_f32_e32 v230, v230, v13
	v_lshlrev_b32_e32 v212, 16, v212
	v_add_f32_e32 v9, v9, v212
	v_add_f32_e32 v230, v230, v9
	v_lshlrev_b32_e32 v213, 16, v213
	v_add_f32_e32 v5, v5, v213
	v_add_f32_e32 v230, v230, v5
	s_nop 1
	v_add_f32_dpp v230, v230, v230 row_ror:8 row_mask:0xf bank_mask:0xf bound_ctrl:1
	s_nop 1
	v_add_f32_dpp v230, v230, v230 row_ror:4 row_mask:0xf bank_mask:0xf bound_ctrl:1
	s_nop 1
	v_add_f32_dpp v230, v230, v230 row_ror:2 row_mask:0xf bank_mask:0xf bound_ctrl:1
	s_nop 1
	v_add_f32_dpp v230, v230, v230 row_ror:1 row_mask:0xf bank_mask:0xf bound_ctrl:1
	v_fmac_f32_e32 v61, 0xbb800000, v230
	v_mul_f32_e32 v231, v61, v61
	v_fmac_f32_e32 v65, 0xbb800000, v230
	v_fmac_f32_e32 v231, v65, v65
	v_fmac_f32_e32 v57, 0xbb800000, v230
	v_fmac_f32_e32 v231, v57, v57
	v_fmac_f32_e32 v53, 0xbb800000, v230
	v_fmac_f32_e32 v231, v53, v53
	v_fmac_f32_e32 v49, 0xbb800000, v230
	v_fmac_f32_e32 v231, v49, v49
	v_fmac_f32_e32 v45, 0xbb800000, v230
	v_fmac_f32_e32 v231, v45, v45
	v_fmac_f32_e32 v41, 0xbb800000, v230
	v_fmac_f32_e32 v231, v41, v41
	v_fmac_f32_e32 v37, 0xbb800000, v230
	v_fmac_f32_e32 v231, v37, v37
	v_fmac_f32_e32 v33, 0xbb800000, v230
	v_fmac_f32_e32 v231, v33, v33
	v_fmac_f32_e32 v29, 0xbb800000, v230
	v_fmac_f32_e32 v231, v29, v29
	v_fmac_f32_e32 v25, 0xbb800000, v230
	v_fmac_f32_e32 v231, v25, v25
	v_fmac_f32_e32 v21, 0xbb800000, v230
	v_fmac_f32_e32 v231, v21, v21
	v_fmac_f32_e32 v17, 0xbb800000, v230
	v_fmac_f32_e32 v231, v17, v17
	v_fmac_f32_e32 v13, 0xbb800000, v230
	v_fmac_f32_e32 v231, v13, v13
	v_fmac_f32_e32 v9, 0xbb800000, v230
	v_fmac_f32_e32 v231, v9, v9
	v_fmac_f32_e32 v5, 0xbb800000, v230
	v_fmac_f32_e32 v231, v5, v5
	s_nop 1
	v_add_f32_dpp v232, v231, v231 row_ror:8 row_mask:0xf bank_mask:0xf bound_ctrl:1
	s_nop 1
	v_add_f32_dpp v232, v232, v232 row_ror:4 row_mask:0xf bank_mask:0xf bound_ctrl:1
	s_nop 1
	v_add_f32_dpp v232, v232, v232 row_ror:2 row_mask:0xf bank_mask:0xf bound_ctrl:1
	s_nop 1
	v_add_f32_dpp v232, v232, v232 row_ror:1 row_mask:0xf bank_mask:0xf bound_ctrl:1
	v_fmamk_f32 v232, v232, 0x3b800000, v169
	v_cmp_gt_f32_e32 vcc, s7, v232
	v_mul_f32_e32 v233, 0x4f800000, v232
	s_nop 0
	v_cndmask_b32_e32 v232, v232, v233, vcc
	v_sqrt_f32_e32 v233, v232
	s_nop 0
	v_add_u32_e32 v234, -1, v233
	v_fma_f32 v235, -v234, v233, v232
	v_cmp_ge_f32_e64 s[0:1], 0, v235
	v_add_u32_e32 v235, 1, v233
	s_nop 0
	v_cndmask_b32_e64 v234, v233, v234, s[0:1]
	v_fma_f32 v233, -v235, v233, v232
	v_cmp_lt_f32_e64 s[0:1], 0, v233
	s_nop 1
	v_cndmask_b32_e64 v233, v234, v235, s[0:1]
	v_mul_f32_e32 v234, 0x37800000, v233
	s_nop 0
	v_cndmask_b32_e32 v233, v233, v234, vcc
	v_cmp_class_f32_e32 vcc, v232, v170
	s_nop 1
	v_cndmask_b32_e32 v232, v233, v232, vcc
	v_div_scale_f32 v233, s[0:1], v232, v232, 1.0
	v_rcp_f32_e32 v234, v233
	s_nop 0
	v_fma_f32 v235, -v233, v234, 1.0
	v_fmac_f32_e32 v234, v235, v234
	v_div_scale_f32 v235, vcc, 1.0, v232, 1.0
	v_mul_f32_e32 v236, v235, v234
	v_fma_f32 v237, -v233, v236, v235
	v_fmac_f32_e32 v236, v237, v234
	v_fma_f32 v233, -v233, v236, v235
	v_div_fmas_f32 v233, v233, v234, v236
	v_div_fixup_f32 v232, v233, v232, 1.0
	s_waitcnt vmcnt(0)
	v_lshlrev_b32_e32 v174, 16, v214
	v_mul_f32_e32 v175, 0xbfb8aa3b, v174
	v_exp_f32_e32 v175, v175
	v_mul_f32_e32 v176, v65, v232
	v_mul_f32_e32 v176, v182, v176
	v_add_f32_e32 v175, 1.0, v175
	v_div_scale_f32 v177, s[0:1], v175, v175, 1.0
	v_rcp_f32_e32 v178, v177
	s_nop 0
	v_fma_f32 v179, -v177, v178, 1.0
	v_fmac_f32_e32 v178, v179, v178
	v_div_scale_f32 v179, vcc, 1.0, v175, 1.0
	v_mul_f32_e32 v180, v179, v178
	v_fma_f32 v181, -v177, v180, v179
	v_fmac_f32_e32 v180, v181, v178
	v_fma_f32 v177, -v177, v180, v179
	v_div_fmas_f32 v177, v177, v178, v180
	v_div_fixup_f32 v175, v177, v175, 1.0
	v_mul_f32_e32 v174, v175, v174
	v_mul_f32_e32 v174, v174, v176
	v_bfe_u32 v176, v174, 16, 1
	v_add3_u32 v174, v174, v176, s5
	global_store_short_d16_hi v[120:121], v174, off offset:0
	v_lshlrev_b32_e32 v230, 16, v215
	v_mul_f32_e32 v231, 0xbfb8aa3b, v230
	v_exp_f32_e32 v231, v231
	v_mul_f32_e32 v233, v61, v232
	v_mul_f32_e32 v233, v183, v233
	v_add_f32_e32 v231, 1.0, v231
	v_div_scale_f32 v234, s[0:1], v231, v231, 1.0
	v_rcp_f32_e32 v235, v234
	s_nop 0
	v_fma_f32 v236, -v234, v235, 1.0
	v_fmac_f32_e32 v235, v236, v235
	v_div_scale_f32 v236, vcc, 1.0, v231, 1.0
	v_mul_f32_e32 v237, v236, v235
	v_fma_f32 v109, -v234, v237, v236
	v_fmac_f32_e32 v237, v109, v235
	v_fma_f32 v234, -v234, v237, v236
	v_div_fmas_f32 v234, v234, v235, v237
	v_div_fixup_f32 v231, v234, v231, 1.0
	v_mul_f32_e32 v230, v231, v230
	v_mul_f32_e32 v230, v230, v233
	v_bfe_u32 v233, v230, 16, 1
	v_add3_u32 v230, v230, v233, s5
	global_store_short_d16_hi v[120:121], v230, off offset:32
	v_lshlrev_b32_e32 v174, 16, v216
	v_mul_f32_e32 v175, 0xbfb8aa3b, v174
	v_exp_f32_e32 v175, v175
	v_mul_f32_e32 v176, v57, v232
	v_mul_f32_e32 v176, v184, v176
	v_add_f32_e32 v175, 1.0, v175
	v_div_scale_f32 v177, s[0:1], v175, v175, 1.0
	v_rcp_f32_e32 v178, v177
	s_nop 0
	v_fma_f32 v179, -v177, v178, 1.0
	v_fmac_f32_e32 v178, v179, v178
	v_div_scale_f32 v179, vcc, 1.0, v175, 1.0
	v_mul_f32_e32 v180, v179, v178
	v_fma_f32 v181, -v177, v180, v179
	v_fmac_f32_e32 v180, v181, v178
	v_fma_f32 v177, -v177, v180, v179
	v_div_fmas_f32 v177, v177, v178, v180
	v_div_fixup_f32 v175, v177, v175, 1.0
	v_mul_f32_e32 v174, v175, v174
	v_mul_f32_e32 v174, v174, v176
	v_bfe_u32 v176, v174, 16, 1
	v_add3_u32 v174, v174, v176, s5
	global_store_short_d16_hi v[120:121], v174, off offset:64
	v_lshlrev_b32_e32 v230, 16, v217
	v_mul_f32_e32 v231, 0xbfb8aa3b, v230
	v_exp_f32_e32 v231, v231
	v_mul_f32_e32 v233, v53, v232
	v_mul_f32_e32 v233, v185, v233
	v_add_f32_e32 v231, 1.0, v231
	v_div_scale_f32 v234, s[0:1], v231, v231, 1.0
	v_rcp_f32_e32 v235, v234
	s_nop 0
	v_fma_f32 v236, -v234, v235, 1.0
	v_fmac_f32_e32 v235, v236, v235
	v_div_scale_f32 v236, vcc, 1.0, v231, 1.0
	v_mul_f32_e32 v237, v236, v235
	v_fma_f32 v109, -v234, v237, v236
	v_fmac_f32_e32 v237, v109, v235
	v_fma_f32 v234, -v234, v237, v236
	v_div_fmas_f32 v234, v234, v235, v237
	v_div_fixup_f32 v231, v234, v231, 1.0
	v_mul_f32_e32 v230, v231, v230
	v_mul_f32_e32 v230, v230, v233
	v_bfe_u32 v233, v230, 16, 1
	v_add3_u32 v230, v230, v233, s5
	global_store_short_d16_hi v[120:121], v230, off offset:96
	v_lshlrev_b32_e32 v174, 16, v218
	v_mul_f32_e32 v175, 0xbfb8aa3b, v174
	v_exp_f32_e32 v175, v175
	v_mul_f32_e32 v176, v49, v232
	v_mul_f32_e32 v176, v186, v176
	v_add_f32_e32 v175, 1.0, v175
	v_div_scale_f32 v177, s[0:1], v175, v175, 1.0
	v_rcp_f32_e32 v178, v177
	s_nop 0
	v_fma_f32 v179, -v177, v178, 1.0
	v_fmac_f32_e32 v178, v179, v178
	v_div_scale_f32 v179, vcc, 1.0, v175, 1.0
	v_mul_f32_e32 v180, v179, v178
	v_fma_f32 v181, -v177, v180, v179
	v_fmac_f32_e32 v180, v181, v178
	v_fma_f32 v177, -v177, v180, v179
	v_div_fmas_f32 v177, v177, v178, v180
	v_div_fixup_f32 v175, v177, v175, 1.0
	v_mul_f32_e32 v174, v175, v174
	v_mul_f32_e32 v174, v174, v176
	v_bfe_u32 v176, v174, 16, 1
	v_add3_u32 v174, v174, v176, s5
	global_store_short_d16_hi v[120:121], v174, off offset:128
	v_lshlrev_b32_e32 v230, 16, v219
	v_mul_f32_e32 v231, 0xbfb8aa3b, v230
	v_exp_f32_e32 v231, v231
	v_mul_f32_e32 v233, v45, v232
	v_mul_f32_e32 v233, v187, v233
	v_add_f32_e32 v231, 1.0, v231
	v_div_scale_f32 v234, s[0:1], v231, v231, 1.0
	v_rcp_f32_e32 v235, v234
	s_nop 0
	v_fma_f32 v236, -v234, v235, 1.0
	v_fmac_f32_e32 v235, v236, v235
	v_div_scale_f32 v236, vcc, 1.0, v231, 1.0
	v_mul_f32_e32 v237, v236, v235
	v_fma_f32 v109, -v234, v237, v236
	v_fmac_f32_e32 v237, v109, v235
	v_fma_f32 v234, -v234, v237, v236
	v_div_fmas_f32 v234, v234, v235, v237
	v_div_fixup_f32 v231, v234, v231, 1.0
	v_mul_f32_e32 v230, v231, v230
	v_mul_f32_e32 v230, v230, v233
	v_bfe_u32 v233, v230, 16, 1
	v_add3_u32 v230, v230, v233, s5
	global_store_short_d16_hi v[120:121], v230, off offset:160
	v_lshlrev_b32_e32 v174, 16, v220
	v_mul_f32_e32 v175, 0xbfb8aa3b, v174
	v_exp_f32_e32 v175, v175
	v_mul_f32_e32 v176, v41, v232
	v_mul_f32_e32 v176, v188, v176
	v_add_f32_e32 v175, 1.0, v175
	v_div_scale_f32 v177, s[0:1], v175, v175, 1.0
	v_rcp_f32_e32 v178, v177
	s_nop 0
	v_fma_f32 v179, -v177, v178, 1.0
	v_fmac_f32_e32 v178, v179, v178
	v_div_scale_f32 v179, vcc, 1.0, v175, 1.0
	v_mul_f32_e32 v180, v179, v178
	v_fma_f32 v181, -v177, v180, v179
	v_fmac_f32_e32 v180, v181, v178
	v_fma_f32 v177, -v177, v180, v179
	v_div_fmas_f32 v177, v177, v178, v180
	v_div_fixup_f32 v175, v177, v175, 1.0
	v_mul_f32_e32 v174, v175, v174
	v_mul_f32_e32 v174, v174, v176
	v_bfe_u32 v176, v174, 16, 1
	v_add3_u32 v174, v174, v176, s5
	global_store_short_d16_hi v[120:121], v174, off offset:192
	v_lshlrev_b32_e32 v230, 16, v221
	v_mul_f32_e32 v231, 0xbfb8aa3b, v230
	v_exp_f32_e32 v231, v231
	v_mul_f32_e32 v233, v37, v232
	v_mul_f32_e32 v233, v189, v233
	v_add_f32_e32 v231, 1.0, v231
	v_div_scale_f32 v234, s[0:1], v231, v231, 1.0
	v_rcp_f32_e32 v235, v234
	s_nop 0
	v_fma_f32 v236, -v234, v235, 1.0
	v_fmac_f32_e32 v235, v236, v235
	v_div_scale_f32 v236, vcc, 1.0, v231, 1.0
	v_mul_f32_e32 v237, v236, v235
	v_fma_f32 v109, -v234, v237, v236
	v_fmac_f32_e32 v237, v109, v235
	v_fma_f32 v234, -v234, v237, v236
	v_div_fmas_f32 v234, v234, v235, v237
	v_div_fixup_f32 v231, v234, v231, 1.0
	v_mul_f32_e32 v230, v231, v230
	v_mul_f32_e32 v230, v230, v233
	v_bfe_u32 v233, v230, 16, 1
	v_add3_u32 v230, v230, v233, s5
	global_store_short_d16_hi v[120:121], v230, off offset:224
	v_lshlrev_b32_e32 v174, 16, v222
	v_mul_f32_e32 v175, 0xbfb8aa3b, v174
	v_exp_f32_e32 v175, v175
	v_mul_f32_e32 v176, v33, v232
	v_mul_f32_e32 v176, v190, v176
	v_add_f32_e32 v175, 1.0, v175
	v_div_scale_f32 v177, s[0:1], v175, v175, 1.0
	v_rcp_f32_e32 v178, v177
	s_nop 0
	v_fma_f32 v179, -v177, v178, 1.0
	v_fmac_f32_e32 v178, v179, v178
	v_div_scale_f32 v179, vcc, 1.0, v175, 1.0
	v_mul_f32_e32 v180, v179, v178
	v_fma_f32 v181, -v177, v180, v179
	v_fmac_f32_e32 v180, v181, v178
	v_fma_f32 v177, -v177, v180, v179
	v_div_fmas_f32 v177, v177, v178, v180
	v_div_fixup_f32 v175, v177, v175, 1.0
	v_mul_f32_e32 v174, v175, v174
	v_mul_f32_e32 v174, v174, v176
	v_bfe_u32 v176, v174, 16, 1
	v_add3_u32 v174, v174, v176, s5
	global_store_short_d16_hi v[120:121], v174, off offset:256
	v_lshlrev_b32_e32 v230, 16, v223
	v_mul_f32_e32 v231, 0xbfb8aa3b, v230
	v_exp_f32_e32 v231, v231
	v_mul_f32_e32 v233, v29, v232
	v_mul_f32_e32 v233, v191, v233
	v_add_f32_e32 v231, 1.0, v231
	v_div_scale_f32 v234, s[0:1], v231, v231, 1.0
	v_rcp_f32_e32 v235, v234
	s_nop 0
	v_fma_f32 v236, -v234, v235, 1.0
	v_fmac_f32_e32 v235, v236, v235
	v_div_scale_f32 v236, vcc, 1.0, v231, 1.0
	v_mul_f32_e32 v237, v236, v235
	v_fma_f32 v109, -v234, v237, v236
	v_fmac_f32_e32 v237, v109, v235
	v_fma_f32 v234, -v234, v237, v236
	v_div_fmas_f32 v234, v234, v235, v237
	v_div_fixup_f32 v231, v234, v231, 1.0
	v_mul_f32_e32 v230, v231, v230
	v_mul_f32_e32 v230, v230, v233
	v_bfe_u32 v233, v230, 16, 1
	v_add3_u32 v230, v230, v233, s5
	global_store_short_d16_hi v[120:121], v230, off offset:288
	v_lshlrev_b32_e32 v174, 16, v224
	v_mul_f32_e32 v175, 0xbfb8aa3b, v174
	v_exp_f32_e32 v175, v175
	v_mul_f32_e32 v176, v25, v232
	v_mul_f32_e32 v176, v192, v176
	v_add_f32_e32 v175, 1.0, v175
	v_div_scale_f32 v177, s[0:1], v175, v175, 1.0
	v_rcp_f32_e32 v178, v177
	s_nop 0
	v_fma_f32 v179, -v177, v178, 1.0
	v_fmac_f32_e32 v178, v179, v178
	v_div_scale_f32 v179, vcc, 1.0, v175, 1.0
	v_mul_f32_e32 v180, v179, v178
	v_fma_f32 v181, -v177, v180, v179
	v_fmac_f32_e32 v180, v181, v178
	v_fma_f32 v177, -v177, v180, v179
	v_div_fmas_f32 v177, v177, v178, v180
	v_div_fixup_f32 v175, v177, v175, 1.0
	v_mul_f32_e32 v174, v175, v174
	v_mul_f32_e32 v174, v174, v176
	v_bfe_u32 v176, v174, 16, 1
	v_add3_u32 v174, v174, v176, s5
	global_store_short_d16_hi v[120:121], v174, off offset:320
	v_lshlrev_b32_e32 v230, 16, v225
	v_mul_f32_e32 v231, 0xbfb8aa3b, v230
	v_exp_f32_e32 v231, v231
	v_mul_f32_e32 v233, v21, v232
	v_mul_f32_e32 v233, v193, v233
	v_add_f32_e32 v231, 1.0, v231
	v_div_scale_f32 v234, s[0:1], v231, v231, 1.0
	v_rcp_f32_e32 v235, v234
	s_nop 0
	v_fma_f32 v236, -v234, v235, 1.0
	v_fmac_f32_e32 v235, v236, v235
	v_div_scale_f32 v236, vcc, 1.0, v231, 1.0
	v_mul_f32_e32 v237, v236, v235
	v_fma_f32 v109, -v234, v237, v236
	v_fmac_f32_e32 v237, v109, v235
	v_fma_f32 v234, -v234, v237, v236
	v_div_fmas_f32 v234, v234, v235, v237
	v_div_fixup_f32 v231, v234, v231, 1.0
	v_mul_f32_e32 v230, v231, v230
	v_mul_f32_e32 v230, v230, v233
	v_bfe_u32 v233, v230, 16, 1
	v_add3_u32 v230, v230, v233, s5
	global_store_short_d16_hi v[120:121], v230, off offset:352
	v_lshlrev_b32_e32 v174, 16, v226
	v_mul_f32_e32 v175, 0xbfb8aa3b, v174
	v_exp_f32_e32 v175, v175
	v_mul_f32_e32 v176, v17, v232
	v_mul_f32_e32 v176, v194, v176
	v_add_f32_e32 v175, 1.0, v175
	v_div_scale_f32 v177, s[0:1], v175, v175, 1.0
	v_rcp_f32_e32 v178, v177
	s_nop 0
	v_fma_f32 v179, -v177, v178, 1.0
	v_fmac_f32_e32 v178, v179, v178
	v_div_scale_f32 v179, vcc, 1.0, v175, 1.0
	v_mul_f32_e32 v180, v179, v178
	v_fma_f32 v181, -v177, v180, v179
	v_fmac_f32_e32 v180, v181, v178
	v_fma_f32 v177, -v177, v180, v179
	v_div_fmas_f32 v177, v177, v178, v180
	v_div_fixup_f32 v175, v177, v175, 1.0
	v_mul_f32_e32 v174, v175, v174
	v_mul_f32_e32 v174, v174, v176
	v_bfe_u32 v176, v174, 16, 1
	v_add3_u32 v174, v174, v176, s5
	global_store_short_d16_hi v[120:121], v174, off offset:384
	v_lshlrev_b32_e32 v230, 16, v227
	v_mul_f32_e32 v231, 0xbfb8aa3b, v230
	v_exp_f32_e32 v231, v231
	v_mul_f32_e32 v233, v13, v232
	v_mul_f32_e32 v233, v195, v233
	v_add_f32_e32 v231, 1.0, v231
	v_div_scale_f32 v234, s[0:1], v231, v231, 1.0
	v_rcp_f32_e32 v235, v234
	s_nop 0
	v_fma_f32 v236, -v234, v235, 1.0
	v_fmac_f32_e32 v235, v236, v235
	v_div_scale_f32 v236, vcc, 1.0, v231, 1.0
	v_mul_f32_e32 v237, v236, v235
	v_fma_f32 v109, -v234, v237, v236
	v_fmac_f32_e32 v237, v109, v235
	v_fma_f32 v234, -v234, v237, v236
	v_div_fmas_f32 v234, v234, v235, v237
	v_div_fixup_f32 v231, v234, v231, 1.0
	v_mul_f32_e32 v230, v231, v230
	v_mul_f32_e32 v230, v230, v233
	v_bfe_u32 v233, v230, 16, 1
	v_add3_u32 v230, v230, v233, s5
	global_store_short_d16_hi v[120:121], v230, off offset:416
	v_lshlrev_b32_e32 v174, 16, v228
	v_mul_f32_e32 v175, 0xbfb8aa3b, v174
	v_exp_f32_e32 v175, v175
	v_mul_f32_e32 v176, v9, v232
	v_mul_f32_e32 v176, v196, v176
	v_add_f32_e32 v175, 1.0, v175
	v_div_scale_f32 v177, s[0:1], v175, v175, 1.0
	v_rcp_f32_e32 v178, v177
	s_nop 0
	v_fma_f32 v179, -v177, v178, 1.0
	v_fmac_f32_e32 v178, v179, v178
	v_div_scale_f32 v179, vcc, 1.0, v175, 1.0
	v_mul_f32_e32 v180, v179, v178
	v_fma_f32 v181, -v177, v180, v179
	v_fmac_f32_e32 v180, v181, v178
	v_fma_f32 v177, -v177, v180, v179
	v_div_fmas_f32 v177, v177, v178, v180
	v_div_fixup_f32 v175, v177, v175, 1.0
	v_mul_f32_e32 v174, v175, v174
	v_mul_f32_e32 v174, v174, v176
	v_bfe_u32 v176, v174, 16, 1
	v_add3_u32 v174, v174, v176, s5
	global_store_short_d16_hi v[120:121], v174, off offset:448
	v_lshlrev_b32_e32 v230, 16, v229
	v_mul_f32_e32 v231, 0xbfb8aa3b, v230
	v_exp_f32_e32 v231, v231
	v_mul_f32_e32 v233, v5, v232
	v_mul_f32_e32 v233, v197, v233
	v_add_f32_e32 v231, 1.0, v231
	v_div_scale_f32 v234, s[0:1], v231, v231, 1.0
	v_rcp_f32_e32 v235, v234
	s_nop 0
	v_fma_f32 v236, -v234, v235, 1.0
	v_fmac_f32_e32 v235, v236, v235
	v_div_scale_f32 v236, vcc, 1.0, v231, 1.0
	v_mul_f32_e32 v237, v236, v235
	v_fma_f32 v109, -v234, v237, v236
	v_fmac_f32_e32 v237, v109, v235
	v_fma_f32 v234, -v234, v237, v236
	v_div_fmas_f32 v234, v234, v235, v237
	v_div_fixup_f32 v231, v234, v231, 1.0
	v_mul_f32_e32 v230, v231, v230
	v_mul_f32_e32 v230, v230, v233
	v_bfe_u32 v233, v230, 16, 1
	v_add3_u32 v230, v230, v233, s5
	global_store_short_d16_hi v[120:121], v230, off offset:480
	s_cmpk_lt_i32 s3, 0x380
	s_barrier
	s_cbranch_scc0 .LBB0_699
.LBB0_679:
	s_waitcnt vmcnt(0)
	s_addk_i32 s3, 0x80
	s_bfe_u32 s9, s3, 0x20007
	v_cvt_f32_ubyte0_e32 v2, s9
	v_sub_f32_e32 v11, 0xc0a00000, v2
	s_ashr_i32 s0, s3, 9
	v_cmp_gt_f32_e64 s[74:75], s4, v11
	s_and_b64 s[10:11], s[74:75], exec
	s_cselect_b32 s12, 0xffffffc0, 0
	s_ashr_i32 s1, s0, 31
	s_lshl_b64 s[0:1], s[0:1], 14
	s_and_b32 s10, s95, 0x3f80
	s_or_b32 s0, s0, s10
	v_mov_b32_e32 v3, s1
	v_or_b32_e32 v2, s0, v68
	v_lshlrev_b64 v[2:3], 13, v[2:3]
	v_lshl_add_u64 v[2:3], s[92:93], 0, v[2:3]
	s_lshl_b32 s96, s9, 9
	v_lshl_add_u64 v[2:3], v[2:3], 0, s[96:97]
	v_lshl_add_u64 v[2:3], v[2:3], 0, v[70:71]
	global_load_dwordx4 v[182:185], v[2:3], off offset:2048
	s_add_u32 s10, s0, s87
	s_addc_u32 s11, s1, 0
	v_mov_b32_e32 v109, v71
	s_andn2_b64 vcc, exec, s[14:15]
	v_mov_b32_e32 v18, 0
	v_mov_b32_e32 v19, 0
	v_mov_b32_e32 v20, 0
	v_mov_b32_e32 v21, 0
	v_mov_b32_e32 v3, s1
	v_or_b32_e32 v2, s0, v72
	v_lshlrev_b64 v[2:3], 13, v[2:3]
	v_lshl_add_u64 v[2:3], s[92:93], 0, v[2:3]
	v_lshl_add_u64 v[2:3], v[2:3], 0, s[96:97]
	v_lshl_add_u64 v[2:3], v[2:3], 0, v[70:71]
	global_load_dwordx4 v[186:189], v[2:3], off offset:2048
	v_mov_b32_e32 v3, s1
	v_or_b32_e32 v2, s0, v74
	v_lshlrev_b64 v[2:3], 13, v[2:3]
	v_lshl_add_u64 v[2:3], s[92:93], 0, v[2:3]
	v_lshl_add_u64 v[2:3], v[2:3], 0, s[96:97]
	v_lshl_add_u64 v[2:3], v[2:3], 0, v[70:71]
	global_load_dwordx4 v[190:193], v[2:3], off offset:2048
	v_mov_b32_e32 v3, s1
	v_or_b32_e32 v2, s0, v76
	v_lshlrev_b64 v[2:3], 13, v[2:3]
	v_lshl_add_u64 v[2:3], s[92:93], 0, v[2:3]
	v_lshl_add_u64 v[2:3], v[2:3], 0, s[96:97]
	v_lshl_add_u64 v[2:3], v[2:3], 0, v[70:71]
	global_load_dwordx4 v[194:197], v[2:3], off offset:2048
	v_mov_b32_e32 v3, s1
	v_or_b32_e32 v2, s0, v78
	v_lshlrev_b64 v[2:3], 13, v[2:3]
	v_lshl_add_u64 v[2:3], s[92:93], 0, v[2:3]
	v_lshl_add_u64 v[2:3], v[2:3], 0, s[96:97]
	v_lshl_add_u64 v[2:3], v[2:3], 0, v[70:71]
	global_load_dwordx4 v[198:201], v[2:3], off offset:2048
	v_mov_b32_e32 v3, s1
	v_or_b32_e32 v2, s0, v80
	v_lshlrev_b64 v[2:3], 13, v[2:3]
	v_lshl_add_u64 v[2:3], s[92:93], 0, v[2:3]
	v_lshl_add_u64 v[2:3], v[2:3], 0, s[96:97]
	v_lshl_add_u64 v[2:3], v[2:3], 0, v[70:71]
	global_load_dwordx4 v[202:205], v[2:3], off offset:2048
	v_mov_b32_e32 v3, s1
	v_or_b32_e32 v2, s0, v82
	v_lshlrev_b64 v[2:3], 13, v[2:3]
	v_lshl_add_u64 v[2:3], s[92:93], 0, v[2:3]
	v_lshl_add_u64 v[2:3], v[2:3], 0, s[96:97]
	v_lshl_add_u64 v[2:3], v[2:3], 0, v[70:71]
	global_load_dwordx4 v[206:209], v[2:3], off offset:2048
	v_lshl_add_u64 v[2:3], s[0:1], 0, v[84:85]
	v_lshlrev_b64 v[2:3], 13, v[2:3]
	v_lshl_add_u64 v[2:3], s[92:93], 0, v[2:3]
	v_lshl_add_u64 v[2:3], v[2:3], 0, s[96:97]
	v_lshl_add_u64 v[2:3], v[2:3], 0, v[70:71]
	global_load_dwordx4 v[210:213], v[2:3], off offset:2048
	v_lshl_add_u64 v[2:3], v[90:91], 0, v[106:107]
	global_load_dwordx4 v[214:217], v[2:3], off
	v_lshl_add_u64 v[2:3], v[92:93], 0, v[106:107]
	global_load_dwordx4 v[218:221], v[2:3], off
	v_lshl_add_u64 v[2:3], v[94:95], 0, v[106:107]
	global_load_dwordx4 v[222:225], v[2:3], off
	v_lshl_add_u64 v[2:3], v[96:97], 0, v[106:107]
	global_load_dwordx4 v[226:229], v[2:3], off
	v_lshl_add_u64 v[2:3], v[98:99], 0, v[106:107]
	global_load_dwordx4 v[230:233], v[2:3], off
	v_lshl_add_u64 v[2:3], v[100:101], 0, v[106:107]
	global_load_dwordx4 v[234:237], v[2:3], off
	v_lshl_add_u64 v[2:3], v[102:103], 0, v[106:107]
	global_load_dwordx4 v[174:177], v[2:3], off
	v_lshl_add_u64 v[2:3], v[104:105], 0, v[106:107]
	global_load_dwordx4 v[178:181], v[2:3], off
	v_mov_b32_e32 v3, s11
	v_or_b32_e32 v2, s10, v66
	v_lshlrev_b64 v[2:3], 13, v[2:3]
	v_lshl_add_u64 v[2:3], s[92:93], 0, v[2:3]
	v_lshl_add_u64 v[2:3], v[2:3], 0, s[96:97]
	v_lshl_add_u64 v[2:3], v[2:3], 0, v[108:109]
	global_load_dwordx4 v[62:65], v[2:3], off
	global_load_dwordx4 v[58:61], v[2:3], off offset:64
	global_load_dwordx4 v[54:57], v[2:3], off offset:128
	global_load_dwordx4 v[50:53], v[2:3], off offset:192
	global_load_dwordx4 v[46:49], v[2:3], off offset:256
	global_load_dwordx4 v[42:45], v[2:3], off offset:320
	global_load_dwordx4 v[38:41], v[2:3], off offset:384
	global_load_dwordx4 v[34:37], v[2:3], off offset:448
	s_waitcnt vmcnt(23)
	ds_write_b128 v1, v[182:185]
	s_waitcnt vmcnt(22)
	ds_write_b128 v67, v[186:189]
	s_waitcnt vmcnt(21)
	ds_write_b128 v69, v[190:193]
	s_waitcnt vmcnt(20)
	ds_write_b128 v73, v[194:197]
	s_waitcnt vmcnt(19)
	ds_write_b128 v75, v[198:201]
	s_waitcnt vmcnt(18)
	ds_write_b128 v77, v[202:205]
	s_waitcnt vmcnt(17)
	ds_write_b128 v79, v[206:209]
	s_waitcnt vmcnt(16)
	ds_write_b128 v81, v[210:213]
	s_waitcnt vmcnt(15)
	ds_write_b128 v83, v[214:217]
	s_waitcnt vmcnt(14)
	ds_write_b128 v87, v[218:221]
	s_waitcnt vmcnt(13)
	ds_write_b128 v122, v[222:225]
	s_waitcnt vmcnt(12)
	ds_write_b128 v123, v[226:229]
	s_waitcnt vmcnt(11)
	ds_write_b128 v124, v[230:233]
	s_waitcnt vmcnt(10)
	ds_write_b128 v125, v[234:237]
	s_waitcnt vmcnt(9)
	ds_write_b128 v126, v[174:177]
	s_waitcnt vmcnt(8)
	ds_write_b128 v127, v[178:181]
	s_waitcnt lgkmcnt(0)
	s_barrier
	ds_read_b128 v[2:5], v128
	ds_read_b128 v[6:9], v128 offset:64
	s_waitcnt vmcnt(7) lgkmcnt(1)
	v_mfma_f32_16x16x32_bf16 v[2:5], v[62:65], v[2:5], 0
	s_waitcnt vmcnt(6) lgkmcnt(0)
	v_mfma_f32_16x16x32_bf16 v[2:5], v[58:61], v[6:9], v[2:5]
	ds_read_b128 v[6:9], v128 offset:128
	s_waitcnt vmcnt(5) lgkmcnt(0)
	v_mfma_f32_16x16x32_bf16 v[2:5], v[54:57], v[6:9], v[2:5]
	ds_read_b128 v[6:9], v128 offset:192
	s_waitcnt vmcnt(4) lgkmcnt(0)
	v_mfma_f32_16x16x32_bf16 v[2:5], v[50:53], v[6:9], v[2:5]
	ds_read_b128 v[6:9], v128 offset:256
	s_waitcnt vmcnt(3) lgkmcnt(0)
	v_mfma_f32_16x16x32_bf16 v[2:5], v[46:49], v[6:9], v[2:5]
	ds_read_b128 v[6:9], v128 offset:320
	s_waitcnt vmcnt(2) lgkmcnt(0)
	v_mfma_f32_16x16x32_bf16 v[2:5], v[42:45], v[6:9], v[2:5]
	ds_read_b128 v[6:9], v128 offset:384
	s_waitcnt vmcnt(1) lgkmcnt(0)
	v_mfma_f32_16x16x32_bf16 v[2:5], v[38:41], v[6:9], v[2:5]
	ds_read_b128 v[6:9], v128 offset:448
	s_waitcnt vmcnt(0) lgkmcnt(0)
	v_mfma_f32_16x16x32_bf16 v[30:33], v[34:37], v[6:9], v[2:5]
	s_cbranch_vccnz .LBB0_681
	s_nop 3
	ds_read_b128 v[2:5], v128 offset:8448
	ds_read_b128 v[6:9], v128 offset:8512
	s_waitcnt lgkmcnt(1)
	v_mfma_f32_16x16x32_bf16 v[2:5], v[62:65], v[2:5], 0
	s_waitcnt lgkmcnt(0)
	v_mfma_f32_16x16x32_bf16 v[2:5], v[58:61], v[6:9], v[2:5]
	ds_read_b128 v[6:9], v128 offset:8576
	s_waitcnt lgkmcnt(0)
	v_mfma_f32_16x16x32_bf16 v[2:5], v[54:57], v[6:9], v[2:5]
	ds_read_b128 v[6:9], v128 offset:8640
	s_waitcnt lgkmcnt(0)
	v_mfma_f32_16x16x32_bf16 v[2:5], v[50:53], v[6:9], v[2:5]
	ds_read_b128 v[6:9], v128 offset:8704
	s_waitcnt lgkmcnt(0)
	v_mfma_f32_16x16x32_bf16 v[2:5], v[46:49], v[6:9], v[2:5]
	ds_read_b128 v[6:9], v128 offset:8768
	s_waitcnt lgkmcnt(0)
	v_mfma_f32_16x16x32_bf16 v[2:5], v[42:45], v[6:9], v[2:5]
	ds_read_b128 v[6:9], v128 offset:8832
	s_waitcnt lgkmcnt(0)
	v_mfma_f32_16x16x32_bf16 v[2:5], v[38:41], v[6:9], v[2:5]
	ds_read_b128 v[6:9], v128 offset:8896
	s_waitcnt lgkmcnt(0)
	v_mfma_f32_16x16x32_bf16 v[18:21], v[34:37], v[6:9], v[2:5]
